# chained MFMA order + half-barrier K-loop (each wave half executes every other barrier)
# baseline (speedup 1.0000x reference)
; #define LAS __attribute__((address_space(3)))
; template <class Epi, class Sched, bool ALIGN_EPI = false, bool SP2 = false>
; __device__ __forceinline__ void gemm_phase(PG8_LAS unsigned char* lds, const Gemm g, const Sched& S, const Epi& E) {
;     ...
;     const int tid = tid_, wid = __builtin_amdgcn_readfirstlane(tid >> 6), lane = tid & 63, wr = wid >> 2, wc = wid & 3, fr = lane & 15, fq = lane >> 4;
; __global__ void __launch_bounds__(NWAVES * 64, 2) skel_fwd(Args args) {
;     extern __shared__ __attribute__((aligned(16))) unsigned char lds[];
;     Frame F;
;     F.lds = (LAS unsigned char*)lds;
;     F.MISC = (volatile LAS unsigned*)(F.lds + MISC_OFF);
;     F.tid = threadIdx.x; F.lane = F.tid & 63; F.wave = __builtin_amdgcn_readfirstlane(F.tid >> 6);
;     F.G = gridDim.x; { const int bx = blockIdx.x; F.vcu = (F.G % 8 == 0) ? (bx % 8) * (F.G / 8) + bx / 8 : bx; }
_Z8skel_fwd4Args:
	v_readfirstlane_b32 s98, v0
	s_nop 3
	s_lshr_b32 s98, s98, 8
	s_load_dword s76, s[0:1], 0x98
	s_mov_b32 s73, s2
	s_add_u32 s2, s0, 0x98
	s_addc_u32 s3, s1, 0
	s_mov_b32 s78, s73
	v_writelane_b32 v243, s2, 0
	s_nop 1
	v_writelane_b32 v243, s3, 1
	s_waitcnt lgkmcnt(0)
	s_and_b32 s2, s76, 7
	s_cmp_lg_u32 s2, 0
	s_cbranch_scc1 .LBB0_2
	s_ashr_i32 s3, s73, 31
	s_lshr_b32 s3, s3, 29
	s_add_i32 s3, s73, s3
	s_and_b32 s4, s3, -8
	s_ashr_i32 s2, s76, 3
	s_sub_i32 s4, s73, s4
	s_mul_i32 s2, s2, s4
	s_ashr_i32 s3, s3, 3
	s_add_i32 s78, s2, s3

; #define PG8_STAGE(bufoff, gbase, voff) do { const char* gb_ = (const char*)(gbase); asm volatile("" : "+s"(gb_)); _Pragma("unroll") for (int _i = 0; _i < 2; ++_i) { unsigned vo_ = (voff)[_i]; asm volatile("" : "+v"(vo_));        \
;         __builtin_amdgcn_global_load_lds((const unsigned*)(gb_ + vo_), (PG8_LAS unsigned*)(lds + (bufoff) + ldsw + _i * 8192), 16, 0, 0); } } while (0)
; #define PG8_WAIT_V(n) asm volatile("s_waitcnt vmcnt(" #n ")" ::: "memory")
; #define PG8_BAR __builtin_amdgcn_s_barrier()
; template <class Epi, class Sched, bool ALIGN_EPI = false, bool SP2 = false>
; __device__ __forceinline__ void gemm_phase(PG8_LAS unsigned char* lds, const Gemm g, const Sched& S, const Epi& E) {
;     ...
;     for (int i = 0; i < 2; ++i) { int R, C; stage_rc(tid * 16 + i * 8192, R, C); const int Rb = Epi::PERM ? ((R & ~31) + perm32(R & 31)) : R;
;         voffA[i] = (unsigned)(R * K + C) * 2u; voffB[i] = (unsigned)(Rb * K + C) * 2u; }
;     const size_t kstep = (size_t)(BK * 2);
;     const size_t hstep = (size_t)HALF * K * 2;
;     const size_t tstep = 2 * hstep;
;     const unsigned ldsw = (unsigned)wid * 1024u;
;     const int aoff = lds_byte(wr * 64 + fr, fq * 8), boff = lds_byte(wc * 32 + fr, fq * 8);
;     ...
;     const char* cA = (const char*)g.A + (size_t)cur.pm * tstep; const char* cB = (const char*)g.Bt + (size_t)cur.pn * tstep;
;     S.a_ready(cur);
;     if constexpr (SP2) {
;         PG8_STAGE(PG8_SB(0, 0), cB, voffB); PG8_STAGE(PG8_SB(0, 1), cB + hstep, voffB); PG8_STAGE(PG8_SA(0, 0), cA, voffA); PG8_STAGE(PG8_SA(0, 1), cA + hstep, voffA);
;         if (wr == 1) PG8_BAR;
;         PG8_WAIT_V(2); PG8_BAR;
;         PG8_STAGE(PG8_SB(1, 0), cB + kstep, voffB); PG8_STAGE(PG8_SA(1, 0), cA + kstep, voffA); PG8_STAGE(PG8_SB(1, 1), cB + hstep + kstep, voffB);
;         PG8_WAIT_V(6); PG8_BAR;
.LBB0_222:
	s_andn2_b64 vcc, exec, s[0:1]
	v_readlane_b32 s40, v241, 42
	v_writelane_b32 v241, s36, 48
	s_cbranch_vccnz .LBB0_325
	v_readlane_b32 s0, v243, 22
	s_waitcnt vmcnt(0)
	v_mov_b32_e32 v2, v0
	v_readlane_b32 s1, v243, 23
	s_andn2_b64 vcc, exec, s[0:1]
	v_readfirstlane_b32 s0, v2
	s_cbranch_vccnz .LBB0_279
	v_bfe_i32 v4, v2, 27, 1
	s_waitcnt lgkmcnt(0)
	v_lshlrev_b32_e32 v3, 4, v2
	v_lshrrev_b32_e32 v4, 22, v4
	v_add_u32_e32 v4, v3, v4
	v_and_b32_e32 v4, 0xfffffc00, v4
	v_sub_u32_e32 v4, v3, v4
	v_ashrrev_i32_e32 v1, 31, v2
	v_lshrrev_b32_e32 v5, 4, v4
	v_lshrrev_b32_e32 v1, 26, v1
	v_bitop3_b32 v4, v5, v4, 32 bitop3:0x6c
	v_add_u32_e32 v1, v2, v1
	v_ashrrev_i32_e32 v6, 31, v4
	v_ashrrev_i32_e32 v1, 6, v1
	v_lshrrev_b32_e32 v6, 26, v6
	v_lshlrev_b32_e32 v5, 3, v1
	v_add_u32_e32 v6, v4, v6
	v_and_b32_e32 v5, -16, v5
	v_ashrrev_i32_e32 v7, 6, v6
	v_and_b32_e32 v6, 0xc0, v6
	v_add_u32_e32 v5, v7, v5
	v_sub_u32_e32 v4, v4, v6
	v_lshlrev_b32_e32 v1, 5, v1
	v_ashrrev_i16_sdwa v4, v217, sext(v4) dst_sel:DWORD dst_unused:UNUSED_PAD src0_sel:DWORD src1_sel:BYTE_0
	v_lshlrev_b32_e32 v6, 1, v5
	v_lshrrev_b32_e32 v8, 2, v5
	v_and_b32_e32 v7, 3, v7
	s_mov_b32 s2, 0xfffe0
	v_and_b32_e32 v1, 32, v1
	v_bfe_i32 v4, v4, 0, 16
	v_and_b32_e32 v6, 24, v6
	v_and_b32_e32 v8, 4, v8
	v_and_or_b32 v7, v5, s2, v7
	v_or3_b32 v6, v7, v8, v6
	v_add_lshl_u32 v4, v1, v4, 1
	v_add_u32_e32 v3, 0x2000, v3
	v_lshl_add_u32 v1, v5, 12, v4
	v_lshl_add_u32 v189, v6, 12, v4
	v_ashrrev_i32_e32 v4, 31, v3
	v_lshrrev_b32_e32 v4, 22, v4
	v_add_u32_e32 v4, v3, v4
	v_ashrrev_i32_e32 v4, 10, v4
	v_mul_i32_i24_e32 v5, 0x400, v4
	v_sub_u32_e32 v3, v3, v5
	v_lshrrev_b32_e32 v5, 4, v3
	v_bitop3_b32 v3, v5, v3, 32 bitop3:0x6c
	v_ashrrev_i32_e32 v6, 31, v3
	v_lshrrev_b32_e32 v6, 26, v6
	v_lshlrev_b32_e32 v5, 3, v4
	v_add_u32_e32 v6, v3, v6
	v_and_b32_e32 v5, -16, v5
	v_ashrrev_i32_e32 v7, 6, v6
	v_and_b32_e32 v6, 0xc0, v6
	v_add_u32_e32 v5, v7, v5
	v_sub_u32_e32 v3, v3, v6
	v_and_b32_e32 v7, 3, v7
	s_ashr_i32 s6, s0, 6
	s_ashr_i32 s1, s0, 8
	v_lshlrev_b32_e32 v4, 5, v4
	v_ashrrev_i16_sdwa v3, v217, sext(v3) dst_sel:DWORD dst_unused:UNUSED_PAD src0_sel:DWORD src1_sel:BYTE_0
	v_lshlrev_b32_e32 v6, 1, v5
	v_lshrrev_b32_e32 v8, 2, v5
	v_and_or_b32 v7, v5, s2, v7
	s_lshl_b32 s12, s6, 10
	v_readlane_b32 s2, v242, 18
	v_readlane_b32 s4, v241, 44
	v_and_b32_e32 v4, 32, v4
	v_bfe_i32 v3, v3, 0, 16
	v_and_b32_e32 v6, 24, v6
	v_and_b32_e32 v8, 4, v8
	v_readlane_b32 s3, v242, 19
	s_add_u32 s2, s4, s2
	v_readlane_b32 s4, v241, 45
	v_or3_b32 v6, v7, v8, v6
	v_add_lshl_u32 v3, v4, v3, 1
	s_addc_u32 s3, s4, s3
	v_lshl_add_u32 v191, v5, 12, v3
	v_lshl_add_u32 v219, v6, 12, v3
	s_mov_b64 s[4:5], s[2:3]
	s_add_i32 s13, s12, 0
	v_mov_b32_e32 v3, v189
	s_add_i32 m0, s13, 0x10000
	s_nop 0
	global_load_lds_dwordx4 v3, s[4:5]
	v_mov_b32_e32 v3, v219
	s_add_i32 m0, s13, 0x12000
	s_nop 0
	global_load_lds_dwordx4 v3, s[4:5]
	s_add_u32 s4, s2, 0x80000
	s_addc_u32 s5, s3, 0
	v_mov_b32_e32 v3, v189
	s_add_i32 m0, s13, 0x14000
	s_add_i32 s14, s13, 0x2000
	global_load_lds_dwordx4 v3, s[4:5]
	v_mov_b32_e32 v3, v219
	s_add_i32 m0, s13, 0x16000
	s_add_i32 s15, s13, 0x4000
	global_load_lds_dwordx4 v3, s[4:5]
	v_readlane_b32 s4, v242, 24
	v_readlane_b32 s5, v242, 25
	v_mov_b32_e32 v3, v1
	s_mov_b32 m0, s13
	s_add_i32 s16, s13, 0x6000
	s_nop 1
	global_load_lds_dwordx4 v3, s[4:5]
	v_mov_b32_e32 v3, v191
	s_mov_b32 m0, s14
	s_cmp_eq_u32 s1, 1
	global_load_lds_dwordx4 v3, s[4:5]
	v_readlane_b32 s4, v242, 22
	v_readlane_b32 s5, v242, 23
	v_mov_b32_e32 v3, v1
	s_mov_b32 m0, s15
	s_nop 2
	global_load_lds_dwordx4 v3, s[4:5]
	v_mov_b32_e32 v3, v191
	s_mov_b32 m0, s16
	s_nop 0
	global_load_lds_dwordx4 v3, s[4:5]
	s_cselect_b64 s[4:5], -1, 0
	s_cmp_lg_u32 s1, 1
	s_cbranch_scc1 .LBB0_226
.LBB0_226:
	s_lshl_b32 s40, s36, 10
	s_lshl_b64 s[8:9], s[40:41], 2
	v_readlane_b32 s7, v243, 18
	s_add_u32 s42, s7, s8
	v_readlane_b32 s7, v243, 19
	s_addc_u32 s43, s7, s9
	s_mul_i32 s8, s36, 0xe000
	v_readlane_b32 s9, v243, 20
	s_mul_hi_u32 s7, s36, 0xe000
	s_add_u32 s17, s9, s8
	v_readlane_b32 s8, v243, 21
	s_addc_u32 s18, s8, s7
	s_lshl_b32 s6, s6, 5
	s_and_b32 s9, s6, 0x60
	s_lshl_b32 s8, s1, 13
	s_lshl_b32 s10, s9, 7
	s_add_u32 s6, s2, 0x80
	s_addc_u32 s7, s3, 0
	v_mov_b32_e32 v3, v189
	s_waitcnt vmcnt(2)
	s_barrier
	s_add_i32 m0, s13, 0x18000
	s_add_i32 s19, s13, 0x8000
	global_load_lds_dwordx4 v3, s[6:7]
	v_mov_b32_e32 v3, v219
	s_add_i32 m0, s13, 0x1a000
	s_add_i32 s20, s13, 0xa000
	global_load_lds_dwordx4 v3, s[6:7]
	v_readlane_b32 s6, v242, 26
	v_readlane_b32 s7, v242, 27
	v_mov_b32_e32 v3, v1
	s_mov_b32 m0, s19
	v_lshrrev_b32_e32 v4, 1, v2
	s_nop 1
	global_load_lds_dwordx4 v3, s[6:7]
	v_mov_b32_e32 v3, v191
	s_mov_b32 m0, s20
	v_and_b32_e32 v4, 24, v4
	global_load_lds_dwordx4 v3, s[6:7]
	s_add_u32 s6, s2, 0x80080
	s_addc_u32 s7, s3, 0
	v_mov_b32_e32 v3, v189
	s_add_i32 m0, s13, 0x1c000
	v_lshlrev_b32_e32 v5, 1, v4
	global_load_lds_dwordx4 v3, s[6:7]
	v_mov_b32_e32 v3, v219
	s_add_i32 m0, s13, 0x1e000
	s_cmpk_lt_u32 s0, 0x100
	global_load_lds_dwordx4 v3, s[6:7]
	v_and_b32_e32 v3, 15, v2
	v_lshl_or_b32 v220, s1, 6, v3
	v_lshlrev_b32_e32 v2, 2, v2
	v_readlane_b32 s0, v242, 20
	v_lshl_or_b32 v3, v3, 6, v5
	v_and_b32_e32 v2, 32, v2
	s_waitcnt vmcnt(6)
	v_readlane_b32 s1, v242, 21
	v_bitop3_b32 v5, v3, s8, v2 bitop3:0xde
	s_mov_b32 s23, s0
	v_readlane_b32 s0, v242, 24
	v_bitop3_b32 v221, v3, s10, v2 bitop3:0xde
	s_cselect_b64 s[44:45], -1, 0
	v_or_b32_e32 v222, s9, v4
	s_mov_b32 s21, 0
	v_add_u32_e32 v223, 0, v5
	v_readlane_b32 s22, v242, 5
	v_readlane_b32 s1, v242, 25
	v_readlane_b32 s40, v241, 42
	s_barrier
	s_branch .LBB0_229

; #define PG8_STAGE(bufoff, gbase, voff) do { const char* gb_ = (const char*)(gbase); asm volatile("" : "+s"(gb_)); _Pragma("unroll") for (int _i = 0; _i < 2; ++_i) { unsigned vo_ = (voff)[_i]; asm volatile("" : "+v"(vo_));        \
;         __builtin_amdgcn_global_load_lds((const unsigned*)(gb_ + vo_), (PG8_LAS unsigned*)(lds + (bufoff) + ldsw + _i * 8192), 16, 0, 0); } } while (0)
; #define PG8_LDA(dst, b, h) do { _Pragma("unroll") for (int m = 0; m < 4; ++m) _Pragma("unroll") for (int k = 0; k < 2; ++k) dst[m][k] = *(const PG8_LAS bf16x8*)(lds + PG8_SA(b, h) + aoff + m * 2048 + k * 1024); } while (0)
; #define PG8_LDB(dst, b, h) do { _Pragma("unroll") for (int n = 0; n < 2; ++n) _Pragma("unroll") for (int k = 0; k < 2; ++k) dst[n][k] = *(const PG8_LAS bf16x8*)(lds + PG8_SB(b, h) + boff + n * 2048 + k * 1024); } while (0)
; #define PG8_MMA(ai, bj, At, Bt) do { __builtin_amdgcn_s_setprio(1); _Pragma("unroll") for (int m = 0; m < 4; ++m) _Pragma("unroll") for (int n = 0; n < 2; ++n) _Pragma("unroll") for (int k = 0; k < 2; ++k) \
;         acc[ai][bj][m][n] = __builtin_amdgcn_mfma_f32_16x16x32_bf16(Bt[n][k], At[m][k], acc[ai][bj][m][n], 0, 0, 0); __builtin_amdgcn_s_setprio(0); } while (0)
; #define PG8_WAIT_V(n) asm volatile("s_waitcnt vmcnt(" #n ")" ::: "memory")
; #define PG8_WAIT_L(n) asm volatile("s_waitcnt lgkmcnt(" #n ")" ::: "memory")
; #define PG8_BAR __builtin_amdgcn_s_barrier()
; #define PG8_SCHED __builtin_amdgcn_sched_barrier(0)
; template <class Epi, class Sched, bool ALIGN_EPI = false, bool SP2 = false>
; __device__ __forceinline__ void gemm_phase(PG8_LAS unsigned char* lds, const Gemm g, const Sched& S, const Epi& E) {
;     ...
;             PG8_LDB(B0, 0, 0); PG8_LDB(B1, 0, 1); PG8_SCHED; PG8_LDA(At, 0, 0); PG8_STAGE(PG8_SA(1, 1), a1 + hstep, voffA);
;             PG8_WAIT_V(8); PG8_WAIT_L(0); PG8_BAR; PG8_MMA(0, 0, At, B0); PG8_MMA(0, 1, At, B1); PG8_BAR; PG8_SCHED;
;             PG8_LDA(At, 0, 1); PG8_STAGE(PG8_SB(0, 0), b2, voffB); PG8_STAGE(PG8_SB(0, 1), b2 + hstep, voffB); PG8_STAGE(PG8_SA(0, 0), a2, voffA);
;             PG8_WAIT_V(8); PG8_WAIT_L(0); PG8_BAR; PG8_MMA(1, 0, At, B0); PG8_MMA(1, 1, At, B1); PG8_BAR; PG8_SCHED;
.LBB0_232:
	s_add_u32 s2, s0, 0x100
	s_addc_u32 s3, s1, 0
	s_cmp_eq_u32 s30, 28
	s_cselect_b32 s10, s25, s2
	s_cselect_b32 s11, s24, s3
	s_cselect_b32 s8, s27, s28
	s_cselect_b32 s9, s26, s29
	s_add_u32 s6, s10, 0x80
	s_addc_u32 s7, s11, 0
	s_add_i32 s31, 0, 0x10000
	s_add_i32 s33, 0, 0x14000
	ds_read_b128 v[66:69], v244
	ds_read_b128 v[70:73], v244 offset:1024
	ds_read_b128 v[74:77], v244 offset:2048
	ds_read_b128 v[78:81], v244 offset:3072
	ds_read_b128 v[146:149], v244 offset:16384
	ds_read_b128 v[150:153], v244 offset:17408
	ds_read_b128 v[154:157], v244 offset:18432
	ds_read_b128 v[158:161], v244 offset:19456
	s_add_u32 s0, s0, 0x80080
	s_addc_u32 s1, s1, 0
	ds_read_b128 v[178:181], v223
	ds_read_b128 v[182:185], v223 offset:1024
	ds_read_b128 v[192:195], v223 offset:2048
	ds_read_b128 v[196:199], v223 offset:3072
	ds_read_b128 v[200:203], v223 offset:4096
	ds_read_b128 v[204:207], v223 offset:5120
	ds_read_b128 v[208:211], v223 offset:6144
	ds_read_b128 v[212:215], v223 offset:7168
	s_add_i32 m0, s13, 0xc000
	s_nop 0
	global_load_lds_dwordx4 v1, s[0:1]
	s_add_i32 m0, s13, 0xe000
	s_nop 0
	global_load_lds_dwordx4 v191, s[0:1]
	s_waitcnt vmcnt(8)
	s_waitcnt lgkmcnt(0)
	s_cmp_lg_u32 s98, 0
	s_cbranch_scc1 .Lhb_0
	s_barrier
.Lhb_0:
	s_setprio 1
	s_waitcnt lgkmcnt(0)
	v_mfma_f32_16x16x32_bf16 v[142:145], v[66:69], v[178:181], v[142:145]
	v_mfma_f32_16x16x32_bf16 v[142:145], v[70:73], v[182:185], v[142:145]
	v_mfma_f32_16x16x32_bf16 v[134:137], v[66:69], v[192:195], v[134:137]
	v_mfma_f32_16x16x32_bf16 v[134:137], v[70:73], v[196:199], v[134:137]
	v_mfma_f32_16x16x32_bf16 v[126:129], v[66:69], v[200:203], v[126:129]
	v_mfma_f32_16x16x32_bf16 v[126:129], v[70:73], v[204:207], v[126:129]
	v_mfma_f32_16x16x32_bf16 v[118:121], v[66:69], v[208:211], v[118:121]
	v_mfma_f32_16x16x32_bf16 v[118:121], v[70:73], v[212:215], v[118:121]
	v_mfma_f32_16x16x32_bf16 v[138:141], v[74:77], v[178:181], v[138:141]
	v_mfma_f32_16x16x32_bf16 v[138:141], v[78:81], v[182:185], v[138:141]
	v_mfma_f32_16x16x32_bf16 v[130:133], v[74:77], v[192:195], v[130:133]
	v_mfma_f32_16x16x32_bf16 v[130:133], v[78:81], v[196:199], v[130:133]
	v_mfma_f32_16x16x32_bf16 v[122:125], v[74:77], v[200:203], v[122:125]
	v_mfma_f32_16x16x32_bf16 v[122:125], v[78:81], v[204:207], v[122:125]
	v_mfma_f32_16x16x32_bf16 v[114:117], v[74:77], v[208:211], v[114:117]
	v_mfma_f32_16x16x32_bf16 v[114:117], v[78:81], v[212:215], v[114:117]
	s_setprio 0
	s_setprio 1
	v_mfma_f32_16x16x32_bf16 v[62:65], v[146:149], v[178:181], v[62:65]
	v_mfma_f32_16x16x32_bf16 v[62:65], v[150:153], v[182:185], v[62:65]
	v_mfma_f32_16x16x32_bf16 v[54:57], v[146:149], v[192:195], v[54:57]
	v_mfma_f32_16x16x32_bf16 v[54:57], v[150:153], v[196:199], v[54:57]
	v_mfma_f32_16x16x32_bf16 v[46:49], v[146:149], v[200:203], v[46:49]
	v_mfma_f32_16x16x32_bf16 v[46:49], v[150:153], v[204:207], v[46:49]
	v_mfma_f32_16x16x32_bf16 v[38:41], v[146:149], v[208:211], v[38:41]
	v_mfma_f32_16x16x32_bf16 v[38:41], v[150:153], v[212:215], v[38:41]
	v_mfma_f32_16x16x32_bf16 v[58:61], v[154:157], v[178:181], v[58:61]
	v_mfma_f32_16x16x32_bf16 v[58:61], v[158:161], v[182:185], v[58:61]
	v_mfma_f32_16x16x32_bf16 v[50:53], v[154:157], v[192:195], v[50:53]
	v_mfma_f32_16x16x32_bf16 v[50:53], v[158:161], v[196:199], v[50:53]
	v_mfma_f32_16x16x32_bf16 v[42:45], v[154:157], v[200:203], v[42:45]
	v_mfma_f32_16x16x32_bf16 v[42:45], v[158:161], v[204:207], v[42:45]
	v_mfma_f32_16x16x32_bf16 v[34:37], v[154:157], v[208:211], v[34:37]
	v_mfma_f32_16x16x32_bf16 v[34:37], v[158:161], v[212:215], v[34:37]
	s_setprio 0
	s_cmp_eq_u32 s98, 0
	s_cbranch_scc1 .Lhb_1
	s_barrier
.Lhb_1:
	s_mov_b64 s[0:1], s[8:9]
	s_add_i32 s31, s31, s12
	ds_read_b128 v[178:181], v223 offset:16384
	ds_read_b128 v[182:185], v223 offset:17408
	ds_read_b128 v[192:195], v223 offset:18432
	ds_read_b128 v[196:199], v223 offset:19456
	ds_read_b128 v[200:203], v223 offset:20480
	ds_read_b128 v[204:207], v223 offset:21504
	ds_read_b128 v[208:211], v223 offset:22528
	ds_read_b128 v[212:215], v223 offset:23552
	s_mov_b32 m0, s31
	s_nop 0
	global_load_lds_dwordx4 v189, s[0:1]
	s_add_i32 m0, s31, 0x2000
	s_nop 0
	global_load_lds_dwordx4 v219, s[0:1]
	s_add_u32 s0, s8, 0x80000
	s_addc_u32 s1, s9, 0
	s_add_i32 s31, s33, s12
	s_mov_b32 m0, s31
	s_nop 0
	global_load_lds_dwordx4 v189, s[0:1]
	s_add_i32 m0, s31, 0x2000
	s_nop 0
	global_load_lds_dwordx4 v219, s[0:1]
	s_mov_b64 s[0:1], s[10:11]
	s_mov_b32 m0, s13
	s_nop 0
	global_load_lds_dwordx4 v1, s[0:1]
	s_mov_b32 m0, s14
	s_nop 0
	global_load_lds_dwordx4 v191, s[0:1]
	s_waitcnt vmcnt(8)
	s_waitcnt lgkmcnt(0)
	s_cmp_lg_u32 s98, 0
	s_cbranch_scc1 .Lhb_2
	s_barrier
; #define PG8_STAGE(bufoff, gbase, voff) do { const char* gb_ = (const char*)(gbase); asm volatile("" : "+s"(gb_)); _Pragma("unroll") for (int _i = 0; _i < 2; ++_i) { unsigned vo_ = (voff)[_i]; asm volatile("" : "+v"(vo_));        \
;         __builtin_amdgcn_global_load_lds((const unsigned*)(gb_ + vo_), (PG8_LAS unsigned*)(lds + (bufoff) + ldsw + _i * 8192), 16, 0, 0); } } while (0)
; #define PG8_LDA(dst, b, h) do { _Pragma("unroll") for (int m = 0; m < 4; ++m) _Pragma("unroll") for (int k = 0; k < 2; ++k) dst[m][k] = *(const PG8_LAS bf16x8*)(lds + PG8_SA(b, h) + aoff + m * 2048 + k * 1024); } while (0)
; #define PG8_LDB(dst, b, h) do { _Pragma("unroll") for (int n = 0; n < 2; ++n) _Pragma("unroll") for (int k = 0; k < 2; ++k) dst[n][k] = *(const PG8_LAS bf16x8*)(lds + PG8_SB(b, h) + boff + n * 2048 + k * 1024); } while (0)
; #define PG8_MMA(ai, bj, At, Bt) do { __builtin_amdgcn_s_setprio(1); _Pragma("unroll") for (int m = 0; m < 4; ++m) _Pragma("unroll") for (int n = 0; n < 2; ++n) _Pragma("unroll") for (int k = 0; k < 2; ++k) \
;         acc[ai][bj][m][n] = __builtin_amdgcn_mfma_f32_16x16x32_bf16(Bt[n][k], At[m][k], acc[ai][bj][m][n], 0, 0, 0); __builtin_amdgcn_s_setprio(0); } while (0)
; #define PG8_WAIT_V(n) asm volatile("s_waitcnt vmcnt(" #n ")" ::: "memory")
; #define PG8_WAIT_L(n) asm volatile("s_waitcnt lgkmcnt(" #n ")" ::: "memory")
; #define PG8_BAR __builtin_amdgcn_s_barrier()
; #define PG8_SCHED __builtin_amdgcn_sched_barrier(0)
; template <class Epi, class Sched, bool ALIGN_EPI = false, bool SP2 = false>
; __device__ __forceinline__ void gemm_phase(PG8_LAS unsigned char* lds, const Gemm g, const Sched& S, const Epi& E) {
;     ...
;             PG8_WAIT_V(8); PG8_WAIT_L(0); PG8_BAR; PG8_MMA(1, 0, At, B0); PG8_MMA(1, 1, At, B1); PG8_BAR; PG8_SCHED;
;             PG8_LDB(B0, 1, 0); PG8_LDB(B1, 1, 1); PG8_SCHED; PG8_LDA(At, 1, 0); PG8_STAGE(PG8_SA(0, 1), a2 + hstep, voffA);
;             PG8_WAIT_V(8); PG8_WAIT_L(0); PG8_BAR; PG8_MMA(0, 0, At, B0); PG8_MMA(0, 1, At, B1); PG8_BAR; PG8_SCHED;
.Lhb_2:
	s_setprio 1
	s_waitcnt lgkmcnt(0)
	v_mfma_f32_16x16x32_bf16 v[110:113], v[66:69], v[178:181], v[110:113]
	v_mfma_f32_16x16x32_bf16 v[110:113], v[70:73], v[182:185], v[110:113]
	v_mfma_f32_16x16x32_bf16 v[102:105], v[66:69], v[192:195], v[102:105]
	v_mfma_f32_16x16x32_bf16 v[102:105], v[70:73], v[196:199], v[102:105]
	v_mfma_f32_16x16x32_bf16 v[94:97], v[66:69], v[200:203], v[94:97]
	v_mfma_f32_16x16x32_bf16 v[94:97], v[70:73], v[204:207], v[94:97]
	v_mfma_f32_16x16x32_bf16 v[66:69], v[66:69], v[208:211], v[86:89]
	v_mfma_f32_16x16x32_bf16 v[66:69], v[70:73], v[212:215], v[66:69]
	v_mfma_f32_16x16x32_bf16 v[106:109], v[74:77], v[178:181], v[106:109]
	v_mfma_f32_16x16x32_bf16 v[106:109], v[78:81], v[182:185], v[106:109]
	v_mfma_f32_16x16x32_bf16 v[98:101], v[74:77], v[192:195], v[98:101]
	v_mfma_f32_16x16x32_bf16 v[98:101], v[78:81], v[196:199], v[98:101]
	v_mfma_f32_16x16x32_bf16 v[90:93], v[74:77], v[200:203], v[90:93]
	v_mfma_f32_16x16x32_bf16 v[90:93], v[78:81], v[204:207], v[90:93]
	v_mfma_f32_16x16x32_bf16 v[70:73], v[74:77], v[208:211], v[82:85]
	v_mfma_f32_16x16x32_bf16 v[70:73], v[78:81], v[212:215], v[70:73]
	s_setprio 0
	s_setprio 1
	v_mfma_f32_16x16x32_bf16 v[30:33], v[146:149], v[178:181], v[30:33]
	v_mfma_f32_16x16x32_bf16 v[30:33], v[150:153], v[182:185], v[30:33]
	v_mfma_f32_16x16x32_bf16 v[22:25], v[146:149], v[192:195], v[22:25]
	v_mfma_f32_16x16x32_bf16 v[22:25], v[150:153], v[196:199], v[22:25]
	v_mfma_f32_16x16x32_bf16 v[14:17], v[146:149], v[200:203], v[14:17]
	v_mfma_f32_16x16x32_bf16 v[14:17], v[150:153], v[204:207], v[14:17]
	v_mfma_f32_16x16x32_bf16 v[6:9], v[146:149], v[208:211], v[6:9]
	v_mfma_f32_16x16x32_bf16 v[6:9], v[150:153], v[212:215], v[6:9]
	v_mfma_f32_16x16x32_bf16 v[26:29], v[154:157], v[178:181], v[26:29]
	v_mfma_f32_16x16x32_bf16 v[26:29], v[158:161], v[182:185], v[26:29]
	v_mfma_f32_16x16x32_bf16 v[18:21], v[154:157], v[192:195], v[18:21]
	v_mfma_f32_16x16x32_bf16 v[18:21], v[158:161], v[196:199], v[18:21]
	v_mfma_f32_16x16x32_bf16 v[10:13], v[154:157], v[200:203], v[10:13]
	v_mfma_f32_16x16x32_bf16 v[10:13], v[158:161], v[204:207], v[10:13]
	v_mfma_f32_16x16x32_bf16 v[2:5], v[154:157], v[208:211], v[2:5]
	v_mfma_f32_16x16x32_bf16 v[2:5], v[158:161], v[212:215], v[2:5]
	s_setprio 0
	s_cmp_eq_u32 s98, 0
	s_cbranch_scc1 .Lhb_3
	s_barrier
.Lhb_3:
	s_add_i32 s31, 0, 0x18000
	s_add_i32 s33, 0, 0x1c000
	ds_read_b128 v[74:77], v244 offset:32768
	ds_read_b128 v[78:81], v244 offset:33792
	ds_read_b128 v[82:85], v244 offset:34816
	ds_read_b128 v[146:149], v244 offset:35840
	ds_read_b128 v[150:153], v244 offset:49152
	ds_read_b128 v[154:157], v244 offset:50176
	ds_read_b128 v[158:161], v244 offset:51200
	ds_read_b128 v[178:181], v244 offset:52224
	s_add_u32 s0, s10, 0x80000
	s_addc_u32 s1, s11, 0
	s_mov_b32 m0, s15
	ds_read_b128 v[86:89], v223 offset:32768
	ds_read_b128 v[182:185], v223 offset:33792
	ds_read_b128 v[192:195], v223 offset:34816
	ds_read_b128 v[196:199], v223 offset:35840
	ds_read_b128 v[200:203], v223 offset:36864
	ds_read_b128 v[204:207], v223 offset:37888
	ds_read_b128 v[208:211], v223 offset:38912
	ds_read_b128 v[212:215], v223 offset:39936
	s_nop 0
	global_load_lds_dwordx4 v1, s[0:1]
	s_mov_b32 m0, s16
	s_nop 0
	global_load_lds_dwordx4 v191, s[0:1]
	s_waitcnt vmcnt(8)
	s_waitcnt lgkmcnt(0)
	s_cmp_lg_u32 s98, 0
	s_cbranch_scc1 .Lhb_4
	s_barrier
.Lhb_4:
	s_setprio 1
	s_waitcnt lgkmcnt(0)
	v_mfma_f32_16x16x32_bf16 v[142:145], v[74:77], v[86:89], v[142:145]
	v_mfma_f32_16x16x32_bf16 v[142:145], v[78:81], v[182:185], v[142:145]
	v_mfma_f32_16x16x32_bf16 v[134:137], v[74:77], v[192:195], v[134:137]
	v_mfma_f32_16x16x32_bf16 v[134:137], v[78:81], v[196:199], v[134:137]
	v_mfma_f32_16x16x32_bf16 v[126:129], v[74:77], v[200:203], v[126:129]
	v_mfma_f32_16x16x32_bf16 v[126:129], v[78:81], v[204:207], v[126:129]
	v_mfma_f32_16x16x32_bf16 v[118:121], v[74:77], v[208:211], v[118:121]
	v_mfma_f32_16x16x32_bf16 v[118:121], v[78:81], v[212:215], v[118:121]
	v_mfma_f32_16x16x32_bf16 v[138:141], v[82:85], v[86:89], v[138:141]
	v_mfma_f32_16x16x32_bf16 v[138:141], v[146:149], v[182:185], v[138:141]
	v_mfma_f32_16x16x32_bf16 v[130:133], v[82:85], v[192:195], v[130:133]
	v_mfma_f32_16x16x32_bf16 v[130:133], v[146:149], v[196:199], v[130:133]
	v_mfma_f32_16x16x32_bf16 v[122:125], v[82:85], v[200:203], v[122:125]
	v_mfma_f32_16x16x32_bf16 v[122:125], v[146:149], v[204:207], v[122:125]
	v_mfma_f32_16x16x32_bf16 v[114:117], v[82:85], v[208:211], v[114:117]
	v_mfma_f32_16x16x32_bf16 v[114:117], v[146:149], v[212:215], v[114:117]
	s_setprio 0
	s_setprio 1
	v_mfma_f32_16x16x32_bf16 v[62:65], v[150:153], v[86:89], v[62:65]
	v_mfma_f32_16x16x32_bf16 v[62:65], v[154:157], v[182:185], v[62:65]
	v_mfma_f32_16x16x32_bf16 v[54:57], v[150:153], v[192:195], v[54:57]
	v_mfma_f32_16x16x32_bf16 v[54:57], v[154:157], v[196:199], v[54:57]
	v_mfma_f32_16x16x32_bf16 v[46:49], v[150:153], v[200:203], v[46:49]
	v_mfma_f32_16x16x32_bf16 v[46:49], v[154:157], v[204:207], v[46:49]
	v_mfma_f32_16x16x32_bf16 v[38:41], v[150:153], v[208:211], v[38:41]
	v_mfma_f32_16x16x32_bf16 v[38:41], v[154:157], v[212:215], v[38:41]
	v_mfma_f32_16x16x32_bf16 v[58:61], v[158:161], v[86:89], v[58:61]
	v_mfma_f32_16x16x32_bf16 v[58:61], v[178:181], v[182:185], v[58:61]
	v_mfma_f32_16x16x32_bf16 v[50:53], v[158:161], v[192:195], v[50:53]
	v_mfma_f32_16x16x32_bf16 v[50:53], v[178:181], v[196:199], v[50:53]
	v_mfma_f32_16x16x32_bf16 v[42:45], v[158:161], v[200:203], v[42:45]
	v_mfma_f32_16x16x32_bf16 v[42:45], v[178:181], v[204:207], v[42:45]
	v_mfma_f32_16x16x32_bf16 v[34:37], v[158:161], v[208:211], v[34:37]
	v_mfma_f32_16x16x32_bf16 v[34:37], v[178:181], v[212:215], v[34:37]
	s_setprio 0
	s_cmp_eq_u32 s98, 0
	s_cbranch_scc1 .Lhb_5
	s_barrier
; #define PG8_STAGE(bufoff, gbase, voff) do { const char* gb_ = (const char*)(gbase); asm volatile("" : "+s"(gb_)); _Pragma("unroll") for (int _i = 0; _i < 2; ++_i) { unsigned vo_ = (voff)[_i]; asm volatile("" : "+v"(vo_));        \
;         __builtin_amdgcn_global_load_lds((const unsigned*)(gb_ + vo_), (PG8_LAS unsigned*)(lds + (bufoff) + ldsw + _i * 8192), 16, 0, 0); } } while (0)
; #define PG8_LDA(dst, b, h) do { _Pragma("unroll") for (int m = 0; m < 4; ++m) _Pragma("unroll") for (int k = 0; k < 2; ++k) dst[m][k] = *(const PG8_LAS bf16x8*)(lds + PG8_SA(b, h) + aoff + m * 2048 + k * 1024); } while (0)
; #define PG8_MMA(ai, bj, At, Bt) do { __builtin_amdgcn_s_setprio(1); _Pragma("unroll") for (int m = 0; m < 4; ++m) _Pragma("unroll") for (int n = 0; n < 2; ++n) _Pragma("unroll") for (int k = 0; k < 2; ++k) \
;         acc[ai][bj][m][n] = __builtin_amdgcn_mfma_f32_16x16x32_bf16(Bt[n][k], At[m][k], acc[ai][bj][m][n], 0, 0, 0); __builtin_amdgcn_s_setprio(0); } while (0)
; #define PG8_WAIT_V(n) asm volatile("s_waitcnt vmcnt(" #n ")" ::: "memory")
; #define PG8_WAIT_L(n) asm volatile("s_waitcnt lgkmcnt(" #n ")" ::: "memory")
; #define PG8_BAR __builtin_amdgcn_s_barrier()
; #define PG8_SCHED __builtin_amdgcn_sched_barrier(0)
; template <class Epi, class Sched, bool ALIGN_EPI = false, bool SP2 = false>
; __device__ __forceinline__ void gemm_phase(PG8_LAS unsigned char* lds, const Gemm g, const Sched& S, const Epi& E) {
;     ...
;             PG8_LDA(At, 1, 1); PG8_STAGE(PG8_SB(1, 0), b3, voffB); PG8_STAGE(PG8_SB(1, 1), b3 + hstep, voffB); PG8_STAGE(PG8_SA(1, 0), a3, voffA);
;             PG8_WAIT_V(8); PG8_WAIT_L(0); PG8_BAR; PG8_MMA(1, 0, At, B0); PG8_MMA(1, 1, At, B1); PG8_BAR; PG8_SCHED;
;     ...
;         if constexpr (ALIGN_EPI) { if (wr == 0) PG8_BAR; }
.Lhb_5:
	s_add_u32 s0, s8, 0x80
	s_addc_u32 s1, s9, 0
	s_add_i32 s10, s31, s12
	ds_read_b128 v[182:185], v223 offset:49152
	ds_read_b128 v[192:195], v223 offset:50176
	ds_read_b128 v[196:199], v223 offset:51200
	ds_read_b128 v[200:203], v223 offset:52224
	ds_read_b128 v[204:207], v223 offset:53248
	ds_read_b128 v[208:211], v223 offset:54272
	ds_read_b128 v[212:215], v223 offset:55296
	ds_read_b128 v[224:227], v223 offset:56320
	s_mov_b32 m0, s10
	s_nop 0
	global_load_lds_dwordx4 v189, s[0:1]
	s_add_i32 m0, s10, 0x2000
	s_nop 0
	global_load_lds_dwordx4 v219, s[0:1]
	s_add_u32 s0, s8, 0x80080
	s_addc_u32 s1, s9, 0
	s_add_i32 s8, s33, s12
	s_mov_b32 m0, s8
	s_nop 0
	global_load_lds_dwordx4 v189, s[0:1]
	s_add_i32 m0, s8, 0x2000
	s_nop 0
	global_load_lds_dwordx4 v219, s[0:1]
	s_mov_b32 m0, s19
	s_nop 0
	global_load_lds_dwordx4 v1, s[6:7]
	s_mov_b32 m0, s20
	s_nop 0
	global_load_lds_dwordx4 v191, s[6:7]
	s_waitcnt vmcnt(8)
	s_waitcnt lgkmcnt(0)
	s_cmp_lg_u32 s98, 0
	s_cbranch_scc1 .Lhb_6
	s_barrier
.Lhb_6:
	s_setprio 1
	s_waitcnt lgkmcnt(0)
	v_mfma_f32_16x16x32_bf16 v[86:89], v[74:77], v[182:185], v[110:113]
	v_mfma_f32_16x16x32_bf16 v[110:113], v[78:81], v[192:195], v[86:89]
	v_mfma_f32_16x16x32_bf16 v[66:69], v[74:77], v[212:215], v[66:69]
	v_mfma_f32_16x16x32_bf16 v[86:89], v[82:85], v[182:185], v[106:109]
	v_mfma_f32_16x16x32_bf16 v[106:109], v[146:149], v[192:195], v[86:89]
	v_mfma_f32_16x16x32_bf16 v[86:89], v[74:77], v[196:199], v[102:105]
	v_mfma_f32_16x16x32_bf16 v[102:105], v[78:81], v[200:203], v[86:89]
	v_mfma_f32_16x16x32_bf16 v[86:89], v[82:85], v[196:199], v[98:101]
	v_mfma_f32_16x16x32_bf16 v[98:101], v[146:149], v[200:203], v[86:89]
	v_mfma_f32_16x16x32_bf16 v[86:89], v[74:77], v[204:207], v[94:97]
	v_mfma_f32_16x16x32_bf16 v[94:97], v[78:81], v[208:211], v[86:89]
	v_mfma_f32_16x16x32_bf16 v[86:89], v[82:85], v[204:207], v[90:93]
	v_mfma_f32_16x16x32_bf16 v[90:93], v[146:149], v[208:211], v[86:89]
	v_mfma_f32_16x16x32_bf16 v[86:89], v[78:81], v[224:227], v[66:69]
	v_mfma_f32_16x16x32_bf16 v[66:69], v[82:85], v[212:215], v[70:73]
	v_mfma_f32_16x16x32_bf16 v[82:85], v[146:149], v[224:227], v[66:69]
	s_setprio 0
	s_setprio 1
	v_mfma_f32_16x16x32_bf16 v[30:33], v[150:153], v[182:185], v[30:33]
	v_mfma_f32_16x16x32_bf16 v[30:33], v[154:157], v[192:195], v[30:33]
	v_mfma_f32_16x16x32_bf16 v[22:25], v[150:153], v[196:199], v[22:25]
	v_mfma_f32_16x16x32_bf16 v[22:25], v[154:157], v[200:203], v[22:25]
	v_mfma_f32_16x16x32_bf16 v[14:17], v[150:153], v[204:207], v[14:17]
	v_mfma_f32_16x16x32_bf16 v[14:17], v[154:157], v[208:211], v[14:17]
	v_mfma_f32_16x16x32_bf16 v[6:9], v[150:153], v[212:215], v[6:9]
	v_mfma_f32_16x16x32_bf16 v[6:9], v[154:157], v[224:227], v[6:9]
	v_mfma_f32_16x16x32_bf16 v[26:29], v[158:161], v[182:185], v[26:29]
	v_mfma_f32_16x16x32_bf16 v[26:29], v[178:181], v[192:195], v[26:29]
	v_mfma_f32_16x16x32_bf16 v[18:21], v[158:161], v[196:199], v[18:21]
	v_mfma_f32_16x16x32_bf16 v[18:21], v[178:181], v[200:203], v[18:21]
	v_mfma_f32_16x16x32_bf16 v[10:13], v[158:161], v[204:207], v[10:13]
	v_mfma_f32_16x16x32_bf16 v[10:13], v[178:181], v[208:211], v[10:13]
	v_mfma_f32_16x16x32_bf16 v[2:5], v[158:161], v[212:215], v[2:5]
	v_mfma_f32_16x16x32_bf16 v[2:5], v[178:181], v[224:227], v[2:5]
	s_setprio 0
	s_cmp_eq_u32 s98, 0
	s_cbranch_scc1 .Lhb_7
	s_barrier
.Lhb_7:
	s_add_i32 s30, s30, 2
	s_add_u32 s28, s28, 0x100
	s_addc_u32 s29, s29, 0
	s_cmp_gt_u32 s30, 29
	s_mov_b64 s[0:1], s[2:3]
	s_cbranch_scc0 .LBB0_232
	s_and_b64 vcc, exec, s[44:45]
	s_cbranch_vccz .LBB0_235

; #define PG8_BAR __builtin_amdgcn_s_barrier()
; template <class Epi, class Sched, bool ALIGN_EPI = false, bool SP2 = false>
; __device__ __forceinline__ void gemm_phase(PG8_LAS unsigned char* lds, const Gemm g, const Sched& S, const Epi& E) {
;     ...
;         if constexpr (ALIGN_EPI) { if (wr == 1) PG8_BAR; }
.LBB0_276:
	s_andn2_b64 vcc, exec, s[4:5]
	s_cbranch_vccnz .LBB0_227
	s_branch .LBB0_227

; #define PG8_STAGE(bufoff, gbase, voff) do { const char* gb_ = (const char*)(gbase); asm volatile("" : "+s"(gb_)); _Pragma("unroll") for (int _i = 0; _i < 2; ++_i) { unsigned vo_ = (voff)[_i]; asm volatile("" : "+v"(vo_));        \
;         __builtin_amdgcn_global_load_lds((const unsigned*)(gb_ + vo_), (PG8_LAS unsigned*)(lds + (bufoff) + ldsw + _i * 8192), 16, 0, 0); } } while (0)
; #define PG8_WAIT_V(n) asm volatile("s_waitcnt vmcnt(" #n ")" ::: "memory")
; #define PG8_BAR __builtin_amdgcn_s_barrier()
; template <class Epi, class Sched, bool ALIGN_EPI = false, bool SP2 = false>
; __device__ __forceinline__ void gemm_phase(PG8_LAS unsigned char* lds, const Gemm g, const Sched& S, const Epi& E) {
;     ...
;     for (int i = 0; i < 2; ++i) { int R, C; stage_rc(tid * 16 + i * 8192, R, C); const int Rb = Epi::PERM ? ((R & ~31) + perm32(R & 31)) : R;
;         voffA[i] = (unsigned)(R * K + C) * 2u; voffB[i] = (unsigned)(Rb * K + C) * 2u; }
;     const size_t kstep = (size_t)(BK * 2);
;     const size_t hstep = (size_t)HALF * K * 2;
;     const size_t tstep = 2 * hstep;
;     const unsigned ldsw = (unsigned)wid * 1024u;
;     const int aoff = lds_byte(wr * 64 + fr, fq * 8), boff = lds_byte(wc * 32 + fr, fq * 8);
;     ...
;     const char* cA = (const char*)g.A + (size_t)cur.pm * tstep; const char* cB = (const char*)g.Bt + (size_t)cur.pn * tstep;
;     S.a_ready(cur);
;     if constexpr (SP2) {
;         PG8_STAGE(PG8_SB(0, 0), cB, voffB); PG8_STAGE(PG8_SB(0, 1), cB + hstep, voffB); PG8_STAGE(PG8_SA(0, 0), cA, voffA); PG8_STAGE(PG8_SA(0, 1), cA + hstep, voffA);
;         if (wr == 1) PG8_BAR;
;         PG8_WAIT_V(2); PG8_BAR;
;         PG8_STAGE(PG8_SB(1, 0), cB + kstep, voffB); PG8_STAGE(PG8_SA(1, 0), cA + kstep, voffA); PG8_STAGE(PG8_SB(1, 1), cB + hstep + kstep, voffB);
;         PG8_WAIT_V(6); PG8_BAR;
.LBB0_542:
	s_andn2_b64 vcc, exec, s[0:1]
	v_readlane_b32 s0, v243, 63
	v_readlane_b32 s1, v242, 0
	s_nop 1
	v_cndmask_b32_e64 v1, 0, 1, s[0:1]
	v_cmp_ne_u32_e64 s[36:37], 1, v1
	s_cbranch_vccnz .LBB0_622
	s_waitcnt vmcnt(0)
	v_mov_b32_e32 v2, v0
	s_and_b64 vcc, exec, s[36:37]
	v_readfirstlane_b32 s14, v2
	s_cbranch_vccnz .LBB0_575
	v_bfe_i32 v4, v2, 27, 1
	s_waitcnt lgkmcnt(0)
	v_lshlrev_b32_e32 v3, 4, v2
	v_lshrrev_b32_e32 v4, 22, v4
	v_add_u32_e32 v4, v3, v4
	v_and_b32_e32 v4, 0xfffffc00, v4
	v_sub_u32_e32 v4, v3, v4
	v_ashrrev_i32_e32 v1, 31, v2
	v_lshrrev_b32_e32 v5, 4, v4
	v_lshrrev_b32_e32 v1, 26, v1
	v_bitop3_b32 v4, v5, v4, 32 bitop3:0x6c
	v_add_u32_e32 v1, v2, v1
	v_ashrrev_i32_e32 v6, 31, v4
	v_ashrrev_i32_e32 v1, 6, v1
	v_lshrrev_b32_e32 v6, 26, v6
	v_lshlrev_b32_e32 v5, 3, v1
	v_add_u32_e32 v6, v4, v6
	v_and_b32_e32 v5, -16, v5
	v_ashrrev_i32_e32 v7, 6, v6
	v_and_b32_e32 v6, 0xc0, v6
	v_add_u32_e32 v5, v7, v5
	v_sub_u32_e32 v4, v4, v6
	v_lshlrev_b32_e32 v1, 5, v1
	v_ashrrev_i16_sdwa v4, v217, sext(v4) dst_sel:DWORD dst_unused:UNUSED_PAD src0_sel:DWORD src1_sel:BYTE_0
	v_lshlrev_b32_e32 v6, 1, v5
	v_lshrrev_b32_e32 v8, 2, v5
	v_and_b32_e32 v7, 3, v7
	s_mov_b32 s1, 0xfffe0
	v_and_b32_e32 v1, 32, v1
	v_bfe_i32 v4, v4, 0, 16
	v_and_b32_e32 v6, 24, v6
	v_and_b32_e32 v8, 4, v8
	v_and_or_b32 v7, v5, s1, v7
	v_or3_b32 v6, v7, v8, v6
	v_add_lshl_u32 v4, v1, v4, 1
	v_add_u32_e32 v3, 0x2000, v3
	v_lshl_add_u32 v1, v5, 12, v4
	v_lshl_add_u32 v162, v6, 12, v4
	v_ashrrev_i32_e32 v4, 31, v3
	v_lshrrev_b32_e32 v4, 22, v4
	v_add_u32_e32 v4, v3, v4
	v_ashrrev_i32_e32 v4, 10, v4
	v_mul_i32_i24_e32 v5, 0x400, v4
	v_sub_u32_e32 v3, v3, v5
	v_lshrrev_b32_e32 v5, 4, v3
	v_bitop3_b32 v3, v5, v3, 32 bitop3:0x6c
	v_ashrrev_i32_e32 v6, 31, v3
	v_lshrrev_b32_e32 v6, 26, v6
	v_lshlrev_b32_e32 v5, 3, v4
	v_add_u32_e32 v6, v3, v6
	v_readlane_b32 s0, v241, 44
	v_and_b32_e32 v5, -16, v5
	v_ashrrev_i32_e32 v7, 6, v6
	s_add_u32 s15, s0, 0x1c00000
	v_readlane_b32 s0, v241, 45
	v_add_u32_e32 v5, v7, v5
	v_and_b32_e32 v6, 0xc0, v6
	v_and_b32_e32 v7, 3, v7
	s_addc_u32 s16, s0, 0
	v_sub_u32_e32 v3, v3, v6
	v_and_or_b32 v7, v5, s1, v7
	s_ashr_i32 s1, s14, 6
	s_ashr_i32 s0, s14, 8
	v_lshlrev_b32_e32 v4, 5, v4
	v_ashrrev_i16_sdwa v3, v217, sext(v3) dst_sel:DWORD dst_unused:UNUSED_PAD src0_sel:DWORD src1_sel:BYTE_0
	v_lshlrev_b32_e32 v6, 1, v5
	v_lshrrev_b32_e32 v8, 2, v5
	s_lshl_b32 s17, s1, 10
	v_readlane_b32 s2, v242, 28
	v_and_b32_e32 v4, 32, v4
	v_bfe_i32 v3, v3, 0, 16
	v_and_b32_e32 v6, 24, v6
	v_and_b32_e32 v8, 4, v8
	v_readlane_b32 s3, v242, 29
	s_add_u32 s6, s15, s2
	v_or3_b32 v6, v7, v8, v6
	v_add_lshl_u32 v3, v4, v3, 1
	s_addc_u32 s7, s16, s3
	v_lshl_add_u32 v164, v5, 12, v3
	v_lshl_add_u32 v206, v6, 12, v3
	s_mov_b64 s[2:3], s[6:7]
	s_add_i32 s18, s17, 0
	v_mov_b32_e32 v3, v162
	s_add_i32 m0, s18, 0x10000
	s_nop 0
	global_load_lds_dwordx4 v3, s[2:3]
	v_mov_b32_e32 v3, v206
	s_add_i32 m0, s18, 0x12000
	s_nop 0
	global_load_lds_dwordx4 v3, s[2:3]
	s_add_u32 s2, s6, 0x80000
	s_addc_u32 s3, s7, 0
	v_mov_b32_e32 v3, v162
	s_add_i32 m0, s18, 0x14000
	s_add_i32 s19, s18, 0x2000
	global_load_lds_dwordx4 v3, s[2:3]
	v_mov_b32_e32 v3, v206
	s_add_i32 m0, s18, 0x16000
	s_add_i32 s20, s18, 0x4000
	global_load_lds_dwordx4 v3, s[2:3]
	v_readlane_b32 s2, v242, 34
	v_readlane_b32 s3, v242, 35
	v_mov_b32_e32 v3, v1
	s_mov_b32 m0, s18
	s_add_i32 s21, s18, 0x6000
	s_nop 1
	global_load_lds_dwordx4 v3, s[2:3]
	v_mov_b32_e32 v3, v164
	s_mov_b32 m0, s19
	s_cmp_lg_u32 s0, 1
	global_load_lds_dwordx4 v3, s[2:3]
	v_readlane_b32 s2, v242, 32
	v_readlane_b32 s3, v242, 33
	v_mov_b32_e32 v3, v1
	s_mov_b32 m0, s20
	s_nop 2
	global_load_lds_dwordx4 v3, s[2:3]
	v_mov_b32_e32 v3, v164
	s_mov_b32 m0, s21
	s_nop 0
	global_load_lds_dwordx4 v3, s[2:3]
	s_cbranch_scc1 .LBB0_546
.LBB0_546:
	s_add_u32 s22, s30, 0x4000
	v_readlane_b32 s2, v241, 48
	s_addc_u32 s23, s31, 0
	s_lshl_b32 s40, s2, 11
	s_lshl_b64 s[2:3], s[40:41], 2
	s_add_u32 s46, s60, s2
	s_addc_u32 s47, s61, s3
	s_add_u32 s24, s30, 0x8000
	s_addc_u32 s25, s31, 0
	s_lshl_b32 s1, s1, 5
	s_and_b32 s5, s1, 0x60
	s_lshl_b32 s4, s0, 13
	s_lshl_b32 s1, s5, 7
	s_add_u32 s2, s6, 0x80
	s_addc_u32 s3, s7, 0
	v_mov_b32_e32 v3, v162
	s_waitcnt vmcnt(2)
	s_barrier
	s_add_i32 m0, s18, 0x18000
	s_add_i32 s26, s18, 0x8000
	global_load_lds_dwordx4 v3, s[2:3]
	v_mov_b32_e32 v3, v206
	s_add_i32 m0, s18, 0x1a000
	s_add_i32 s27, s18, 0xa000
	global_load_lds_dwordx4 v3, s[2:3]
	v_readlane_b32 s2, v242, 36
	v_readlane_b32 s3, v242, 37
	v_mov_b32_e32 v3, v1
	s_mov_b32 m0, s26
	v_bfe_u32 v4, v2, 4, 2
	s_nop 1
	global_load_lds_dwordx4 v3, s[2:3]
	v_mov_b32_e32 v3, v164
	s_mov_b32 m0, s27
	v_lshlrev_b32_e32 v5, 4, v4
	global_load_lds_dwordx4 v3, s[2:3]
	s_add_u32 s2, s6, 0x80080
	s_addc_u32 s3, s7, 0
	v_mov_b32_e32 v3, v162
	s_add_i32 m0, s18, 0x1c000
	v_lshl_or_b32 v209, v4, 3, s5
	global_load_lds_dwordx4 v3, s[2:3]
	v_mov_b32_e32 v3, v206
	s_add_i32 m0, s18, 0x1e000
	s_mov_b32 s28, 0
	global_load_lds_dwordx4 v3, s[2:3]
	v_and_b32_e32 v3, 15, v2
	v_lshlrev_b32_e32 v2, 2, v2
	v_lshl_or_b32 v207, s0, 6, v3
	v_lshl_or_b32 v3, v3, 6, v5
	v_and_b32_e32 v2, 32, v2
	s_waitcnt vmcnt(6)
	v_bitop3_b32 v5, v3, s4, v2 bitop3:0xde
	v_readlane_b32 s2, v242, 38
	v_readlane_b32 s4, v242, 34
	v_bitop3_b32 v208, v3, s1, v2 bitop3:0xde
	v_cmp_eq_u32_e64 s[0:1], 0, v4
	v_add_u32_e32 v210, 0, v5
	v_readlane_b32 s33, v242, 9
	s_mov_b32 s29, s2
	v_readlane_b32 s5, v242, 35
	s_barrier
	v_readlane_b32 s3, v242, 39
	s_branch .LBB0_548

; #define PG8_STAGE(bufoff, gbase, voff) do { const char* gb_ = (const char*)(gbase); asm volatile("" : "+s"(gb_)); _Pragma("unroll") for (int _i = 0; _i < 2; ++_i) { unsigned vo_ = (voff)[_i]; asm volatile("" : "+v"(vo_));        \
;         __builtin_amdgcn_global_load_lds((const unsigned*)(gb_ + vo_), (PG8_LAS unsigned*)(lds + (bufoff) + ldsw + _i * 8192), 16, 0, 0); } } while (0)
; #define PG8_LDA(dst, b, h) do { _Pragma("unroll") for (int m = 0; m < 4; ++m) _Pragma("unroll") for (int k = 0; k < 2; ++k) dst[m][k] = *(const PG8_LAS bf16x8*)(lds + PG8_SA(b, h) + aoff + m * 2048 + k * 1024); } while (0)
; #define PG8_LDB(dst, b, h) do { _Pragma("unroll") for (int n = 0; n < 2; ++n) _Pragma("unroll") for (int k = 0; k < 2; ++k) dst[n][k] = *(const PG8_LAS bf16x8*)(lds + PG8_SB(b, h) + boff + n * 2048 + k * 1024); } while (0)
; #define PG8_MMA(ai, bj, At, Bt) do { __builtin_amdgcn_s_setprio(1); _Pragma("unroll") for (int m = 0; m < 4; ++m) _Pragma("unroll") for (int n = 0; n < 2; ++n) _Pragma("unroll") for (int k = 0; k < 2; ++k) \
;         acc[ai][bj][m][n] = __builtin_amdgcn_mfma_f32_16x16x32_bf16(Bt[n][k], At[m][k], acc[ai][bj][m][n], 0, 0, 0); __builtin_amdgcn_s_setprio(0); } while (0)
; #define PG8_WAIT_V(n) asm volatile("s_waitcnt vmcnt(" #n ")" ::: "memory")
; #define PG8_WAIT_L(n) asm volatile("s_waitcnt lgkmcnt(" #n ")" ::: "memory")
; #define PG8_BAR __builtin_amdgcn_s_barrier()
; #define PG8_SCHED __builtin_amdgcn_sched_barrier(0)
; template <class Epi, class Sched, bool ALIGN_EPI = false, bool SP2 = false>
; __device__ __forceinline__ void gemm_phase(PG8_LAS unsigned char* lds, const Gemm g, const Sched& S, const Epi& E) {
;     ...
;             PG8_LDB(B0, 0, 0); PG8_LDB(B1, 0, 1); PG8_SCHED; PG8_LDA(At, 0, 0); PG8_STAGE(PG8_SA(1, 1), a1 + hstep, voffA);
;             PG8_WAIT_V(8); PG8_WAIT_L(0); PG8_BAR; PG8_MMA(0, 0, At, B0); PG8_MMA(0, 1, At, B1); PG8_BAR; PG8_SCHED;
;             PG8_LDA(At, 0, 1); PG8_STAGE(PG8_SB(0, 0), b2, voffB); PG8_STAGE(PG8_SB(0, 1), b2 + hstep, voffB); PG8_STAGE(PG8_SA(0, 0), a2, voffA);
;             PG8_WAIT_V(8); PG8_WAIT_L(0); PG8_BAR; PG8_MMA(1, 0, At, B0); PG8_MMA(1, 1, At, B1); PG8_BAR; PG8_SCHED;
.LBB0_555:
	s_add_u32 s6, s4, 0x100
	s_addc_u32 s7, s5, 0
	s_cmp_eq_u32 s51, 28
	s_cselect_b32 s12, s35, s6
	s_cselect_b32 s13, s34, s7
	s_cselect_b32 s10, s39, s40
	s_cselect_b32 s11, s38, s49
	s_add_u32 s8, s12, 0x80
	s_addc_u32 s9, s13, 0
	s_add_i32 s56, 0, 0x10000
	s_add_i32 s57, 0, 0x14000
	ds_read_b128 v[26:29], v244
	ds_read_b128 v[30:33], v244 offset:1024
	ds_read_b128 v[98:101], v244 offset:2048
	ds_read_b128 v[102:105], v244 offset:3072
	ds_read_b128 v[146:149], v244 offset:16384
	ds_read_b128 v[150:153], v244 offset:17408
	ds_read_b128 v[154:157], v244 offset:18432
	ds_read_b128 v[158:161], v244 offset:19456
	s_add_u32 s4, s4, 0x80080
	s_addc_u32 s5, s5, 0
	ds_read_b128 v[178:181], v210
	ds_read_b128 v[182:185], v210 offset:1024
	ds_read_b128 v[186:189], v210 offset:2048
	ds_read_b128 v[190:193], v210 offset:3072
	ds_read_b128 v[194:197], v210 offset:4096
	ds_read_b128 v[198:201], v210 offset:5120
	ds_read_b128 v[202:205], v210 offset:6144
	ds_read_b128 v[212:215], v210 offset:7168
	s_add_i32 m0, s18, 0xc000
	s_nop 0
	global_load_lds_dwordx4 v1, s[4:5]
	s_add_i32 m0, s18, 0xe000
	s_nop 0
	global_load_lds_dwordx4 v164, s[4:5]
	s_waitcnt vmcnt(8)
	s_waitcnt lgkmcnt(0)
	s_cmp_lg_u32 s98, 0
	s_cbranch_scc1 .Lhb_8
	s_barrier
.Lhb_8:
	s_setprio 1
	s_waitcnt lgkmcnt(0)
	v_mfma_f32_16x16x32_bf16 v[142:145], v[26:29], v[178:181], v[142:145]
	v_mfma_f32_16x16x32_bf16 v[142:145], v[30:33], v[182:185], v[142:145]
	v_mfma_f32_16x16x32_bf16 v[134:137], v[26:29], v[186:189], v[134:137]
	v_mfma_f32_16x16x32_bf16 v[134:137], v[30:33], v[190:193], v[134:137]
	v_mfma_f32_16x16x32_bf16 v[126:129], v[26:29], v[194:197], v[126:129]
	v_mfma_f32_16x16x32_bf16 v[126:129], v[30:33], v[198:201], v[126:129]
	v_mfma_f32_16x16x32_bf16 v[118:121], v[26:29], v[202:205], v[118:121]
	v_mfma_f32_16x16x32_bf16 v[118:121], v[30:33], v[212:215], v[118:121]
	v_mfma_f32_16x16x32_bf16 v[138:141], v[98:101], v[178:181], v[138:141]
	v_mfma_f32_16x16x32_bf16 v[138:141], v[102:105], v[182:185], v[138:141]
	v_mfma_f32_16x16x32_bf16 v[130:133], v[98:101], v[186:189], v[130:133]
	v_mfma_f32_16x16x32_bf16 v[130:133], v[102:105], v[190:193], v[130:133]
	v_mfma_f32_16x16x32_bf16 v[122:125], v[98:101], v[194:197], v[122:125]
	v_mfma_f32_16x16x32_bf16 v[122:125], v[102:105], v[198:201], v[122:125]
	v_mfma_f32_16x16x32_bf16 v[114:117], v[98:101], v[202:205], v[114:117]
	v_mfma_f32_16x16x32_bf16 v[114:117], v[102:105], v[212:215], v[114:117]
	s_setprio 0
	s_setprio 1
	v_mfma_f32_16x16x32_bf16 v[70:73], v[146:149], v[178:181], v[70:73]
	v_mfma_f32_16x16x32_bf16 v[70:73], v[150:153], v[182:185], v[70:73]
	v_mfma_f32_16x16x32_bf16 v[62:65], v[146:149], v[186:189], v[62:65]
	v_mfma_f32_16x16x32_bf16 v[62:65], v[150:153], v[190:193], v[62:65]
	v_mfma_f32_16x16x32_bf16 v[54:57], v[146:149], v[194:197], v[54:57]
	v_mfma_f32_16x16x32_bf16 v[54:57], v[150:153], v[198:201], v[54:57]
	v_mfma_f32_16x16x32_bf16 v[46:49], v[146:149], v[202:205], v[46:49]
	v_mfma_f32_16x16x32_bf16 v[46:49], v[150:153], v[212:215], v[46:49]
	v_mfma_f32_16x16x32_bf16 v[66:69], v[154:157], v[178:181], v[66:69]
	v_mfma_f32_16x16x32_bf16 v[66:69], v[158:161], v[182:185], v[66:69]
	v_mfma_f32_16x16x32_bf16 v[58:61], v[154:157], v[186:189], v[58:61]
	v_mfma_f32_16x16x32_bf16 v[58:61], v[158:161], v[190:193], v[58:61]
	v_mfma_f32_16x16x32_bf16 v[50:53], v[154:157], v[194:197], v[50:53]
	v_mfma_f32_16x16x32_bf16 v[50:53], v[158:161], v[198:201], v[50:53]
	v_mfma_f32_16x16x32_bf16 v[42:45], v[154:157], v[202:205], v[42:45]
	v_mfma_f32_16x16x32_bf16 v[42:45], v[158:161], v[212:215], v[42:45]
	s_setprio 0
	s_cmp_eq_u32 s98, 0
	s_cbranch_scc1 .Lhb_9
	s_barrier
.Lhb_9:
	s_mov_b64 s[4:5], s[10:11]
	s_add_i32 s56, s56, s17
	ds_read_b128 v[178:181], v210 offset:16384
	ds_read_b128 v[182:185], v210 offset:17408
	ds_read_b128 v[186:189], v210 offset:18432
	ds_read_b128 v[190:193], v210 offset:19456
	ds_read_b128 v[194:197], v210 offset:20480
	ds_read_b128 v[198:201], v210 offset:21504
	ds_read_b128 v[202:205], v210 offset:22528
	ds_read_b128 v[212:215], v210 offset:23552
	s_mov_b32 m0, s56
	s_nop 0
	global_load_lds_dwordx4 v162, s[4:5]
	s_add_i32 m0, s56, 0x2000
	s_nop 0
	global_load_lds_dwordx4 v206, s[4:5]
	s_add_u32 s4, s10, 0x80000
	s_addc_u32 s5, s11, 0
	s_add_i32 s56, s57, s17
	s_mov_b32 m0, s56
	s_nop 0
	global_load_lds_dwordx4 v162, s[4:5]
	s_add_i32 m0, s56, 0x2000
	s_nop 0
	global_load_lds_dwordx4 v206, s[4:5]
	s_mov_b64 s[4:5], s[12:13]
	s_mov_b32 m0, s18
	s_nop 0
	global_load_lds_dwordx4 v1, s[4:5]
	s_mov_b32 m0, s19
	s_nop 0
	global_load_lds_dwordx4 v164, s[4:5]
	s_waitcnt vmcnt(8)
	s_waitcnt lgkmcnt(0)
	s_cmp_lg_u32 s98, 0
	s_cbranch_scc1 .Lhb_10
	s_barrier
; #define PG8_STAGE(bufoff, gbase, voff) do { const char* gb_ = (const char*)(gbase); asm volatile("" : "+s"(gb_)); _Pragma("unroll") for (int _i = 0; _i < 2; ++_i) { unsigned vo_ = (voff)[_i]; asm volatile("" : "+v"(vo_));        \
;         __builtin_amdgcn_global_load_lds((const unsigned*)(gb_ + vo_), (PG8_LAS unsigned*)(lds + (bufoff) + ldsw + _i * 8192), 16, 0, 0); } } while (0)
; #define PG8_LDA(dst, b, h) do { _Pragma("unroll") for (int m = 0; m < 4; ++m) _Pragma("unroll") for (int k = 0; k < 2; ++k) dst[m][k] = *(const PG8_LAS bf16x8*)(lds + PG8_SA(b, h) + aoff + m * 2048 + k * 1024); } while (0)
; #define PG8_LDB(dst, b, h) do { _Pragma("unroll") for (int n = 0; n < 2; ++n) _Pragma("unroll") for (int k = 0; k < 2; ++k) dst[n][k] = *(const PG8_LAS bf16x8*)(lds + PG8_SB(b, h) + boff + n * 2048 + k * 1024); } while (0)
; #define PG8_MMA(ai, bj, At, Bt) do { __builtin_amdgcn_s_setprio(1); _Pragma("unroll") for (int m = 0; m < 4; ++m) _Pragma("unroll") for (int n = 0; n < 2; ++n) _Pragma("unroll") for (int k = 0; k < 2; ++k) \
;         acc[ai][bj][m][n] = __builtin_amdgcn_mfma_f32_16x16x32_bf16(Bt[n][k], At[m][k], acc[ai][bj][m][n], 0, 0, 0); __builtin_amdgcn_s_setprio(0); } while (0)
; #define PG8_WAIT_V(n) asm volatile("s_waitcnt vmcnt(" #n ")" ::: "memory")
; #define PG8_WAIT_L(n) asm volatile("s_waitcnt lgkmcnt(" #n ")" ::: "memory")
; #define PG8_BAR __builtin_amdgcn_s_barrier()
; #define PG8_SCHED __builtin_amdgcn_sched_barrier(0)
; template <class Epi, class Sched, bool ALIGN_EPI = false, bool SP2 = false>
; __device__ __forceinline__ void gemm_phase(PG8_LAS unsigned char* lds, const Gemm g, const Sched& S, const Epi& E) {
;     ...
;             PG8_WAIT_V(8); PG8_WAIT_L(0); PG8_BAR; PG8_MMA(1, 0, At, B0); PG8_MMA(1, 1, At, B1); PG8_BAR; PG8_SCHED;
;             PG8_LDB(B0, 1, 0); PG8_LDB(B1, 1, 1); PG8_SCHED; PG8_LDA(At, 1, 0); PG8_STAGE(PG8_SA(0, 1), a2 + hstep, voffA);
;             PG8_WAIT_V(8); PG8_WAIT_L(0); PG8_BAR; PG8_MMA(0, 0, At, B0); PG8_MMA(0, 1, At, B1); PG8_BAR; PG8_SCHED;
.Lhb_10:
	s_setprio 1
	s_waitcnt lgkmcnt(0)
	v_mfma_f32_16x16x32_bf16 v[110:113], v[26:29], v[178:181], v[110:113]
	v_mfma_f32_16x16x32_bf16 v[110:113], v[30:33], v[182:185], v[110:113]
	v_mfma_f32_16x16x32_bf16 v[94:97], v[26:29], v[186:189], v[94:97]
	v_mfma_f32_16x16x32_bf16 v[94:97], v[30:33], v[190:193], v[94:97]
	v_mfma_f32_16x16x32_bf16 v[86:89], v[26:29], v[194:197], v[86:89]
	v_mfma_f32_16x16x32_bf16 v[86:89], v[30:33], v[198:201], v[86:89]
	v_mfma_f32_16x16x32_bf16 v[26:29], v[26:29], v[202:205], v[78:81]
	v_mfma_f32_16x16x32_bf16 v[26:29], v[30:33], v[212:215], v[26:29]
	v_mfma_f32_16x16x32_bf16 v[106:109], v[98:101], v[178:181], v[106:109]
	v_mfma_f32_16x16x32_bf16 v[106:109], v[102:105], v[182:185], v[106:109]
	v_mfma_f32_16x16x32_bf16 v[90:93], v[98:101], v[186:189], v[90:93]
	v_mfma_f32_16x16x32_bf16 v[90:93], v[102:105], v[190:193], v[90:93]
	v_mfma_f32_16x16x32_bf16 v[82:85], v[98:101], v[194:197], v[82:85]
	v_mfma_f32_16x16x32_bf16 v[82:85], v[102:105], v[198:201], v[82:85]
	v_mfma_f32_16x16x32_bf16 v[30:33], v[98:101], v[202:205], v[74:77]
	v_mfma_f32_16x16x32_bf16 v[30:33], v[102:105], v[212:215], v[30:33]
	s_setprio 0
	s_setprio 1
	v_mfma_f32_16x16x32_bf16 v[38:41], v[146:149], v[178:181], v[38:41]
	v_mfma_f32_16x16x32_bf16 v[38:41], v[150:153], v[182:185], v[38:41]
	v_mfma_f32_16x16x32_bf16 v[22:25], v[146:149], v[186:189], v[22:25]
	v_mfma_f32_16x16x32_bf16 v[22:25], v[150:153], v[190:193], v[22:25]
	v_mfma_f32_16x16x32_bf16 v[14:17], v[146:149], v[194:197], v[14:17]
	v_mfma_f32_16x16x32_bf16 v[14:17], v[150:153], v[198:201], v[14:17]
	v_mfma_f32_16x16x32_bf16 v[6:9], v[146:149], v[202:205], v[6:9]
	v_mfma_f32_16x16x32_bf16 v[6:9], v[150:153], v[212:215], v[6:9]
	v_mfma_f32_16x16x32_bf16 v[34:37], v[154:157], v[178:181], v[34:37]
	v_mfma_f32_16x16x32_bf16 v[34:37], v[158:161], v[182:185], v[34:37]
	v_mfma_f32_16x16x32_bf16 v[18:21], v[154:157], v[186:189], v[18:21]
	v_mfma_f32_16x16x32_bf16 v[18:21], v[158:161], v[190:193], v[18:21]
	v_mfma_f32_16x16x32_bf16 v[10:13], v[154:157], v[194:197], v[10:13]
	v_mfma_f32_16x16x32_bf16 v[10:13], v[158:161], v[198:201], v[10:13]
	v_mfma_f32_16x16x32_bf16 v[2:5], v[154:157], v[202:205], v[2:5]
	v_mfma_f32_16x16x32_bf16 v[2:5], v[158:161], v[212:215], v[2:5]
	s_setprio 0
	s_cmp_eq_u32 s98, 0
	s_cbranch_scc1 .Lhb_11
	s_barrier
.Lhb_11:
	s_add_i32 s56, 0, 0x18000
	s_add_i32 s57, 0, 0x1c000
	ds_read_b128 v[74:77], v244 offset:32768
	ds_read_b128 v[78:81], v244 offset:33792
	ds_read_b128 v[98:101], v244 offset:34816
	ds_read_b128 v[102:105], v244 offset:35840
	ds_read_b128 v[146:149], v244 offset:49152
	ds_read_b128 v[150:153], v244 offset:50176
	ds_read_b128 v[154:157], v244 offset:51200
	ds_read_b128 v[158:161], v244 offset:52224
	s_add_u32 s4, s12, 0x80000
	s_addc_u32 s5, s13, 0
	s_mov_b32 m0, s20
	ds_read_b128 v[178:181], v210 offset:32768
	ds_read_b128 v[182:185], v210 offset:33792
	ds_read_b128 v[186:189], v210 offset:34816
	ds_read_b128 v[190:193], v210 offset:35840
	ds_read_b128 v[194:197], v210 offset:36864
	ds_read_b128 v[198:201], v210 offset:37888
	ds_read_b128 v[202:205], v210 offset:38912
	ds_read_b128 v[212:215], v210 offset:39936
	s_nop 0
	global_load_lds_dwordx4 v1, s[4:5]
	s_mov_b32 m0, s21
	s_nop 0
	global_load_lds_dwordx4 v164, s[4:5]
	s_waitcnt vmcnt(8)
	s_waitcnt lgkmcnt(0)
	s_cmp_lg_u32 s98, 0
	s_cbranch_scc1 .Lhb_12
	s_barrier
.Lhb_12:
	s_setprio 1
	s_waitcnt lgkmcnt(0)
	v_mfma_f32_16x16x32_bf16 v[142:145], v[74:77], v[178:181], v[142:145]
	v_mfma_f32_16x16x32_bf16 v[142:145], v[78:81], v[182:185], v[142:145]
	v_mfma_f32_16x16x32_bf16 v[134:137], v[74:77], v[186:189], v[134:137]
	v_mfma_f32_16x16x32_bf16 v[134:137], v[78:81], v[190:193], v[134:137]
	v_mfma_f32_16x16x32_bf16 v[126:129], v[74:77], v[194:197], v[126:129]
	v_mfma_f32_16x16x32_bf16 v[126:129], v[78:81], v[198:201], v[126:129]
	v_mfma_f32_16x16x32_bf16 v[118:121], v[74:77], v[202:205], v[118:121]
	v_mfma_f32_16x16x32_bf16 v[118:121], v[78:81], v[212:215], v[118:121]
	v_mfma_f32_16x16x32_bf16 v[138:141], v[98:101], v[178:181], v[138:141]
	v_mfma_f32_16x16x32_bf16 v[138:141], v[102:105], v[182:185], v[138:141]
	v_mfma_f32_16x16x32_bf16 v[130:133], v[98:101], v[186:189], v[130:133]
	v_mfma_f32_16x16x32_bf16 v[130:133], v[102:105], v[190:193], v[130:133]
	v_mfma_f32_16x16x32_bf16 v[122:125], v[98:101], v[194:197], v[122:125]
	v_mfma_f32_16x16x32_bf16 v[122:125], v[102:105], v[198:201], v[122:125]
	v_mfma_f32_16x16x32_bf16 v[114:117], v[98:101], v[202:205], v[114:117]
	v_mfma_f32_16x16x32_bf16 v[114:117], v[102:105], v[212:215], v[114:117]
	s_setprio 0
	s_setprio 1
	v_mfma_f32_16x16x32_bf16 v[70:73], v[146:149], v[178:181], v[70:73]
	v_mfma_f32_16x16x32_bf16 v[70:73], v[150:153], v[182:185], v[70:73]
	v_mfma_f32_16x16x32_bf16 v[62:65], v[146:149], v[186:189], v[62:65]
	v_mfma_f32_16x16x32_bf16 v[62:65], v[150:153], v[190:193], v[62:65]
	v_mfma_f32_16x16x32_bf16 v[54:57], v[146:149], v[194:197], v[54:57]
	v_mfma_f32_16x16x32_bf16 v[54:57], v[150:153], v[198:201], v[54:57]
	v_mfma_f32_16x16x32_bf16 v[46:49], v[146:149], v[202:205], v[46:49]
	v_mfma_f32_16x16x32_bf16 v[46:49], v[150:153], v[212:215], v[46:49]
	v_mfma_f32_16x16x32_bf16 v[66:69], v[154:157], v[178:181], v[66:69]
	v_mfma_f32_16x16x32_bf16 v[66:69], v[158:161], v[182:185], v[66:69]
	v_mfma_f32_16x16x32_bf16 v[58:61], v[154:157], v[186:189], v[58:61]
	v_mfma_f32_16x16x32_bf16 v[58:61], v[158:161], v[190:193], v[58:61]
	v_mfma_f32_16x16x32_bf16 v[50:53], v[154:157], v[194:197], v[50:53]
	v_mfma_f32_16x16x32_bf16 v[50:53], v[158:161], v[198:201], v[50:53]
	v_mfma_f32_16x16x32_bf16 v[42:45], v[154:157], v[202:205], v[42:45]
	v_mfma_f32_16x16x32_bf16 v[42:45], v[158:161], v[212:215], v[42:45]
	s_setprio 0
	s_cmp_eq_u32 s98, 0
	s_cbranch_scc1 .Lhb_13
	s_barrier
;     __device__ __forceinline__ void operator()(const f32x4 (&acc)[2][2][4][2], const Unit& u, int wr, int wc, int fr, int fq) const {
;         const int row0 = u.pm * BM + wr * 64 + fr, col0 = u.pn * BM + wc * 32 + 8 * fq, b = (u.pm * BM) / rows_per_batch;
;         const float* g = gate + (size_t)b * gate_bstride + col0;
;         float ssq[2][4];
; #pragma unroll
;         for (int ai = 0; ai < 2; ++ai)
; #pragma unroll
;             for (int m = 0; m < 4; ++m) ssq[ai][m] = 0.f;
;         f32x4 gv[2][2], Gv[2][2];
; #pragma unroll
;         for (int bj = 0; bj < 2; ++bj) { gv[bj][0] = *(const f32x4*)(g + bj * HALF); gv[bj][1] = *(const f32x4*)(g + bj * HALF + 4); Gv[bj][0] = (f32x4){0.f, 0.f, 0.f, 0.f}; Gv[bj][1] = (f32x4){0.f, 0.f, 0.f, 0.f};
;             if (Hn) { const float* sc = scnext + (size_t)b * gate_bstride + col0 + bj * HALF;
;                 Gv[bj][0] = *(const f32x4*)(gnext + col0 + bj * HALF) * (1.0f + *(const f32x4*)(sc)); Gv[bj][1] = *(const f32x4*)(gnext + col0 + bj * HALF + 4) * (1.0f + *(const f32x4*)(sc + 4)); } }
; #pragma unroll
;         for (int bj = 0; bj < 2; ++bj) {
;             const f32x4 g0 = gv[bj][0], g1 = gv[bj][1], G0 = Gv[bj][0], G1 = Gv[bj][1];
; #pragma unroll
;             for (int ai = 0; ai < 2; ++ai)
; #pragma unroll
;                 for (int m = 0; m < 4; ++m) { const size_t off = (size_t)(row0 + ai * HALF + m * 16) * 2048 + col0 + bj * HALF;
;                     f32x4 x0 = __builtin_nontemporal_load((const f32x4*)(base + off)), x1 = __builtin_nontemporal_load((const f32x4*)(base + off + 4));
;                     if constexpr (HAS_DIN) { const u32x4 dw = __builtin_nontemporal_load((const u32x4*)(dbuf + off));
;                         x0 += (f32x4){__builtin_bit_cast(float, dw.x << 16), __builtin_bit_cast(float, dw.x & 0xffff0000u), __builtin_bit_cast(float, dw.y << 16), __builtin_bit_cast(float, dw.y & 0xffff0000u)};
; template <class Epi, class Sched, bool ALIGN_EPI = false, bool SP2 = false>
; __device__ __forceinline__ void gemm_phase(PG8_LAS unsigned char* lds, const Gemm g, const Sched& S, const Epi& E) {
;     ...
;             PG8_LDA(At, 1, 1); PG8_STAGE(PG8_SB(1, 0), b3, voffB); PG8_STAGE(PG8_SB(1, 1), b3 + hstep, voffB); PG8_STAGE(PG8_SA(1, 0), a3, voffA);
;             PG8_WAIT_V(8); PG8_WAIT_L(0); PG8_BAR; PG8_MMA(1, 0, At, B0); PG8_MMA(1, 1, At, B1); PG8_BAR; PG8_SCHED;
.Lhb_13:
	s_add_u32 s4, s10, 0x80
	s_addc_u32 s5, s11, 0
	s_add_i32 s12, s56, s17
	ds_read_b128 v[178:181], v210 offset:49152
	ds_read_b128 v[182:185], v210 offset:50176
	ds_read_b128 v[186:189], v210 offset:51200
	ds_read_b128 v[190:193], v210 offset:52224
	ds_read_b128 v[194:197], v210 offset:53248
	ds_read_b128 v[198:201], v210 offset:54272
	ds_read_b128 v[202:205], v210 offset:55296
	ds_read_b128 v[212:215], v210 offset:56320
	s_mov_b32 m0, s12
	s_nop 0
	global_load_lds_dwordx4 v162, s[4:5]
	s_add_i32 m0, s12, 0x2000
	s_nop 0
	global_load_lds_dwordx4 v206, s[4:5]
	s_add_u32 s4, s10, 0x80080
	s_addc_u32 s5, s11, 0
	s_add_i32 s10, s57, s17
	s_mov_b32 m0, s10
	s_nop 0
	global_load_lds_dwordx4 v162, s[4:5]
	s_add_i32 m0, s10, 0x2000
	s_nop 0
	global_load_lds_dwordx4 v206, s[4:5]
	s_mov_b32 m0, s26
	s_nop 0
	global_load_lds_dwordx4 v1, s[8:9]
	s_mov_b32 m0, s27
	s_nop 0
	global_load_lds_dwordx4 v164, s[8:9]
	s_waitcnt vmcnt(8)
	s_waitcnt lgkmcnt(0)
	s_cmp_lg_u32 s98, 0
	s_cbranch_scc1 .Lhb_14
	s_barrier
.Lhb_14:
	s_setprio 1
	s_waitcnt lgkmcnt(0)
	v_mfma_f32_16x16x32_bf16 v[110:113], v[74:77], v[178:181], v[110:113]
	v_mfma_f32_16x16x32_bf16 v[110:113], v[78:81], v[182:185], v[110:113]
	v_mfma_f32_16x16x32_bf16 v[94:97], v[74:77], v[186:189], v[94:97]
	v_mfma_f32_16x16x32_bf16 v[94:97], v[78:81], v[190:193], v[94:97]
	v_mfma_f32_16x16x32_bf16 v[86:89], v[74:77], v[194:197], v[86:89]
	v_mfma_f32_16x16x32_bf16 v[86:89], v[78:81], v[198:201], v[86:89]
	v_mfma_f32_16x16x32_bf16 v[26:29], v[74:77], v[202:205], v[26:29]
	v_mfma_f32_16x16x32_bf16 v[78:81], v[78:81], v[212:215], v[26:29]
	v_mfma_f32_16x16x32_bf16 v[106:109], v[98:101], v[178:181], v[106:109]
	v_mfma_f32_16x16x32_bf16 v[106:109], v[102:105], v[182:185], v[106:109]
	v_mfma_f32_16x16x32_bf16 v[90:93], v[98:101], v[186:189], v[90:93]
	v_mfma_f32_16x16x32_bf16 v[90:93], v[102:105], v[190:193], v[90:93]
	v_mfma_f32_16x16x32_bf16 v[82:85], v[98:101], v[194:197], v[82:85]
	v_mfma_f32_16x16x32_bf16 v[82:85], v[102:105], v[198:201], v[82:85]
	v_mfma_f32_16x16x32_bf16 v[26:29], v[98:101], v[202:205], v[30:33]
	v_mfma_f32_16x16x32_bf16 v[74:77], v[102:105], v[212:215], v[26:29]
	s_setprio 0
	s_setprio 1
	v_mfma_f32_16x16x32_bf16 v[26:29], v[146:149], v[178:181], v[38:41]
	v_mfma_f32_16x16x32_bf16 v[38:41], v[150:153], v[182:185], v[26:29]
	v_mfma_f32_16x16x32_bf16 v[22:25], v[146:149], v[186:189], v[22:25]
	v_mfma_f32_16x16x32_bf16 v[22:25], v[150:153], v[190:193], v[22:25]
	v_mfma_f32_16x16x32_bf16 v[14:17], v[146:149], v[194:197], v[14:17]
	v_mfma_f32_16x16x32_bf16 v[14:17], v[150:153], v[198:201], v[14:17]
	v_mfma_f32_16x16x32_bf16 v[6:9], v[146:149], v[202:205], v[6:9]
	v_mfma_f32_16x16x32_bf16 v[6:9], v[150:153], v[212:215], v[6:9]
	v_mfma_f32_16x16x32_bf16 v[26:29], v[154:157], v[178:181], v[34:37]
	v_mfma_f32_16x16x32_bf16 v[34:37], v[158:161], v[182:185], v[26:29]
	v_mfma_f32_16x16x32_bf16 v[18:21], v[154:157], v[186:189], v[18:21]
	v_mfma_f32_16x16x32_bf16 v[18:21], v[158:161], v[190:193], v[18:21]
	v_mfma_f32_16x16x32_bf16 v[10:13], v[154:157], v[194:197], v[10:13]
	v_mfma_f32_16x16x32_bf16 v[10:13], v[158:161], v[198:201], v[10:13]
	v_mfma_f32_16x16x32_bf16 v[2:5], v[154:157], v[202:205], v[2:5]
	v_mfma_f32_16x16x32_bf16 v[2:5], v[158:161], v[212:215], v[2:5]
	s_setprio 0
	s_cmp_eq_u32 s98, 0
	s_cbranch_scc1 .Lhb_15
	s_barrier
.Lhb_15:
	s_add_i32 s51, s51, 2
	s_add_u32 s40, s40, 0x100
	s_addc_u32 s49, s49, 0
	s_cmp_gt_u32 s51, 29
	s_mov_b64 s[4:5], s[6:7]
	s_cbranch_scc0 .LBB0_555
	s_ashr_i32 s4, s29, 31
	s_lshr_b32 s4, s4, 27
	s_add_i32 s4, s29, s4
	s_ashr_i32 s4, s4, 5
	v_lshl_or_b32 v148, s33, 8, v209
	s_mul_i32 s7, s4, 0xc000
	v_ashrrev_i32_e32 v149, 31, v148
	s_mul_hi_i32 s6, s4, 0xc000
	s_add_u32 s4, s22, s7
	s_addc_u32 s5, s23, s6
	v_lshlrev_b64 v[26:27], 2, v[148:149]
	v_lshl_add_u64 v[146:147], s[4:5], 0, v[26:27]
	s_add_u32 s4, s24, s7
	s_addc_u32 s5, s25, s6
	v_lshl_add_u64 v[160:161], s[4:5], 0, v[26:27]
	v_lshl_add_u64 v[178:179], s[46:47], 0, v[26:27]
	global_load_dwordx4 v[98:101], v[146:147], off offset:16
	global_load_dwordx4 v[102:105], v[146:147], off
	global_load_dwordx4 v[26:29], v[178:179], off offset:16
	global_load_dwordx4 v[30:33], v[178:179], off
	global_load_dwordx4 v[150:153], v[160:161], off offset:16
	global_load_dwordx4 v[154:157], v[160:161], off
	s_mov_b64 s[4:5], 0x40000
	s_waitcnt vmcnt(0)
	v_pk_mul_f32 v[188:189], v[140:141], v[100:101]
	v_pk_mul_f32 v[142:143], v[142:143], v[102:103]
	v_pk_mul_f32 v[144:145], v[144:145], v[104:105]
	v_pk_mul_f32 v[140:141], v[138:139], v[98:99]
	v_pk_mul_f32 v[136:137], v[136:137], v[104:105]
	v_pk_add_f32 v[156:157], v[156:157], 1.0 op_sel_hi:[1,0]
	v_pk_add_f32 v[154:155], v[154:155], 1.0 op_sel_hi:[1,0]
	v_pk_mul_f32 v[198:199], v[32:33], v[156:157]
	v_pk_mul_f32 v[200:201], v[30:31], v[154:155]
	v_pk_add_f32 v[30:31], v[152:153], 1.0 op_sel_hi:[1,0]
	v_pk_add_f32 v[32:33], v[150:151], 1.0 op_sel_hi:[1,0]
	v_pk_mul_f32 v[202:203], v[28:29], v[30:31]
	v_pk_mul_f32 v[204:205], v[26:27], v[32:33]
	global_load_dwordx4 v[26:29], v[146:147], off offset:528
	global_load_dwordx4 v[30:33], v[146:147], off offset:512
	global_load_dwordx4 v[156:159], v[178:179], off offset:528
	global_load_dwordx4 v[152:155], v[178:179], off offset:512
	s_nop 0
	global_load_dwordx4 v[178:181], v[160:161], off offset:528
	global_load_dwordx4 v[182:185], v[160:161], off offset:512
	v_pk_mul_f32 v[134:135], v[134:135], v[102:103]
	v_pk_mul_f32 v[130:131], v[130:131], v[98:99]
	v_pk_mul_f32 v[132:133], v[132:133], v[100:101]
	v_pk_mul_f32 v[128:129], v[128:129], v[104:105]
	v_pk_mul_f32 v[126:127], v[126:127], v[102:103]
	v_pk_mul_f32 v[122:123], v[122:123], v[98:99]
	v_pk_mul_f32 v[124:125], v[124:125], v[100:101]
	v_pk_mul_f32 v[120:121], v[120:121], v[104:105]
	v_pk_mul_f32 v[118:119], v[118:119], v[102:103]
	v_pk_mul_f32 v[114:115], v[114:115], v[98:99]
	v_pk_mul_f32 v[116:117], v[116:117], v[100:101]
	v_pk_mul_f32 v[112:113], v[112:113], v[104:105]
	v_pk_mul_f32 v[110:111], v[110:111], v[102:103]
	v_pk_mul_f32 v[106:107], v[106:107], v[98:99]
	v_pk_mul_f32 v[108:109], v[108:109], v[100:101]
	v_pk_mul_f32 v[96:97], v[96:97], v[104:105]
	v_pk_mul_f32 v[94:95], v[94:95], v[102:103]
	v_pk_mul_f32 v[90:91], v[90:91], v[98:99]
	v_pk_mul_f32 v[92:93], v[92:93], v[100:101]
	v_pk_mul_f32 v[88:89], v[88:89], v[104:105]
	v_pk_mul_f32 v[86:87], v[86:87], v[102:103]
	v_pk_mul_f32 v[82:83], v[82:83], v[98:99]
	v_pk_mul_f32 v[84:85], v[84:85], v[100:101]
	v_pk_mul_f32 v[80:81], v[80:81], v[104:105]
	v_pk_mul_f32 v[78:79], v[78:79], v[102:103]
	v_pk_mul_f32 v[74:75], v[74:75], v[98:99]
	v_pk_mul_f32 v[76:77], v[76:77], v[100:101]
	s_waitcnt vmcnt(5)
; __device__ __forceinline__ unsigned cvt_pk_bf16(float lo, float hi) { unsigned r; asm volatile("v_cvt_pk_bf16_f32 %0, %1, %2" : "=v"(r) : "v"(lo), "v"(hi)); return r; }
;     __device__ __forceinline__ void operator()(const f32x4 (&acc)[2][2][4][2], const Unit& u, int wr, int wc, int fr, int fq) const {
;     ...
;                 for (int m = 0; m < 4; ++m) { const size_t off = (size_t)(row0 + ai * HALF + m * 16) * 2048 + col0 + bj * HALF;
;                     f32x4 x0 = __builtin_nontemporal_load((const f32x4*)(base + off)), x1 = __builtin_nontemporal_load((const f32x4*)(base + off + 4));
;                     if constexpr (HAS_DIN) { const u32x4 dw = __builtin_nontemporal_load((const u32x4*)(dbuf + off));
;                         x0 += (f32x4){__builtin_bit_cast(float, dw.x << 16), __builtin_bit_cast(float, dw.x & 0xffff0000u), __builtin_bit_cast(float, dw.y << 16), __builtin_bit_cast(float, dw.y & 0xffff0000u)};
;                         x1 += (f32x4){__builtin_bit_cast(float, dw.z << 16), __builtin_bit_cast(float, dw.z & 0xffff0000u), __builtin_bit_cast(float, dw.w << 16), __builtin_bit_cast(float, dw.w & 0xffff0000u)}; }
;                     f32x4 o0, o1;
;                     if constexpr (OUT_DELTA) { const f32x4 d0 = g0 * acc[ai][bj][m][0], d1 = g1 * acc[ai][bj][m][1];
;                         u32x4 w; w.x = cvt_pk_bf16(d0[0], d0[1]); w.y = cvt_pk_bf16(d0[2], d0[3]); w.z = cvt_pk_bf16(d1[0], d1[1]); w.w = cvt_pk_bf16(d1[2], d1[3]);
;                         *(u32x4*)(dbuf + off) = w;
;                         o0 = x0 + (f32x4){__builtin_bit_cast(float, w.x << 16), __builtin_bit_cast(float, w.x & 0xffff0000u), __builtin_bit_cast(float, w.y << 16), __builtin_bit_cast(float, w.y & 0xffff0000u)};
;                         o1 = x1 + (f32x4){__builtin_bit_cast(float, w.z << 16), __builtin_bit_cast(float, w.z & 0xffff0000u), __builtin_bit_cast(float, w.w << 16), __builtin_bit_cast(float, w.w & 0xffff0000u)}; }
;                     else { o0 = x0 + g0 * acc[ai][bj][m][0]; o1 = x1 + g1 * acc[ai][bj][m][1]; *(f32x4*)(out + off) = o0; *(f32x4*)(out + off + 4) = o1; }
;                     if (Hn) { const f32x4 h0 = o0 * G0, h1 = o1 * G1;
;                         u32x4 w; w.x = cvt_pk_bf16(h0[0], h0[1]); w.y = cvt_pk_bf16(h0[2], h0[3]); w.z = cvt_pk_bf16(h1[0], h1[1]); w.w = cvt_pk_bf16(h1[2], h1[3]);
;                         *(u32x4*)(Hn + off) = w;
	v_pk_mul_f32 v[58:59], v[58:59], v[26:27]
	s_waitcnt vmcnt(4)
	v_pk_mul_f32 v[72:73], v[72:73], v[32:33]
	v_pk_mul_f32 v[70:71], v[70:71], v[30:31]
	v_pk_mul_f32 v[64:65], v[64:65], v[32:33]
	v_pk_mul_f32 v[62:63], v[62:63], v[30:31]
	s_waitcnt vmcnt(0)
	v_pk_add_f32 v[146:147], v[184:185], 1.0 op_sel_hi:[1,0]
	v_pk_add_f32 v[160:161], v[182:183], 1.0 op_sel_hi:[1,0]
	v_pk_mul_f32 v[150:151], v[154:155], v[146:147]
	v_pk_add_f32 v[146:147], v[180:181], 1.0 op_sel_hi:[1,0]
	v_pk_mul_f32 v[152:153], v[152:153], v[160:161]
	v_pk_mul_f32 v[154:155], v[158:159], v[146:147]
	v_lshl_add_u32 v146, s29, 8, v207
	v_ashrrev_i32_e32 v147, 31, v146
	v_lshlrev_b64 v[184:185], 11, v[146:147]
	v_lshl_add_u64 v[186:187], v[184:185], 0, v[148:149]
	v_pk_add_f32 v[160:161], v[178:179], 1.0 op_sel_hi:[1,0]
	v_lshl_add_u64 v[178:179], v[186:187], 2, s[44:45]
	v_pk_mul_f32 v[156:157], v[156:157], v[160:161]
	global_load_dwordx4 v[158:161], v[178:179], off nt
	global_load_dwordx4 v[180:183], v[178:179], off offset:16 nt
	v_cvt_pk_bf16_f32 v138, v142, v143
	v_lshlrev_b64 v[142:143], 1, v[186:187]
	v_cvt_pk_bf16_f32 v139, v144, v145
	v_cvt_pk_bf16_f32 v140, v140, v141
	v_cvt_pk_bf16_f32 v141, v188, v189
	v_lshl_add_u64 v[144:145], s[90:91], 0, v[142:143]
	global_store_dwordx4 v[144:145], v[138:141], off
	v_lshlrev_b32_e32 v144, 16, v140
	v_and_b32_e32 v145, 0xffff0000, v140
	v_lshlrev_b32_e32 v140, 16, v141
	v_and_b32_e32 v141, 0xffff0000, v141
	v_lshl_add_u64 v[142:143], s[96:97], 0, v[142:143]
	v_pk_mul_f32 v[60:61], v[60:61], v[28:29]
	v_pk_mul_f32 v[56:57], v[56:57], v[32:33]
	v_pk_mul_f32 v[54:55], v[54:55], v[30:31]
	v_pk_mul_f32 v[50:51], v[50:51], v[26:27]
	v_pk_mul_f32 v[52:53], v[52:53], v[28:29]
	v_pk_mul_f32 v[48:49], v[48:49], v[32:33]
	v_pk_mul_f32 v[46:47], v[46:47], v[30:31]
	v_pk_mul_f32 v[42:43], v[42:43], v[26:27]
	v_pk_mul_f32 v[44:45], v[44:45], v[28:29]
	v_pk_mul_f32 v[40:41], v[40:41], v[32:33]
	v_pk_mul_f32 v[38:39], v[38:39], v[30:31]
	v_pk_mul_f32 v[34:35], v[34:35], v[26:27]
	v_pk_mul_f32 v[36:37], v[36:37], v[28:29]
	v_pk_mul_f32 v[24:25], v[24:25], v[32:33]
	v_pk_mul_f32 v[22:23], v[22:23], v[30:31]
	v_pk_mul_f32 v[18:19], v[18:19], v[26:27]
	v_pk_mul_f32 v[20:21], v[20:21], v[28:29]
	v_pk_mul_f32 v[16:17], v[16:17], v[32:33]
	v_pk_mul_f32 v[14:15], v[14:15], v[30:31]
	v_pk_mul_f32 v[10:11], v[10:11], v[26:27]
	v_pk_mul_f32 v[12:13], v[12:13], v[28:29]
	v_pk_mul_f32 v[8:9], v[8:9], v[32:33]
	v_pk_mul_f32 v[6:7], v[6:7], v[30:31]
	v_pk_mul_f32 v[2:3], v[2:3], v[26:27]
	v_pk_mul_f32 v[4:5], v[4:5], v[28:29]
	s_waitcnt vmcnt(1)
	v_pk_add_f32 v[182:183], v[182:183], v[140:141]
	v_lshlrev_b32_e32 v140, 16, v138
	v_and_b32_e32 v141, 0xffff0000, v138
	v_lshlrev_b32_e32 v138, 16, v139
	v_and_b32_e32 v139, 0xffff0000, v139
	v_pk_add_f32 v[158:159], v[158:159], v[140:141]
	v_pk_add_f32 v[160:161], v[160:161], v[138:139]
	v_pk_mul_f32 v[138:139], v[200:201], v[158:159]
	v_pk_add_f32 v[144:145], v[180:181], v[144:145]
	v_pk_mul_f32 v[140:141], v[198:199], v[160:161]
	v_cvt_pk_bf16_f32 v138, v138, v139
	v_pk_mul_f32 v[180:181], v[202:203], v[182:183]
	v_cvt_pk_bf16_f32 v139, v140, v141
	v_pk_mul_f32 v[186:187], v[204:205], v[144:145]
	s_nop 0
	v_cvt_pk_bf16_f32 v140, v186, v187
	v_cvt_pk_bf16_f32 v141, v180, v181
	global_store_dwordx4 v[142:143], v[138:141], off
	s_nop 1
	v_mul_f32_e32 v138, v159, v159
	v_mul_f32_e32 v139, v161, v161
	v_fmac_f32_e32 v138, v158, v158
	v_fmac_f32_e32 v139, v160, v160
	v_add_f32_e32 v138, v138, v139
	v_mul_f32_e32 v139, v145, v145
	v_mul_f32_e32 v140, v183, v183
	v_fmac_f32_e32 v139, v144, v144
	v_fmac_f32_e32 v140, v182, v182
	v_add_f32_e32 v139, v139, v140
	v_add_f32_e32 v211, v138, v139
	v_or_b32_e32 v138, 16, v146
	v_ashrrev_i32_e32 v139, 31, v138
	v_lshlrev_b64 v[140:141], 11, v[138:139]
	v_lshl_add_u64 v[180:181], v[140:141], 0, v[148:149]
	v_lshl_add_u64 v[138:139], v[180:181], 2, s[44:45]
	global_load_dwordx4 v[142:145], v[138:139], off nt
	global_load_dwordx4 v[158:161], v[138:139], off offset:16 nt
	v_lshlrev_b64 v[180:181], 1, v[180:181]
	v_cvt_pk_bf16_f32 v134, v134, v135
	v_cvt_pk_bf16_f32 v135, v136, v137
	v_cvt_pk_bf16_f32 v136, v130, v131
	v_cvt_pk_bf16_f32 v137, v132, v133
	v_lshl_add_u64 v[130:131], s[90:91], 0, v[180:181]
	global_store_dwordx4 v[130:131], v[134:137], off
	v_lshlrev_b32_e32 v132, 16, v136
	v_and_b32_e32 v133, 0xffff0000, v136
	v_lshlrev_b32_e32 v130, 16, v137
	v_and_b32_e32 v131, 0xffff0000, v137
	v_lshlrev_b32_e32 v136, 16, v134
	v_and_b32_e32 v137, 0xffff0000, v134
	v_lshlrev_b32_e32 v134, 16, v135
	v_and_b32_e32 v135, 0xffff0000, v135
	s_waitcnt vmcnt(2)
	v_pk_add_f32 v[134:135], v[144:145], v[134:135]
	s_waitcnt vmcnt(1)
	v_pk_add_f32 v[130:131], v[160:161], v[130:131]
	v_pk_add_f32 v[136:137], v[142:143], v[136:137]
	v_pk_add_f32 v[132:133], v[158:159], v[132:133]
	v_pk_mul_f32 v[144:145], v[198:199], v[134:135]
	v_pk_mul_f32 v[142:143], v[200:201], v[136:137]
	v_pk_mul_f32 v[158:159], v[202:203], v[130:131]
	v_pk_mul_f32 v[160:161], v[204:205], v[132:133]
	v_cvt_pk_bf16_f32 v142, v142, v143
	v_cvt_pk_bf16_f32 v143, v144, v145
	s_nop 0
	v_cvt_pk_bf16_f32 v144, v160, v161
	v_cvt_pk_bf16_f32 v145, v158, v159
	v_lshl_add_u64 v[158:159], s[96:97], 0, v[180:181]
	global_store_dwordx4 v[158:159], v[142:145], off
	s_nop 1
	v_or_b32_e32 v142, 32, v146
	v_ashrrev_i32_e32 v143, 31, v142
	v_lshlrev_b64 v[144:145], 11, v[142:143]
	v_lshl_add_u64 v[186:187], v[144:145], 0, v[148:149]
	v_lshl_add_u64 v[142:143], v[186:187], 2, s[44:45]
	global_load_dwordx4 v[158:161], v[142:143], off nt
	global_load_dwordx4 v[180:183], v[142:143], off offset:16 nt
	v_lshlrev_b64 v[186:187], 1, v[186:187]
	v_cvt_pk_bf16_f32 v126, v126, v127
	v_cvt_pk_bf16_f32 v127, v128, v129
	v_cvt_pk_bf16_f32 v128, v122, v123
	v_cvt_pk_bf16_f32 v129, v124, v125
	v_lshl_add_u64 v[122:123], s[90:91], 0, v[186:187]
	global_store_dwordx4 v[122:123], v[126:129], off
	v_lshlrev_b32_e32 v124, 16, v128
	v_and_b32_e32 v125, 0xffff0000, v128
	v_lshlrev_b32_e32 v122, 16, v129
	v_and_b32_e32 v123, 0xffff0000, v129
	v_lshlrev_b32_e32 v128, 16, v126
	v_and_b32_e32 v129, 0xffff0000, v126
	v_lshlrev_b32_e32 v126, 16, v127
	v_and_b32_e32 v127, 0xffff0000, v127
	s_waitcnt vmcnt(2)
; __device__ __forceinline__ unsigned cvt_pk_bf16(float lo, float hi) { unsigned r; asm volatile("v_cvt_pk_bf16_f32 %0, %1, %2" : "=v"(r) : "v"(lo), "v"(hi)); return r; }
;     __device__ __forceinline__ void operator()(const f32x4 (&acc)[2][2][4][2], const Unit& u, int wr, int wc, int fr, int fq) const {
;     ...
;                 for (int m = 0; m < 4; ++m) { const size_t off = (size_t)(row0 + ai * HALF + m * 16) * 2048 + col0 + bj * HALF;
;                     f32x4 x0 = __builtin_nontemporal_load((const f32x4*)(base + off)), x1 = __builtin_nontemporal_load((const f32x4*)(base + off + 4));
;                     if constexpr (HAS_DIN) { const u32x4 dw = __builtin_nontemporal_load((const u32x4*)(dbuf + off));
;                         x0 += (f32x4){__builtin_bit_cast(float, dw.x << 16), __builtin_bit_cast(float, dw.x & 0xffff0000u), __builtin_bit_cast(float, dw.y << 16), __builtin_bit_cast(float, dw.y & 0xffff0000u)};
;                         x1 += (f32x4){__builtin_bit_cast(float, dw.z << 16), __builtin_bit_cast(float, dw.z & 0xffff0000u), __builtin_bit_cast(float, dw.w << 16), __builtin_bit_cast(float, dw.w & 0xffff0000u)}; }
;                     f32x4 o0, o1;
;                     if constexpr (OUT_DELTA) { const f32x4 d0 = g0 * acc[ai][bj][m][0], d1 = g1 * acc[ai][bj][m][1];
;                         u32x4 w; w.x = cvt_pk_bf16(d0[0], d0[1]); w.y = cvt_pk_bf16(d0[2], d0[3]); w.z = cvt_pk_bf16(d1[0], d1[1]); w.w = cvt_pk_bf16(d1[2], d1[3]);
;                         *(u32x4*)(dbuf + off) = w;
;                         o0 = x0 + (f32x4){__builtin_bit_cast(float, w.x << 16), __builtin_bit_cast(float, w.x & 0xffff0000u), __builtin_bit_cast(float, w.y << 16), __builtin_bit_cast(float, w.y & 0xffff0000u)};
;                         o1 = x1 + (f32x4){__builtin_bit_cast(float, w.z << 16), __builtin_bit_cast(float, w.z & 0xffff0000u), __builtin_bit_cast(float, w.w << 16), __builtin_bit_cast(float, w.w & 0xffff0000u)}; }
;                     else { o0 = x0 + g0 * acc[ai][bj][m][0]; o1 = x1 + g1 * acc[ai][bj][m][1]; *(f32x4*)(out + off) = o0; *(f32x4*)(out + off + 4) = o1; }
;                     if (Hn) { const f32x4 h0 = o0 * G0, h1 = o1 * G1;
;                         u32x4 w; w.x = cvt_pk_bf16(h0[0], h0[1]); w.y = cvt_pk_bf16(h0[2], h0[3]); w.z = cvt_pk_bf16(h1[0], h1[1]); w.w = cvt_pk_bf16(h1[2], h1[3]);
;                         *(u32x4*)(Hn + off) = w;
	v_pk_add_f32 v[126:127], v[160:161], v[126:127]
	s_waitcnt vmcnt(1)
	v_pk_add_f32 v[122:123], v[182:183], v[122:123]
	v_pk_add_f32 v[128:129], v[158:159], v[128:129]
	v_pk_add_f32 v[124:125], v[180:181], v[124:125]
	v_pk_mul_f32 v[160:161], v[198:199], v[126:127]
	v_pk_mul_f32 v[158:159], v[200:201], v[128:129]
	v_pk_mul_f32 v[180:181], v[202:203], v[122:123]
	v_pk_mul_f32 v[182:183], v[204:205], v[124:125]
	v_cvt_pk_bf16_f32 v158, v158, v159
	v_cvt_pk_bf16_f32 v159, v160, v161
	s_nop 0
	v_cvt_pk_bf16_f32 v160, v182, v183
	v_cvt_pk_bf16_f32 v161, v180, v181
	v_lshl_add_u64 v[180:181], s[96:97], 0, v[186:187]
	global_store_dwordx4 v[180:181], v[158:161], off
	s_nop 1
	v_or_b32_e32 v158, 48, v146
	v_ashrrev_i32_e32 v159, 31, v158
	v_lshlrev_b64 v[160:161], 11, v[158:159]
	v_lshl_add_u64 v[190:191], v[160:161], 0, v[148:149]
	v_lshl_add_u64 v[158:159], v[190:191], 2, s[44:45]
	global_load_dwordx4 v[180:183], v[158:159], off nt
	global_load_dwordx4 v[186:189], v[158:159], off offset:16 nt
	v_lshlrev_b64 v[190:191], 1, v[190:191]
	v_cvt_pk_bf16_f32 v118, v118, v119
	v_cvt_pk_bf16_f32 v119, v120, v121
	v_cvt_pk_bf16_f32 v120, v114, v115
	v_cvt_pk_bf16_f32 v121, v116, v117
	v_lshl_add_u64 v[114:115], s[90:91], 0, v[190:191]
	global_store_dwordx4 v[114:115], v[118:121], off
	v_lshlrev_b32_e32 v116, 16, v120
	v_and_b32_e32 v117, 0xffff0000, v120
	v_lshlrev_b32_e32 v114, 16, v121
	v_and_b32_e32 v115, 0xffff0000, v121
	v_lshlrev_b32_e32 v120, 16, v118
	v_and_b32_e32 v121, 0xffff0000, v118
	v_lshlrev_b32_e32 v118, 16, v119
	v_and_b32_e32 v119, 0xffff0000, v119
	s_waitcnt vmcnt(2)
	v_pk_add_f32 v[118:119], v[182:183], v[118:119]
	s_waitcnt vmcnt(1)
	v_pk_add_f32 v[114:115], v[188:189], v[114:115]
	v_pk_add_f32 v[120:121], v[180:181], v[120:121]
	v_pk_add_f32 v[116:117], v[186:187], v[116:117]
	v_pk_mul_f32 v[182:183], v[198:199], v[118:119]
	v_pk_mul_f32 v[180:181], v[200:201], v[120:121]
	v_pk_mul_f32 v[186:187], v[202:203], v[114:115]
	v_pk_mul_f32 v[188:189], v[204:205], v[116:117]
	v_cvt_pk_bf16_f32 v180, v180, v181
	v_cvt_pk_bf16_f32 v181, v182, v183
	s_nop 0
	v_cvt_pk_bf16_f32 v182, v188, v189
	v_cvt_pk_bf16_f32 v183, v186, v187
	v_lshl_add_u64 v[186:187], s[96:97], 0, v[190:191]
	global_store_dwordx4 v[186:187], v[180:183], off
	s_nop 1
	v_lshl_add_u64 v[182:183], v[184:185], 0, s[4:5]
	v_lshl_add_u64 v[194:195], v[182:183], 0, v[148:149]
	v_lshl_add_u64 v[180:181], v[194:195], 2, s[44:45]
	global_load_dwordx4 v[186:189], v[180:181], off nt
	global_load_dwordx4 v[190:193], v[180:181], off offset:16 nt
	v_lshlrev_b64 v[194:195], 1, v[194:195]
	v_cvt_pk_bf16_f32 v110, v110, v111
	v_cvt_pk_bf16_f32 v111, v112, v113
	v_cvt_pk_bf16_f32 v112, v106, v107
	v_cvt_pk_bf16_f32 v113, v108, v109
	v_lshl_add_u64 v[106:107], s[90:91], 0, v[194:195]
	global_store_dwordx4 v[106:107], v[110:113], off
	v_lshlrev_b32_e32 v108, 16, v112
	v_and_b32_e32 v109, 0xffff0000, v112
	v_lshlrev_b32_e32 v106, 16, v113
	v_and_b32_e32 v107, 0xffff0000, v113
	v_lshlrev_b32_e32 v112, 16, v110
	v_and_b32_e32 v113, 0xffff0000, v110
	v_lshlrev_b32_e32 v110, 16, v111
	v_and_b32_e32 v111, 0xffff0000, v111
	s_mov_b64 s[4:5], 0x48000
	s_waitcnt vmcnt(2)
	v_pk_add_f32 v[110:111], v[188:189], v[110:111]
	s_waitcnt vmcnt(1)
	v_pk_add_f32 v[106:107], v[192:193], v[106:107]
	v_pk_add_f32 v[112:113], v[186:187], v[112:113]
	v_pk_add_f32 v[108:109], v[190:191], v[108:109]
	v_pk_mul_f32 v[188:189], v[198:199], v[110:111]
	v_pk_mul_f32 v[186:187], v[200:201], v[112:113]
	v_pk_mul_f32 v[190:191], v[202:203], v[106:107]
	v_pk_mul_f32 v[192:193], v[204:205], v[108:109]
	v_cvt_pk_bf16_f32 v186, v186, v187
	v_cvt_pk_bf16_f32 v187, v188, v189
	s_nop 0
	v_cvt_pk_bf16_f32 v188, v192, v193
	v_cvt_pk_bf16_f32 v189, v190, v191
	v_lshl_add_u64 v[190:191], s[96:97], 0, v[194:195]
	global_store_dwordx4 v[190:191], v[186:189], off
	s_nop 1
	v_lshl_add_u64 v[188:189], v[184:185], 0, s[4:5]
	v_lshl_add_u64 v[212:213], v[188:189], 0, v[148:149]
	v_lshl_add_u64 v[186:187], v[212:213], 2, s[44:45]
	global_load_dwordx4 v[190:193], v[186:187], off nt
	global_load_dwordx4 v[194:197], v[186:187], off offset:16 nt
	v_lshlrev_b64 v[212:213], 1, v[212:213]
	v_cvt_pk_bf16_f32 v94, v94, v95
	v_cvt_pk_bf16_f32 v95, v96, v97
	v_cvt_pk_bf16_f32 v96, v90, v91
	v_cvt_pk_bf16_f32 v97, v92, v93
	v_lshl_add_u64 v[90:91], s[90:91], 0, v[212:213]
	global_store_dwordx4 v[90:91], v[94:97], off
	v_lshlrev_b32_e32 v92, 16, v96
	v_and_b32_e32 v93, 0xffff0000, v96
	v_lshlrev_b32_e32 v90, 16, v97
	v_and_b32_e32 v91, 0xffff0000, v97
	v_lshlrev_b32_e32 v96, 16, v94
	v_and_b32_e32 v97, 0xffff0000, v94
	v_lshlrev_b32_e32 v94, 16, v95
	v_and_b32_e32 v95, 0xffff0000, v95
	s_mov_b64 s[4:5], 0x50000
	s_waitcnt vmcnt(2)
	v_pk_add_f32 v[94:95], v[192:193], v[94:95]
	s_waitcnt vmcnt(1)
	v_pk_add_f32 v[90:91], v[196:197], v[90:91]
	v_pk_add_f32 v[96:97], v[190:191], v[96:97]
	v_pk_add_f32 v[92:93], v[194:195], v[92:93]
	v_pk_mul_f32 v[192:193], v[198:199], v[94:95]
	v_pk_mul_f32 v[190:191], v[200:201], v[96:97]
	v_pk_mul_f32 v[194:195], v[202:203], v[90:91]
	v_pk_mul_f32 v[196:197], v[204:205], v[92:93]
	v_cvt_pk_bf16_f32 v190, v190, v191
	v_cvt_pk_bf16_f32 v191, v192, v193
	s_nop 0
	v_cvt_pk_bf16_f32 v192, v196, v197
	v_cvt_pk_bf16_f32 v193, v194, v195
	v_lshl_add_u64 v[194:195], s[96:97], 0, v[212:213]
	global_store_dwordx4 v[194:195], v[190:193], off
	s_nop 1
	v_lshl_add_u64 v[192:193], v[184:185], 0, s[4:5]
	v_lshl_add_u64 v[220:221], v[192:193], 0, v[148:149]
	v_lshl_add_u64 v[190:191], v[220:221], 2, s[44:45]
	global_load_dwordx4 v[194:197], v[190:191], off nt
	global_load_dwordx4 v[212:215], v[190:191], off offset:16 nt
	v_lshlrev_b64 v[220:221], 1, v[220:221]
	v_cvt_pk_bf16_f32 v86, v86, v87
	v_cvt_pk_bf16_f32 v87, v88, v89
	v_cvt_pk_bf16_f32 v88, v82, v83
	v_cvt_pk_bf16_f32 v89, v84, v85
	v_lshl_add_u64 v[82:83], s[90:91], 0, v[220:221]
	global_store_dwordx4 v[82:83], v[86:89], off
	v_lshlrev_b32_e32 v84, 16, v88
	v_and_b32_e32 v85, 0xffff0000, v88
	v_lshlrev_b32_e32 v82, 16, v89
	v_and_b32_e32 v83, 0xffff0000, v89
	v_lshlrev_b32_e32 v88, 16, v86
	v_and_b32_e32 v89, 0xffff0000, v86
	v_lshlrev_b32_e32 v86, 16, v87
	v_and_b32_e32 v87, 0xffff0000, v87
	s_mov_b64 s[4:5], 0x58000
	s_waitcnt vmcnt(2)
; __device__ __forceinline__ unsigned cvt_pk_bf16(float lo, float hi) { unsigned r; asm volatile("v_cvt_pk_bf16_f32 %0, %1, %2" : "=v"(r) : "v"(lo), "v"(hi)); return r; }
;     __device__ __forceinline__ void operator()(const f32x4 (&acc)[2][2][4][2], const Unit& u, int wr, int wc, int fr, int fq) const {
;     ...
;                 for (int m = 0; m < 4; ++m) { const size_t off = (size_t)(row0 + ai * HALF + m * 16) * 2048 + col0 + bj * HALF;
;                     f32x4 x0 = __builtin_nontemporal_load((const f32x4*)(base + off)), x1 = __builtin_nontemporal_load((const f32x4*)(base + off + 4));
;                     if constexpr (HAS_DIN) { const u32x4 dw = __builtin_nontemporal_load((const u32x4*)(dbuf + off));
;                         x0 += (f32x4){__builtin_bit_cast(float, dw.x << 16), __builtin_bit_cast(float, dw.x & 0xffff0000u), __builtin_bit_cast(float, dw.y << 16), __builtin_bit_cast(float, dw.y & 0xffff0000u)};
;                         x1 += (f32x4){__builtin_bit_cast(float, dw.z << 16), __builtin_bit_cast(float, dw.z & 0xffff0000u), __builtin_bit_cast(float, dw.w << 16), __builtin_bit_cast(float, dw.w & 0xffff0000u)}; }
;                     f32x4 o0, o1;
;                     if constexpr (OUT_DELTA) { const f32x4 d0 = g0 * acc[ai][bj][m][0], d1 = g1 * acc[ai][bj][m][1];
;                         u32x4 w; w.x = cvt_pk_bf16(d0[0], d0[1]); w.y = cvt_pk_bf16(d0[2], d0[3]); w.z = cvt_pk_bf16(d1[0], d1[1]); w.w = cvt_pk_bf16(d1[2], d1[3]);
;                         *(u32x4*)(dbuf + off) = w;
;                         o0 = x0 + (f32x4){__builtin_bit_cast(float, w.x << 16), __builtin_bit_cast(float, w.x & 0xffff0000u), __builtin_bit_cast(float, w.y << 16), __builtin_bit_cast(float, w.y & 0xffff0000u)};
;                         o1 = x1 + (f32x4){__builtin_bit_cast(float, w.z << 16), __builtin_bit_cast(float, w.z & 0xffff0000u), __builtin_bit_cast(float, w.w << 16), __builtin_bit_cast(float, w.w & 0xffff0000u)}; }
;                     else { o0 = x0 + g0 * acc[ai][bj][m][0]; o1 = x1 + g1 * acc[ai][bj][m][1]; *(f32x4*)(out + off) = o0; *(f32x4*)(out + off + 4) = o1; }
;                     if (Hn) { const f32x4 h0 = o0 * G0, h1 = o1 * G1;
;                         u32x4 w; w.x = cvt_pk_bf16(h0[0], h0[1]); w.y = cvt_pk_bf16(h0[2], h0[3]); w.z = cvt_pk_bf16(h1[0], h1[1]); w.w = cvt_pk_bf16(h1[2], h1[3]);
;                         *(u32x4*)(Hn + off) = w;
	v_pk_add_f32 v[86:87], v[196:197], v[86:87]
	s_waitcnt vmcnt(1)
	v_pk_add_f32 v[82:83], v[214:215], v[82:83]
	v_pk_add_f32 v[88:89], v[194:195], v[88:89]
	v_pk_add_f32 v[84:85], v[212:213], v[84:85]
	v_pk_mul_f32 v[196:197], v[198:199], v[86:87]
	v_pk_mul_f32 v[194:195], v[200:201], v[88:89]
	v_pk_mul_f32 v[212:213], v[202:203], v[82:83]
	v_pk_mul_f32 v[214:215], v[204:205], v[84:85]
	v_cvt_pk_bf16_f32 v194, v194, v195
	v_cvt_pk_bf16_f32 v195, v196, v197
	s_nop 0
	v_cvt_pk_bf16_f32 v196, v214, v215
	v_cvt_pk_bf16_f32 v197, v212, v213
	v_lshl_add_u64 v[212:213], s[96:97], 0, v[220:221]
	global_store_dwordx4 v[212:213], v[194:197], off
	s_nop 1
	v_lshl_add_u64 v[196:197], v[184:185], 0, s[4:5]
	v_lshl_add_u64 v[224:225], v[196:197], 0, v[148:149]
	v_lshl_add_u64 v[194:195], v[224:225], 2, s[44:45]
	global_load_dwordx4 v[212:215], v[194:195], off nt
	global_load_dwordx4 v[220:223], v[194:195], off offset:16 nt
	v_lshlrev_b64 v[102:103], 1, v[224:225]
	v_cvt_pk_bf16_f32 v78, v78, v79
	v_cvt_pk_bf16_f32 v79, v80, v81
	v_cvt_pk_bf16_f32 v80, v74, v75
	v_cvt_pk_bf16_f32 v81, v76, v77
	v_lshl_add_u64 v[74:75], s[90:91], 0, v[102:103]
	global_store_dwordx4 v[74:75], v[78:81], off
	v_lshlrev_b32_e32 v76, 16, v80
	v_and_b32_e32 v77, 0xffff0000, v80
	v_lshlrev_b32_e32 v74, 16, v81
	v_and_b32_e32 v75, 0xffff0000, v81
	v_lshlrev_b32_e32 v80, 16, v78
	v_and_b32_e32 v81, 0xffff0000, v78
	v_lshlrev_b32_e32 v78, 16, v79
	v_and_b32_e32 v79, 0xffff0000, v79
	v_lshl_add_u64 v[102:103], s[96:97], 0, v[102:103]
	v_or_b32_e32 v148, 0x80, v148
	s_waitcnt vmcnt(2)
	v_pk_add_f32 v[78:79], v[214:215], v[78:79]
	v_pk_add_f32 v[80:81], v[212:213], v[80:81]
	s_waitcnt vmcnt(1)
	v_pk_add_f32 v[74:75], v[222:223], v[74:75]
	v_pk_add_f32 v[76:77], v[220:221], v[76:77]
	v_pk_mul_f32 v[100:101], v[198:199], v[78:79]
	v_pk_mul_f32 v[98:99], v[200:201], v[80:81]
	v_pk_mul_f32 v[104:105], v[202:203], v[74:75]
	v_pk_mul_f32 v[198:199], v[204:205], v[76:77]
	v_cvt_pk_bf16_f32 v98, v98, v99
	v_cvt_pk_bf16_f32 v99, v100, v101
	s_nop 0
	v_cvt_pk_bf16_f32 v100, v198, v199
	v_cvt_pk_bf16_f32 v101, v104, v105
	global_store_dwordx4 v[102:103], v[98:101], off
	global_load_dwordx4 v[100:103], v[178:179], off offset:512 nt
	global_load_dwordx4 v[198:201], v[178:179], off offset:528 nt
	v_lshl_add_u64 v[98:99], v[184:185], 0, v[148:149]
	v_pk_mul_f32 v[104:105], v[68:69], v[28:29]
	v_pk_mul_f32 v[68:69], v[66:67], v[26:27]
	v_cvt_pk_bf16_f32 v66, v70, v71
	v_cvt_pk_bf16_f32 v67, v72, v73
	s_nop 0
	v_cvt_pk_bf16_f32 v68, v68, v69
	v_cvt_pk_bf16_f32 v69, v104, v105
	v_lshlrev_b64 v[104:105], 1, v[98:99]
	v_lshl_add_u64 v[70:71], s[90:91], 0, v[104:105]
	global_store_dwordx4 v[70:71], v[66:69], off
	v_lshlrev_b32_e32 v72, 16, v68
	v_and_b32_e32 v73, 0xffff0000, v68
	v_lshlrev_b32_e32 v68, 16, v69
	v_and_b32_e32 v69, 0xffff0000, v69
	s_waitcnt vmcnt(1)
	v_pk_add_f32 v[70:71], v[200:201], v[68:69]
	v_lshlrev_b32_e32 v68, 16, v66
	v_and_b32_e32 v69, 0xffff0000, v66
	v_lshlrev_b32_e32 v66, 16, v67
	v_and_b32_e32 v67, 0xffff0000, v67
	v_pk_add_f32 v[98:99], v[102:103], v[66:67]
	v_pk_add_f32 v[100:101], v[100:101], v[68:69]
	v_pk_add_f32 v[72:73], v[198:199], v[72:73]
	v_pk_mul_f32 v[68:69], v[150:151], v[98:99]
	v_pk_mul_f32 v[66:67], v[152:153], v[100:101]
	v_pk_mul_f32 v[102:103], v[154:155], v[70:71]
	v_pk_mul_f32 v[178:179], v[156:157], v[72:73]
	v_cvt_pk_bf16_f32 v66, v66, v67
	v_cvt_pk_bf16_f32 v67, v68, v69
	s_nop 0
	v_cvt_pk_bf16_f32 v68, v178, v179
	v_cvt_pk_bf16_f32 v69, v102, v103
	v_lshl_add_u64 v[102:103], s[96:97], 0, v[104:105]
	global_store_dwordx4 v[102:103], v[66:69], off
	s_nop 1
	v_mul_f32_e32 v66, v101, v101
	v_mul_f32_e32 v67, v99, v99
	v_fmac_f32_e32 v66, v100, v100
	v_fmac_f32_e32 v67, v98, v98
	v_add_f32_e32 v66, v66, v67
	v_mul_f32_e32 v67, v73, v73
	v_mul_f32_e32 v68, v71, v71
	v_fmac_f32_e32 v67, v72, v72
	v_fmac_f32_e32 v68, v70, v70
	v_add_f32_e32 v67, v67, v68
	global_load_dwordx4 v[68:71], v[138:139], off offset:512 nt
	global_load_dwordx4 v[98:101], v[138:139], off offset:528 nt
	v_lshl_add_u64 v[72:73], v[140:141], 0, v[148:149]
	v_lshlrev_b64 v[72:73], 1, v[72:73]
	v_cvt_pk_bf16_f32 v62, v62, v63
	v_cvt_pk_bf16_f32 v63, v64, v65
	v_cvt_pk_bf16_f32 v64, v58, v59
	v_cvt_pk_bf16_f32 v65, v60, v61
	v_lshl_add_u64 v[58:59], s[90:91], 0, v[72:73]
	global_store_dwordx4 v[58:59], v[62:65], off
	v_lshlrev_b32_e32 v60, 16, v64
	v_and_b32_e32 v61, 0xffff0000, v64
	v_lshlrev_b32_e32 v58, 16, v65
	v_and_b32_e32 v59, 0xffff0000, v65
	v_lshlrev_b32_e32 v64, 16, v62
	v_and_b32_e32 v65, 0xffff0000, v62
	v_lshlrev_b32_e32 v62, 16, v63
	v_and_b32_e32 v63, 0xffff0000, v63
	v_lshl_add_u64 v[72:73], s[96:97], 0, v[72:73]
	v_add_f32_e32 v66, v66, v67
	v_add_f32_e32 v66, v211, v66
	s_waitcnt vmcnt(2)
	v_pk_add_f32 v[62:63], v[70:71], v[62:63]
	v_pk_add_f32 v[64:65], v[68:69], v[64:65]
	s_waitcnt vmcnt(1)
	v_pk_add_f32 v[58:59], v[100:101], v[58:59]
	v_pk_add_f32 v[60:61], v[98:99], v[60:61]
	v_pk_mul_f32 v[70:71], v[150:151], v[62:63]
	v_pk_mul_f32 v[68:69], v[152:153], v[64:65]
	v_pk_mul_f32 v[98:99], v[154:155], v[58:59]
	v_pk_mul_f32 v[100:101], v[156:157], v[60:61]
	v_cvt_pk_bf16_f32 v68, v68, v69
	v_cvt_pk_bf16_f32 v69, v70, v71
	s_nop 0
	v_cvt_pk_bf16_f32 v70, v100, v101
	v_cvt_pk_bf16_f32 v71, v98, v99
	global_store_dwordx4 v[72:73], v[68:71], off
	global_load_dwordx4 v[68:71], v[142:143], off offset:512 nt
	s_nop 0
	global_load_dwordx4 v[98:101], v[142:143], off offset:528 nt
	v_lshl_add_u64 v[72:73], v[144:145], 0, v[148:149]
	v_lshlrev_b64 v[72:73], 1, v[72:73]
	v_cvt_pk_bf16_f32 v54, v54, v55
	v_cvt_pk_bf16_f32 v55, v56, v57
	v_cvt_pk_bf16_f32 v56, v50, v51
	v_cvt_pk_bf16_f32 v57, v52, v53
	v_lshl_add_u64 v[50:51], s[90:91], 0, v[72:73]
	global_store_dwordx4 v[50:51], v[54:57], off
	v_lshlrev_b32_e32 v52, 16, v56
	v_and_b32_e32 v53, 0xffff0000, v56
	v_lshlrev_b32_e32 v50, 16, v57
	v_and_b32_e32 v51, 0xffff0000, v57
	v_lshlrev_b32_e32 v56, 16, v54
	v_and_b32_e32 v57, 0xffff0000, v54
	v_lshlrev_b32_e32 v54, 16, v55
	v_and_b32_e32 v55, 0xffff0000, v55
	v_lshl_add_u64 v[72:73], s[96:97], 0, v[72:73]
	s_waitcnt vmcnt(2)
; __device__ __forceinline__ unsigned cvt_pk_bf16(float lo, float hi) { unsigned r; asm volatile("v_cvt_pk_bf16_f32 %0, %1, %2" : "=v"(r) : "v"(lo), "v"(hi)); return r; }
;     __device__ __forceinline__ void operator()(const f32x4 (&acc)[2][2][4][2], const Unit& u, int wr, int wc, int fr, int fq) const {
;     ...
;                 for (int m = 0; m < 4; ++m) { const size_t off = (size_t)(row0 + ai * HALF + m * 16) * 2048 + col0 + bj * HALF;
;                     f32x4 x0 = __builtin_nontemporal_load((const f32x4*)(base + off)), x1 = __builtin_nontemporal_load((const f32x4*)(base + off + 4));
;                     if constexpr (HAS_DIN) { const u32x4 dw = __builtin_nontemporal_load((const u32x4*)(dbuf + off));
;                         x0 += (f32x4){__builtin_bit_cast(float, dw.x << 16), __builtin_bit_cast(float, dw.x & 0xffff0000u), __builtin_bit_cast(float, dw.y << 16), __builtin_bit_cast(float, dw.y & 0xffff0000u)};
;                         x1 += (f32x4){__builtin_bit_cast(float, dw.z << 16), __builtin_bit_cast(float, dw.z & 0xffff0000u), __builtin_bit_cast(float, dw.w << 16), __builtin_bit_cast(float, dw.w & 0xffff0000u)}; }
;                     f32x4 o0, o1;
;                     if constexpr (OUT_DELTA) { const f32x4 d0 = g0 * acc[ai][bj][m][0], d1 = g1 * acc[ai][bj][m][1];
;                         u32x4 w; w.x = cvt_pk_bf16(d0[0], d0[1]); w.y = cvt_pk_bf16(d0[2], d0[3]); w.z = cvt_pk_bf16(d1[0], d1[1]); w.w = cvt_pk_bf16(d1[2], d1[3]);
;                         *(u32x4*)(dbuf + off) = w;
;                         o0 = x0 + (f32x4){__builtin_bit_cast(float, w.x << 16), __builtin_bit_cast(float, w.x & 0xffff0000u), __builtin_bit_cast(float, w.y << 16), __builtin_bit_cast(float, w.y & 0xffff0000u)};
;                         o1 = x1 + (f32x4){__builtin_bit_cast(float, w.z << 16), __builtin_bit_cast(float, w.z & 0xffff0000u), __builtin_bit_cast(float, w.w << 16), __builtin_bit_cast(float, w.w & 0xffff0000u)}; }
;                     else { o0 = x0 + g0 * acc[ai][bj][m][0]; o1 = x1 + g1 * acc[ai][bj][m][1]; *(f32x4*)(out + off) = o0; *(f32x4*)(out + off + 4) = o1; }
;                     if (Hn) { const f32x4 h0 = o0 * G0, h1 = o1 * G1;
;                         u32x4 w; w.x = cvt_pk_bf16(h0[0], h0[1]); w.y = cvt_pk_bf16(h0[2], h0[3]); w.z = cvt_pk_bf16(h1[0], h1[1]); w.w = cvt_pk_bf16(h1[2], h1[3]);
;                         *(u32x4*)(Hn + off) = w;
	v_pk_add_f32 v[54:55], v[70:71], v[54:55]
	v_pk_add_f32 v[56:57], v[68:69], v[56:57]
	s_waitcnt vmcnt(1)
	v_pk_add_f32 v[50:51], v[100:101], v[50:51]
	v_pk_add_f32 v[52:53], v[98:99], v[52:53]
	v_pk_mul_f32 v[70:71], v[150:151], v[54:55]
	v_pk_mul_f32 v[68:69], v[152:153], v[56:57]
	v_pk_mul_f32 v[98:99], v[154:155], v[50:51]
	v_pk_mul_f32 v[100:101], v[156:157], v[52:53]
	v_cvt_pk_bf16_f32 v68, v68, v69
	v_cvt_pk_bf16_f32 v69, v70, v71
	s_nop 0
	v_cvt_pk_bf16_f32 v70, v100, v101
	v_cvt_pk_bf16_f32 v71, v98, v99
	global_store_dwordx4 v[72:73], v[68:71], off
	global_load_dwordx4 v[68:71], v[158:159], off offset:512 nt
	s_nop 0
	global_load_dwordx4 v[98:101], v[158:159], off offset:528 nt
	v_lshl_add_u64 v[72:73], v[160:161], 0, v[148:149]
	v_lshlrev_b64 v[72:73], 1, v[72:73]
	v_cvt_pk_bf16_f32 v46, v46, v47
	v_cvt_pk_bf16_f32 v47, v48, v49
	v_cvt_pk_bf16_f32 v48, v42, v43
	v_cvt_pk_bf16_f32 v49, v44, v45
	v_lshl_add_u64 v[42:43], s[90:91], 0, v[72:73]
	global_store_dwordx4 v[42:43], v[46:49], off
	v_lshlrev_b32_e32 v44, 16, v48
	v_and_b32_e32 v45, 0xffff0000, v48
	v_lshlrev_b32_e32 v42, 16, v49
	v_and_b32_e32 v43, 0xffff0000, v49
	v_lshlrev_b32_e32 v48, 16, v46
	v_and_b32_e32 v49, 0xffff0000, v46
	v_lshlrev_b32_e32 v46, 16, v47
	v_and_b32_e32 v47, 0xffff0000, v47
	v_lshl_add_u64 v[72:73], s[96:97], 0, v[72:73]
	s_waitcnt vmcnt(2)
	v_pk_add_f32 v[46:47], v[70:71], v[46:47]
	v_pk_add_f32 v[48:49], v[68:69], v[48:49]
	s_waitcnt vmcnt(1)
	v_pk_add_f32 v[42:43], v[100:101], v[42:43]
	v_pk_add_f32 v[44:45], v[98:99], v[44:45]
	v_pk_mul_f32 v[70:71], v[150:151], v[46:47]
	v_pk_mul_f32 v[68:69], v[152:153], v[48:49]
	v_pk_mul_f32 v[98:99], v[154:155], v[42:43]
	v_pk_mul_f32 v[100:101], v[156:157], v[44:45]
	v_cvt_pk_bf16_f32 v68, v68, v69
	v_cvt_pk_bf16_f32 v69, v70, v71
	s_nop 0
	v_cvt_pk_bf16_f32 v70, v100, v101
	v_cvt_pk_bf16_f32 v71, v98, v99
	global_store_dwordx4 v[72:73], v[68:71], off
	global_load_dwordx4 v[68:71], v[180:181], off offset:512 nt
	s_nop 0
	global_load_dwordx4 v[98:101], v[180:181], off offset:528 nt
	v_lshl_add_u64 v[72:73], v[182:183], 0, v[148:149]
	v_lshlrev_b64 v[72:73], 1, v[72:73]
	v_cvt_pk_bf16_f32 v38, v38, v39
	v_cvt_pk_bf16_f32 v39, v40, v41
	v_cvt_pk_bf16_f32 v40, v34, v35
	v_cvt_pk_bf16_f32 v41, v36, v37
	v_lshl_add_u64 v[34:35], s[90:91], 0, v[72:73]
	global_store_dwordx4 v[34:35], v[38:41], off
	v_lshlrev_b32_e32 v36, 16, v40
	v_and_b32_e32 v37, 0xffff0000, v40
	v_lshlrev_b32_e32 v34, 16, v41
	v_and_b32_e32 v35, 0xffff0000, v41
	v_lshlrev_b32_e32 v40, 16, v38
	v_and_b32_e32 v41, 0xffff0000, v38
	v_lshlrev_b32_e32 v38, 16, v39
	v_and_b32_e32 v39, 0xffff0000, v39
	v_lshl_add_u64 v[72:73], s[96:97], 0, v[72:73]
	s_waitcnt vmcnt(2)
	v_pk_add_f32 v[38:39], v[70:71], v[38:39]
	v_pk_add_f32 v[40:41], v[68:69], v[40:41]
	s_waitcnt vmcnt(1)
	v_pk_add_f32 v[34:35], v[100:101], v[34:35]
	v_pk_add_f32 v[36:37], v[98:99], v[36:37]
	v_pk_mul_f32 v[70:71], v[150:151], v[38:39]
	v_pk_mul_f32 v[68:69], v[152:153], v[40:41]
	v_pk_mul_f32 v[98:99], v[154:155], v[34:35]
	v_pk_mul_f32 v[100:101], v[156:157], v[36:37]
	v_cvt_pk_bf16_f32 v68, v68, v69
	v_cvt_pk_bf16_f32 v69, v70, v71
	s_nop 0
	v_cvt_pk_bf16_f32 v70, v100, v101
	v_cvt_pk_bf16_f32 v71, v98, v99
	global_store_dwordx4 v[72:73], v[68:71], off
	global_load_dwordx4 v[68:71], v[186:187], off offset:512 nt
	s_nop 0
	global_load_dwordx4 v[98:101], v[186:187], off offset:528 nt
	v_lshl_add_u64 v[72:73], v[188:189], 0, v[148:149]
	v_lshlrev_b64 v[72:73], 1, v[72:73]
	v_cvt_pk_bf16_f32 v22, v22, v23
	v_cvt_pk_bf16_f32 v23, v24, v25
	v_cvt_pk_bf16_f32 v24, v18, v19
	v_cvt_pk_bf16_f32 v25, v20, v21
	v_lshl_add_u64 v[18:19], s[90:91], 0, v[72:73]
	global_store_dwordx4 v[18:19], v[22:25], off
	v_lshlrev_b32_e32 v20, 16, v24
	v_and_b32_e32 v21, 0xffff0000, v24
	v_lshlrev_b32_e32 v18, 16, v25
	v_and_b32_e32 v19, 0xffff0000, v25
	v_lshlrev_b32_e32 v24, 16, v22
	v_and_b32_e32 v25, 0xffff0000, v22
	v_lshlrev_b32_e32 v22, 16, v23
	v_and_b32_e32 v23, 0xffff0000, v23
	v_lshl_add_u64 v[72:73], s[96:97], 0, v[72:73]
	s_waitcnt vmcnt(2)
	v_pk_add_f32 v[22:23], v[70:71], v[22:23]
	v_pk_add_f32 v[24:25], v[68:69], v[24:25]
	s_waitcnt vmcnt(1)
; __device__ __forceinline__ unsigned cvt_pk_bf16(float lo, float hi) { unsigned r; asm volatile("v_cvt_pk_bf16_f32 %0, %1, %2" : "=v"(r) : "v"(lo), "v"(hi)); return r; }
;     __device__ __forceinline__ void operator()(const f32x4 (&acc)[2][2][4][2], const Unit& u, int wr, int wc, int fr, int fq) const {
;     ...
;                 for (int m = 0; m < 4; ++m) { const size_t off = (size_t)(row0 + ai * HALF + m * 16) * 2048 + col0 + bj * HALF;
;                     f32x4 x0 = __builtin_nontemporal_load((const f32x4*)(base + off)), x1 = __builtin_nontemporal_load((const f32x4*)(base + off + 4));
;                     if constexpr (HAS_DIN) { const u32x4 dw = __builtin_nontemporal_load((const u32x4*)(dbuf + off));
;                         x0 += (f32x4){__builtin_bit_cast(float, dw.x << 16), __builtin_bit_cast(float, dw.x & 0xffff0000u), __builtin_bit_cast(float, dw.y << 16), __builtin_bit_cast(float, dw.y & 0xffff0000u)};
;                         x1 += (f32x4){__builtin_bit_cast(float, dw.z << 16), __builtin_bit_cast(float, dw.z & 0xffff0000u), __builtin_bit_cast(float, dw.w << 16), __builtin_bit_cast(float, dw.w & 0xffff0000u)}; }
;                     f32x4 o0, o1;
;                     if constexpr (OUT_DELTA) { const f32x4 d0 = g0 * acc[ai][bj][m][0], d1 = g1 * acc[ai][bj][m][1];
;                         u32x4 w; w.x = cvt_pk_bf16(d0[0], d0[1]); w.y = cvt_pk_bf16(d0[2], d0[3]); w.z = cvt_pk_bf16(d1[0], d1[1]); w.w = cvt_pk_bf16(d1[2], d1[3]);
;                         *(u32x4*)(dbuf + off) = w;
;                         o0 = x0 + (f32x4){__builtin_bit_cast(float, w.x << 16), __builtin_bit_cast(float, w.x & 0xffff0000u), __builtin_bit_cast(float, w.y << 16), __builtin_bit_cast(float, w.y & 0xffff0000u)};
;                         o1 = x1 + (f32x4){__builtin_bit_cast(float, w.z << 16), __builtin_bit_cast(float, w.z & 0xffff0000u), __builtin_bit_cast(float, w.w << 16), __builtin_bit_cast(float, w.w & 0xffff0000u)}; }
;                     else { o0 = x0 + g0 * acc[ai][bj][m][0]; o1 = x1 + g1 * acc[ai][bj][m][1]; *(f32x4*)(out + off) = o0; *(f32x4*)(out + off + 4) = o1; }
;                     if (Hn) { const f32x4 h0 = o0 * G0, h1 = o1 * G1;
;                         u32x4 w; w.x = cvt_pk_bf16(h0[0], h0[1]); w.y = cvt_pk_bf16(h0[2], h0[3]); w.z = cvt_pk_bf16(h1[0], h1[1]); w.w = cvt_pk_bf16(h1[2], h1[3]);
;                         *(u32x4*)(Hn + off) = w;
	v_pk_add_f32 v[18:19], v[100:101], v[18:19]
	v_pk_add_f32 v[20:21], v[98:99], v[20:21]
	v_pk_mul_f32 v[70:71], v[150:151], v[22:23]
	v_pk_mul_f32 v[68:69], v[152:153], v[24:25]
	v_pk_mul_f32 v[98:99], v[154:155], v[18:19]
	v_pk_mul_f32 v[100:101], v[156:157], v[20:21]
	v_cvt_pk_bf16_f32 v68, v68, v69
	v_cvt_pk_bf16_f32 v69, v70, v71
	s_nop 0
	v_cvt_pk_bf16_f32 v70, v100, v101
	v_cvt_pk_bf16_f32 v71, v98, v99
	global_store_dwordx4 v[72:73], v[68:71], off
	global_load_dwordx4 v[68:71], v[190:191], off offset:512 nt
	s_nop 0
	global_load_dwordx4 v[98:101], v[190:191], off offset:528 nt
	v_lshl_add_u64 v[72:73], v[192:193], 0, v[148:149]
	v_lshlrev_b64 v[72:73], 1, v[72:73]
	v_cvt_pk_bf16_f32 v14, v14, v15
	v_cvt_pk_bf16_f32 v15, v16, v17
	v_cvt_pk_bf16_f32 v16, v10, v11
	v_cvt_pk_bf16_f32 v17, v12, v13
	v_lshl_add_u64 v[10:11], s[90:91], 0, v[72:73]
	global_store_dwordx4 v[10:11], v[14:17], off
	v_lshlrev_b32_e32 v12, 16, v16
	v_and_b32_e32 v13, 0xffff0000, v16
	v_lshlrev_b32_e32 v10, 16, v17
	v_and_b32_e32 v11, 0xffff0000, v17
	v_lshlrev_b32_e32 v16, 16, v14
	v_and_b32_e32 v17, 0xffff0000, v14
	v_lshlrev_b32_e32 v14, 16, v15
	v_and_b32_e32 v15, 0xffff0000, v15
	v_lshl_add_u64 v[72:73], s[96:97], 0, v[72:73]
	s_waitcnt vmcnt(2)
	v_pk_add_f32 v[14:15], v[70:71], v[14:15]
	v_pk_add_f32 v[16:17], v[68:69], v[16:17]
	s_waitcnt vmcnt(1)
	v_pk_add_f32 v[10:11], v[100:101], v[10:11]
	v_pk_add_f32 v[12:13], v[98:99], v[12:13]
	v_pk_mul_f32 v[70:71], v[150:151], v[14:15]
	v_pk_mul_f32 v[68:69], v[152:153], v[16:17]
	v_pk_mul_f32 v[98:99], v[154:155], v[10:11]
	v_pk_mul_f32 v[100:101], v[156:157], v[12:13]
	v_cvt_pk_bf16_f32 v68, v68, v69
	v_cvt_pk_bf16_f32 v69, v70, v71
	s_nop 0
	v_cvt_pk_bf16_f32 v70, v100, v101
	v_cvt_pk_bf16_f32 v71, v98, v99
	global_store_dwordx4 v[72:73], v[68:71], off
	global_load_dwordx4 v[68:71], v[194:195], off offset:512 nt
	s_nop 0
	global_load_dwordx4 v[98:101], v[194:195], off offset:528 nt
	v_lshl_add_u64 v[72:73], v[196:197], 0, v[148:149]
	v_lshlrev_b64 v[30:31], 1, v[72:73]
	v_cvt_pk_bf16_f32 v6, v6, v7
	v_cvt_pk_bf16_f32 v7, v8, v9
	v_cvt_pk_bf16_f32 v8, v2, v3
	v_cvt_pk_bf16_f32 v9, v4, v5
	v_lshl_add_u64 v[2:3], s[90:91], 0, v[30:31]
	global_store_dwordx4 v[2:3], v[6:9], off
	v_lshlrev_b32_e32 v4, 16, v8
	v_and_b32_e32 v5, 0xffff0000, v8
	v_lshlrev_b32_e32 v2, 16, v9
	v_and_b32_e32 v3, 0xffff0000, v9
	v_lshlrev_b32_e32 v8, 16, v6
	v_and_b32_e32 v9, 0xffff0000, v6
	v_lshlrev_b32_e32 v6, 16, v7
	v_and_b32_e32 v7, 0xffff0000, v7
	v_lshl_add_u64 v[30:31], s[96:97], 0, v[30:31]
	s_waitcnt vmcnt(2)
	v_pk_add_f32 v[8:9], v[68:69], v[8:9]
	v_pk_add_f32 v[6:7], v[70:71], v[6:7]
	v_pk_mul_f32 v[26:27], v[152:153], v[8:9]
	s_waitcnt vmcnt(1)
	v_pk_add_f32 v[2:3], v[100:101], v[2:3]
	v_pk_add_f32 v[4:5], v[98:99], v[4:5]
	v_pk_mul_f32 v[28:29], v[150:151], v[6:7]
	v_cvt_pk_bf16_f32 v26, v26, v27
	v_pk_mul_f32 v[32:33], v[154:155], v[2:3]
	v_cvt_pk_bf16_f32 v27, v28, v29
	v_pk_mul_f32 v[68:69], v[156:157], v[4:5]
	s_nop 0
	v_cvt_pk_bf16_f32 v28, v68, v69
	v_cvt_pk_bf16_f32 v29, v32, v33
	global_store_dwordx4 v[30:31], v[26:29], off
	s_nop 1
	v_and_b32_e32 v27, 64, v218
	v_xor_b32_e32 v26, 16, v218
	v_add_u32_e32 v27, 64, v27
	v_cmp_lt_i32_e32 vcc, v26, v27
	s_nop 1
	v_cndmask_b32_e32 v26, v218, v26, vcc
	v_lshlrev_b32_e32 v28, 2, v26
	v_xor_b32_e32 v26, 32, v218
	v_cmp_lt_i32_e32 vcc, v26, v27
	s_nop 1
	v_cndmask_b32_e32 v26, v218, v26, vcc
	v_lshlrev_b32_e32 v29, 2, v26
	ds_bpermute_b32 v26, v28, v66
	s_waitcnt lgkmcnt(0)
	v_add_f32_e32 v30, v66, v26
	ds_bpermute_b32 v31, v29, v30
	v_lshl_add_u64 v[26:27], v[146:147], 3, s[42:43]
	s_and_saveexec_b64 s[4:5], s[0:1]
	s_mov_b32 s8, 0x2f800000
	s_mov_b32 s9, 0xcf800000
	s_cbranch_execz .LBB0_558
	s_waitcnt lgkmcnt(0)
	v_add_f32_e32 v30, v30, v31
	v_mul_f32_e32 v30, 0x47800000, v30
	v_rndne_f32_e32 v30, v30
	v_mul_f32_e64 v31, |v30|, s8
	v_floor_f32_e32 v31, v31
	v_fma_f32 v32, v31, s9, |v30|
	v_cvt_u32_f32_e32 v32, v32
	v_cvt_u32_f32_e32 v31, v31
	v_ashrrev_i32_e32 v33, 31, v30
	v_xor_b32_e32 v30, v32, v33
	v_xor_b32_e32 v31, v31, v33
	v_sub_co_u32_e32 v30, vcc, v30, v33
	s_nop 1
	v_subb_co_u32_e32 v31, vcc, v31, v33, vcc
	global_atomic_add_x2 v[26:27], v[30:31], off

; #define PG8_WAIT_V(n) asm volatile("s_waitcnt vmcnt(" #n ")" ::: "memory")
; #define PG8_BAR __builtin_amdgcn_s_barrier()
; template <class Epi, class Sched, bool ALIGN_EPI = false, bool SP2 = false>
; __device__ __forceinline__ void gemm_phase(PG8_LAS unsigned char* lds, const Gemm g, const Sched& S, const Epi& E) {
;     ...
;     PG8_WAIT_V(0);
;     if constexpr (!ALIGN_EPI) { if (wr == 0) PG8_BAR; }
;     PG8_BAR;
.LBB0_572:
	s_waitcnt vmcnt(0)
	s_cmpk_gt_u32 s14, 0xff
	s_movk_i32 s48, 0x2000
	s_movk_i32 s49, 0x3000
	s_movk_i32 s46, 0x1ff
	v_readlane_b32 s50, v241, 17
	v_readlane_b32 s40, v241, 42
	s_cbranch_scc1 .LBB0_574
.LBB0_574:
	s_barrier

; #define PG8_STAGE(bufoff, gbase, voff) do { const char* gb_ = (const char*)(gbase); asm volatile("" : "+s"(gb_)); _Pragma("unroll") for (int _i = 0; _i < 2; ++_i) { unsigned vo_ = (voff)[_i]; asm volatile("" : "+v"(vo_));        \
;         __builtin_amdgcn_global_load_lds((const unsigned*)(gb_ + vo_), (PG8_LAS unsigned*)(lds + (bufoff) + ldsw + _i * 8192), 16, 0, 0); } } while (0)
; #define PG8_WAIT_V(n) asm volatile("s_waitcnt vmcnt(" #n ")" ::: "memory")
; #define PG8_BAR __builtin_amdgcn_s_barrier()
; template <class Epi, class Sched, bool ALIGN_EPI = false, bool SP2 = false>
; __device__ __forceinline__ void gemm_phase(PG8_LAS unsigned char* lds, const Gemm g, const Sched& S, const Epi& E) {
;     ...
;     for (int i = 0; i < 2; ++i) { int R, C; stage_rc(tid * 16 + i * 8192, R, C); const int Rb = Epi::PERM ? ((R & ~31) + perm32(R & 31)) : R;
;         voffA[i] = (unsigned)(R * K + C) * 2u; voffB[i] = (unsigned)(Rb * K + C) * 2u; }
;     const size_t kstep = (size_t)(BK * 2);
;     const size_t hstep = (size_t)HALF * K * 2;
;     const size_t tstep = 2 * hstep;
;     const unsigned ldsw = (unsigned)wid * 1024u;
;     const int aoff = lds_byte(wr * 64 + fr, fq * 8), boff = lds_byte(wc * 32 + fr, fq * 8);
;     ...
;     const char* cA = (const char*)g.A + (size_t)cur.pm * tstep; const char* cB = (const char*)g.Bt + (size_t)cur.pn * tstep;
;     S.a_ready(cur);
;     if constexpr (SP2) {
;         PG8_STAGE(PG8_SB(0, 0), cB, voffB); PG8_STAGE(PG8_SB(0, 1), cB + hstep, voffB); PG8_STAGE(PG8_SA(0, 0), cA, voffA); PG8_STAGE(PG8_SA(0, 1), cA + hstep, voffA);
;         if (wr == 1) PG8_BAR;
;         PG8_WAIT_V(2); PG8_BAR;
;         PG8_STAGE(PG8_SB(1, 0), cB + kstep, voffB); PG8_STAGE(PG8_SA(1, 0), cA + kstep, voffA); PG8_STAGE(PG8_SB(1, 1), cB + hstep + kstep, voffB);
;         PG8_WAIT_V(6); PG8_BAR;
.LBB0_624:
	s_andn2_b64 vcc, exec, s[0:1]
	s_cbranch_vccnz .LBB0_687
	v_readlane_b32 s0, v242, 3
	s_waitcnt vmcnt(0)
	v_mov_b32_e32 v2, v0
	v_readlane_b32 s1, v242, 4
	s_andn2_b64 vcc, exec, s[0:1]
	v_readfirstlane_b32 s2, v2
	s_cbranch_vccnz .LBB0_641
	v_bfe_i32 v4, v2, 27, 1
	s_waitcnt lgkmcnt(0)
	v_lshlrev_b32_e32 v3, 4, v2
	v_lshrrev_b32_e32 v4, 22, v4
	v_add_u32_e32 v4, v3, v4
	v_and_b32_e32 v4, 0xfffffc00, v4
	v_sub_u32_e32 v4, v3, v4
	v_ashrrev_i32_e32 v1, 31, v2
	v_lshrrev_b32_e32 v5, 4, v4
	v_lshrrev_b32_e32 v1, 26, v1
	v_bitop3_b32 v4, v5, v4, 32 bitop3:0x6c
	v_add_u32_e32 v1, v2, v1
	v_ashrrev_i32_e32 v6, 31, v4
	v_ashrrev_i32_e32 v1, 6, v1
	v_lshrrev_b32_e32 v6, 26, v6
	v_lshlrev_b32_e32 v5, 3, v1
	v_add_u32_e32 v6, v4, v6
	v_readlane_b32 s0, v241, 44
	v_and_b32_e32 v5, -16, v5
	v_ashrrev_i32_e32 v7, 6, v6
	v_and_b32_e32 v6, 0xc0, v6
	s_add_u32 s24, s0, 0x2400000
	v_readlane_b32 s0, v241, 45
	v_add_u32_e32 v5, v7, v5
	v_sub_u32_e32 v4, v4, v6
	s_addc_u32 s25, s0, 0
	v_lshlrev_b32_e32 v1, 5, v1
	v_ashrrev_i16_sdwa v4, v217, sext(v4) dst_sel:DWORD dst_unused:UNUSED_PAD src0_sel:DWORD src1_sel:BYTE_0
	v_lshlrev_b32_e32 v6, 1, v5
	v_lshrrev_b32_e32 v8, 2, v5
	v_and_b32_e32 v7, 3, v7
	s_mov_b32 s0, 0xfffe0
	v_and_b32_e32 v1, 32, v1
	v_bfe_i32 v4, v4, 0, 16
	v_and_b32_e32 v6, 24, v6
	v_and_b32_e32 v8, 4, v8
	v_and_or_b32 v7, v5, s0, v7
	v_or3_b32 v6, v7, v8, v6
	v_add_lshl_u32 v4, v1, v4, 1
	v_add_u32_e32 v3, 0x2000, v3
	v_lshl_add_u32 v1, v5, 12, v4
	v_lshl_add_u32 v162, v6, 12, v4
	v_ashrrev_i32_e32 v4, 31, v3
	v_lshrrev_b32_e32 v4, 22, v4
	v_add_u32_e32 v4, v3, v4
	v_ashrrev_i32_e32 v4, 10, v4
	v_mul_i32_i24_e32 v5, 0x400, v4
	v_sub_u32_e32 v3, v3, v5
	v_lshrrev_b32_e32 v5, 4, v3
	v_bitop3_b32 v3, v5, v3, 32 bitop3:0x6c
	v_ashrrev_i32_e32 v6, 31, v3
	v_lshrrev_b32_e32 v6, 26, v6
	v_lshlrev_b32_e32 v5, 3, v4
	v_add_u32_e32 v6, v3, v6
	v_and_b32_e32 v5, -16, v5
	v_ashrrev_i32_e32 v7, 6, v6
	v_and_b32_e32 v6, 0xc0, v6
	v_add_u32_e32 v5, v7, v5
	v_sub_u32_e32 v3, v3, v6
	v_and_b32_e32 v7, 3, v7
	s_ashr_i32 s4, s2, 6
	s_ashr_i32 s3, s2, 8
	v_lshlrev_b32_e32 v4, 5, v4
	v_ashrrev_i16_sdwa v3, v217, sext(v3) dst_sel:DWORD dst_unused:UNUSED_PAD src0_sel:DWORD src1_sel:BYTE_0
	v_lshlrev_b32_e32 v6, 1, v5
	v_lshrrev_b32_e32 v8, 2, v5
	v_and_or_b32 v7, v5, s0, v7
	s_lshl_b32 s26, s4, 10
	v_readlane_b32 s0, v242, 7
	v_and_b32_e32 v4, 32, v4
	v_bfe_i32 v3, v3, 0, 16
	v_and_b32_e32 v6, 24, v6
	v_and_b32_e32 v8, 4, v8
	v_readlane_b32 s1, v242, 8
	s_add_u32 s16, s24, s0
	v_or3_b32 v6, v7, v8, v6
	v_add_lshl_u32 v3, v4, v3, 1
	s_addc_u32 s17, s25, s1
	v_lshl_add_u32 v164, v5, 12, v3
	v_lshl_add_u32 v184, v6, 12, v3
	s_mov_b64 s[0:1], s[16:17]
	s_add_i32 s27, s26, 0
	v_mov_b32_e32 v3, v162
	s_add_i32 m0, s27, 0x10000
	s_nop 0
	global_load_lds_dwordx4 v3, s[0:1]
	v_mov_b32_e32 v3, v184
	s_add_i32 m0, s27, 0x12000
	s_nop 0
	global_load_lds_dwordx4 v3, s[0:1]
	s_add_u32 s0, s16, 0x80000
	s_addc_u32 s1, s17, 0
	v_mov_b32_e32 v3, v162
	s_add_i32 m0, s27, 0x14000
	s_add_i32 s28, s27, 0x2000
	global_load_lds_dwordx4 v3, s[0:1]
	v_mov_b32_e32 v3, v184
	s_add_i32 m0, s27, 0x16000
	s_add_i32 s29, s27, 0x4000
	global_load_lds_dwordx4 v3, s[0:1]
	v_readlane_b32 s0, v242, 14
	v_readlane_b32 s1, v242, 15
	v_mov_b32_e32 v3, v1
	s_mov_b32 m0, s27
	s_add_i32 s33, s27, 0x6000
	s_nop 1
	global_load_lds_dwordx4 v3, s[0:1]
	v_mov_b32_e32 v3, v164
	s_mov_b32 m0, s28
	s_cmp_eq_u32 s3, 1
	global_load_lds_dwordx4 v3, s[0:1]
	v_readlane_b32 s0, v242, 12
	v_readlane_b32 s1, v242, 13
	v_mov_b32_e32 v3, v1
	s_mov_b32 m0, s29
	s_nop 2
	global_load_lds_dwordx4 v3, s[0:1]
	v_mov_b32_e32 v3, v164
	s_mov_b32 m0, s33
	s_nop 0
	global_load_lds_dwordx4 v3, s[0:1]
	s_cselect_b64 s[0:1], -1, 0
	s_cmp_lg_u32 s3, 1
	s_cbranch_scc1 .LBB0_628
.LBB0_628:
	v_readlane_b32 s6, v241, 48
	s_mul_hi_u32 s5, s6, 0x16000
	s_mul_i32 s6, s6, 0x16000
	v_readlane_b32 s7, v242, 1
	s_add_u32 s34, s7, s6
	v_readlane_b32 s6, v242, 2
	s_addc_u32 s35, s6, s5
	s_lshl_b32 s4, s4, 5
	s_and_b32 s7, s4, 0x60
	s_lshl_b32 s6, s3, 13
	s_lshl_b32 s8, s7, 7
	s_add_u32 s4, s16, 0x80
	s_addc_u32 s5, s17, 0
	v_mov_b32_e32 v3, v162
	s_waitcnt vmcnt(2)
	s_barrier
	s_add_i32 m0, s27, 0x18000
	s_add_i32 s38, s27, 0x8000
	global_load_lds_dwordx4 v3, s[4:5]
	v_mov_b32_e32 v3, v184
	s_add_i32 m0, s27, 0x1a000
	s_add_i32 s39, s27, 0xa000
	global_load_lds_dwordx4 v3, s[4:5]
	v_readlane_b32 s4, v242, 16
	v_readlane_b32 s5, v242, 17
	v_mov_b32_e32 v3, v1
	s_mov_b32 m0, s38
	v_lshrrev_b32_e32 v4, 1, v2
	s_nop 1
	global_load_lds_dwordx4 v3, s[4:5]
	v_mov_b32_e32 v3, v164
	s_mov_b32 m0, s39
	v_and_b32_e32 v4, 24, v4
	global_load_lds_dwordx4 v3, s[4:5]
	s_add_u32 s4, s16, 0x80080
	s_addc_u32 s5, s17, 0
	v_mov_b32_e32 v3, v162
	s_add_i32 m0, s27, 0x1c000
	v_lshlrev_b32_e32 v5, 1, v4
	global_load_lds_dwordx4 v3, s[4:5]
	v_mov_b32_e32 v3, v184
	s_add_i32 m0, s27, 0x1e000
	s_cmpk_lt_u32 s2, 0x100
	global_load_lds_dwordx4 v3, s[4:5]
	v_and_b32_e32 v3, 15, v2
	v_lshlrev_b32_e32 v2, 2, v2
	v_lshl_or_b32 v185, s3, 6, v3
	v_lshl_or_b32 v3, v3, 6, v5
	v_and_b32_e32 v2, 32, v2
	s_waitcnt vmcnt(6)
	v_bitop3_b32 v5, v3, s6, v2 bitop3:0xde
	v_readlane_b32 s4, v242, 10
	v_readlane_b32 s14, v242, 14
	v_bitop3_b32 v186, v3, s8, v2 bitop3:0xde
	s_cselect_b64 s[2:3], -1, 0
	v_or_b32_e32 v187, s7, v4
	s_mov_b32 s40, 0
	v_add_u32_e32 v188, 0, v5
	s_lshl_b32 s46, s7, 2
	v_lshlrev_b32_e32 v189, 2, v4
	v_readlane_b32 s47, v242, 6
	s_mov_b32 s48, s4
	v_readlane_b32 s15, v242, 15
	s_barrier
	v_readlane_b32 s5, v242, 11
	s_branch .LBB0_631

; #define PG8_STAGE(bufoff, gbase, voff) do { const char* gb_ = (const char*)(gbase); asm volatile("" : "+s"(gb_)); _Pragma("unroll") for (int _i = 0; _i < 2; ++_i) { unsigned vo_ = (voff)[_i]; asm volatile("" : "+v"(vo_));        \
;         __builtin_amdgcn_global_load_lds((const unsigned*)(gb_ + vo_), (PG8_LAS unsigned*)(lds + (bufoff) + ldsw + _i * 8192), 16, 0, 0); } } while (0)
; #define PG8_LDA(dst, b, h) do { _Pragma("unroll") for (int m = 0; m < 4; ++m) _Pragma("unroll") for (int k = 0; k < 2; ++k) dst[m][k] = *(const PG8_LAS bf16x8*)(lds + PG8_SA(b, h) + aoff + m * 2048 + k * 1024); } while (0)
; #define PG8_LDB(dst, b, h) do { _Pragma("unroll") for (int n = 0; n < 2; ++n) _Pragma("unroll") for (int k = 0; k < 2; ++k) dst[n][k] = *(const PG8_LAS bf16x8*)(lds + PG8_SB(b, h) + boff + n * 2048 + k * 1024); } while (0)
; #define PG8_MMA(ai, bj, At, Bt) do { __builtin_amdgcn_s_setprio(1); _Pragma("unroll") for (int m = 0; m < 4; ++m) _Pragma("unroll") for (int n = 0; n < 2; ++n) _Pragma("unroll") for (int k = 0; k < 2; ++k) \
;         acc[ai][bj][m][n] = __builtin_amdgcn_mfma_f32_16x16x32_bf16(Bt[n][k], At[m][k], acc[ai][bj][m][n], 0, 0, 0); __builtin_amdgcn_s_setprio(0); } while (0)
; #define PG8_WAIT_V(n) asm volatile("s_waitcnt vmcnt(" #n ")" ::: "memory")
; #define PG8_WAIT_L(n) asm volatile("s_waitcnt lgkmcnt(" #n ")" ::: "memory")
; #define PG8_BAR __builtin_amdgcn_s_barrier()
; #define PG8_SCHED __builtin_amdgcn_sched_barrier(0)
; template <class Epi, class Sched, bool ALIGN_EPI = false, bool SP2 = false>
; __device__ __forceinline__ void gemm_phase(PG8_LAS unsigned char* lds, const Gemm g, const Sched& S, const Epi& E) {
;     ...
;             PG8_LDB(B0, 0, 0); PG8_LDB(B1, 0, 1); PG8_SCHED; PG8_LDA(At, 0, 0); PG8_STAGE(PG8_SA(1, 1), a1 + hstep, voffA);
;             PG8_WAIT_V(8); PG8_WAIT_L(0); PG8_BAR; PG8_MMA(0, 0, At, B0); PG8_MMA(0, 1, At, B1); PG8_BAR; PG8_SCHED;
.LBB0_634:
	s_add_u32 s16, s14, 0x100
	s_addc_u32 s17, s15, 0
	s_cmp_eq_u32 s53, 28
	s_cselect_b32 s22, s49, s16
	s_cselect_b32 s23, s7, s17
	s_cselect_b32 s20, s50, s51
	s_cselect_b32 s21, s5, s52
	s_add_u32 s18, s22, 0x80
	s_addc_u32 s19, s23, 0
	s_add_i32 s54, 0, 0x10000
	s_add_i32 s55, 0, 0x14000
	ds_read_b128 v[82:85], v244
	ds_read_b128 v[86:89], v244 offset:1024
	ds_read_b128 v[90:93], v244 offset:2048
	ds_read_b128 v[94:97], v244 offset:3072
	ds_read_b128 v[146:149], v244 offset:16384
	ds_read_b128 v[150:153], v244 offset:17408
	ds_read_b128 v[154:157], v244 offset:18432
	ds_read_b128 v[158:161], v244 offset:19456
	s_add_u32 s14, s14, 0x80080
	s_addc_u32 s15, s15, 0
	ds_read_b128 v[178:181], v188
	ds_read_b128 v[190:193], v188 offset:1024
	ds_read_b128 v[194:197], v188 offset:2048
	ds_read_b128 v[198:201], v188 offset:3072
	ds_read_b128 v[202:205], v188 offset:4096
	ds_read_b128 v[206:209], v188 offset:5120
	ds_read_b128 v[210:213], v188 offset:6144
	ds_read_b128 v[220:223], v188 offset:7168
	s_add_i32 m0, s27, 0xc000
	s_nop 0
	global_load_lds_dwordx4 v1, s[14:15]
	s_add_i32 m0, s27, 0xe000
	s_nop 0
	global_load_lds_dwordx4 v164, s[14:15]
	s_waitcnt vmcnt(8)
	s_waitcnt lgkmcnt(0)
	s_cmp_lg_u32 s98, 0
	s_cbranch_scc1 .Lhb_16
	s_barrier
.Lhb_16:
	s_setprio 1
	s_waitcnt lgkmcnt(0)
	v_mfma_f32_16x16x32_bf16 v[142:145], v[82:85], v[178:181], v[142:145]
	v_mfma_f32_16x16x32_bf16 v[142:145], v[86:89], v[190:193], v[142:145]
	v_mfma_f32_16x16x32_bf16 v[126:129], v[82:85], v[194:197], v[126:129]
	v_mfma_f32_16x16x32_bf16 v[126:129], v[86:89], v[198:201], v[126:129]
	v_mfma_f32_16x16x32_bf16 v[110:113], v[82:85], v[202:205], v[110:113]
	v_mfma_f32_16x16x32_bf16 v[110:113], v[86:89], v[206:209], v[110:113]
	v_mfma_f32_16x16x32_bf16 v[78:81], v[82:85], v[210:213], v[78:81]
	v_mfma_f32_16x16x32_bf16 v[78:81], v[86:89], v[220:223], v[78:81]
	v_mfma_f32_16x16x32_bf16 v[138:141], v[90:93], v[178:181], v[138:141]
	v_mfma_f32_16x16x32_bf16 v[138:141], v[94:97], v[190:193], v[138:141]
	v_mfma_f32_16x16x32_bf16 v[122:125], v[90:93], v[194:197], v[122:125]
	v_mfma_f32_16x16x32_bf16 v[122:125], v[94:97], v[198:201], v[122:125]
	v_mfma_f32_16x16x32_bf16 v[106:109], v[90:93], v[202:205], v[106:109]
	v_mfma_f32_16x16x32_bf16 v[106:109], v[94:97], v[206:209], v[106:109]
	v_mfma_f32_16x16x32_bf16 v[74:77], v[90:93], v[210:213], v[74:77]
	v_mfma_f32_16x16x32_bf16 v[74:77], v[94:97], v[220:223], v[74:77]
	s_setprio 0
	s_setprio 1
	v_mfma_f32_16x16x32_bf16 v[134:137], v[146:149], v[178:181], v[134:137]
	v_mfma_f32_16x16x32_bf16 v[134:137], v[150:153], v[190:193], v[134:137]
	v_mfma_f32_16x16x32_bf16 v[118:121], v[146:149], v[194:197], v[118:121]
	v_mfma_f32_16x16x32_bf16 v[118:121], v[150:153], v[198:201], v[118:121]
	v_mfma_f32_16x16x32_bf16 v[102:105], v[146:149], v[202:205], v[102:105]
	v_mfma_f32_16x16x32_bf16 v[102:105], v[150:153], v[206:209], v[102:105]
	v_mfma_f32_16x16x32_bf16 v[70:73], v[146:149], v[210:213], v[70:73]
	v_mfma_f32_16x16x32_bf16 v[70:73], v[150:153], v[220:223], v[70:73]
	v_mfma_f32_16x16x32_bf16 v[130:133], v[154:157], v[178:181], v[130:133]
	v_mfma_f32_16x16x32_bf16 v[130:133], v[158:161], v[190:193], v[130:133]
	v_mfma_f32_16x16x32_bf16 v[114:117], v[154:157], v[194:197], v[114:117]
	v_mfma_f32_16x16x32_bf16 v[114:117], v[158:161], v[198:201], v[114:117]
	v_mfma_f32_16x16x32_bf16 v[98:101], v[154:157], v[202:205], v[98:101]
	v_mfma_f32_16x16x32_bf16 v[98:101], v[158:161], v[206:209], v[98:101]
	v_mfma_f32_16x16x32_bf16 v[66:69], v[154:157], v[210:213], v[66:69]
	v_mfma_f32_16x16x32_bf16 v[66:69], v[158:161], v[220:223], v[66:69]
	s_setprio 0
	s_cmp_eq_u32 s98, 0
	s_cbranch_scc1 .Lhb_17
	s_barrier
; #define PG8_STAGE(bufoff, gbase, voff) do { const char* gb_ = (const char*)(gbase); asm volatile("" : "+s"(gb_)); _Pragma("unroll") for (int _i = 0; _i < 2; ++_i) { unsigned vo_ = (voff)[_i]; asm volatile("" : "+v"(vo_));        \
;         __builtin_amdgcn_global_load_lds((const unsigned*)(gb_ + vo_), (PG8_LAS unsigned*)(lds + (bufoff) + ldsw + _i * 8192), 16, 0, 0); } } while (0)
; #define PG8_LDA(dst, b, h) do { _Pragma("unroll") for (int m = 0; m < 4; ++m) _Pragma("unroll") for (int k = 0; k < 2; ++k) dst[m][k] = *(const PG8_LAS bf16x8*)(lds + PG8_SA(b, h) + aoff + m * 2048 + k * 1024); } while (0)
; #define PG8_LDB(dst, b, h) do { _Pragma("unroll") for (int n = 0; n < 2; ++n) _Pragma("unroll") for (int k = 0; k < 2; ++k) dst[n][k] = *(const PG8_LAS bf16x8*)(lds + PG8_SB(b, h) + boff + n * 2048 + k * 1024); } while (0)
; #define PG8_MMA(ai, bj, At, Bt) do { __builtin_amdgcn_s_setprio(1); _Pragma("unroll") for (int m = 0; m < 4; ++m) _Pragma("unroll") for (int n = 0; n < 2; ++n) _Pragma("unroll") for (int k = 0; k < 2; ++k) \
;         acc[ai][bj][m][n] = __builtin_amdgcn_mfma_f32_16x16x32_bf16(Bt[n][k], At[m][k], acc[ai][bj][m][n], 0, 0, 0); __builtin_amdgcn_s_setprio(0); } while (0)
; #define PG8_WAIT_V(n) asm volatile("s_waitcnt vmcnt(" #n ")" ::: "memory")
; #define PG8_WAIT_L(n) asm volatile("s_waitcnt lgkmcnt(" #n ")" ::: "memory")
; #define PG8_BAR __builtin_amdgcn_s_barrier()
; #define PG8_SCHED __builtin_amdgcn_sched_barrier(0)
; template <class Epi, class Sched, bool ALIGN_EPI = false, bool SP2 = false>
; __device__ __forceinline__ void gemm_phase(PG8_LAS unsigned char* lds, const Gemm g, const Sched& S, const Epi& E) {
;     ...
;             PG8_LDA(At, 0, 1); PG8_STAGE(PG8_SB(0, 0), b2, voffB); PG8_STAGE(PG8_SB(0, 1), b2 + hstep, voffB); PG8_STAGE(PG8_SA(0, 0), a2, voffA);
;             PG8_WAIT_V(8); PG8_WAIT_L(0); PG8_BAR; PG8_MMA(1, 0, At, B0); PG8_MMA(1, 1, At, B1); PG8_BAR; PG8_SCHED;
;             PG8_LDB(B0, 1, 0); PG8_LDB(B1, 1, 1); PG8_SCHED; PG8_LDA(At, 1, 0); PG8_STAGE(PG8_SA(0, 1), a2 + hstep, voffA);
.Lhb_17:
	s_mov_b64 s[14:15], s[20:21]
	s_add_i32 s54, s54, s26
	ds_read_b128 v[178:181], v188 offset:16384
	ds_read_b128 v[190:193], v188 offset:17408
	ds_read_b128 v[194:197], v188 offset:18432
	ds_read_b128 v[198:201], v188 offset:19456
	ds_read_b128 v[202:205], v188 offset:20480
	ds_read_b128 v[206:209], v188 offset:21504
	ds_read_b128 v[210:213], v188 offset:22528
	ds_read_b128 v[220:223], v188 offset:23552
	s_mov_b32 m0, s54
	s_nop 0
	global_load_lds_dwordx4 v162, s[14:15]
	s_add_i32 m0, s54, 0x2000
	s_nop 0
	global_load_lds_dwordx4 v184, s[14:15]
	s_add_u32 s14, s20, 0x80000
	s_addc_u32 s15, s21, 0
	s_add_i32 s54, s55, s26
	s_mov_b32 m0, s54
	s_nop 0
	global_load_lds_dwordx4 v162, s[14:15]
	s_add_i32 m0, s54, 0x2000
	s_nop 0
	global_load_lds_dwordx4 v184, s[14:15]
	s_mov_b64 s[14:15], s[22:23]
	s_mov_b32 m0, s27
	s_nop 0
	global_load_lds_dwordx4 v1, s[14:15]
	s_mov_b32 m0, s28
	s_nop 0
	global_load_lds_dwordx4 v164, s[14:15]
	s_waitcnt vmcnt(8)
	s_waitcnt lgkmcnt(0)
	s_cmp_lg_u32 s98, 0
	s_cbranch_scc1 .Lhb_18
	s_barrier
.Lhb_18:
	s_setprio 1
	s_waitcnt lgkmcnt(0)
	v_mfma_f32_16x16x32_bf16 v[62:65], v[82:85], v[178:181], v[62:65]
	v_mfma_f32_16x16x32_bf16 v[62:65], v[86:89], v[190:193], v[62:65]
	v_mfma_f32_16x16x32_bf16 v[46:49], v[82:85], v[194:197], v[46:49]
	v_mfma_f32_16x16x32_bf16 v[46:49], v[86:89], v[198:201], v[46:49]
	v_mfma_f32_16x16x32_bf16 v[30:33], v[82:85], v[202:205], v[30:33]
	v_mfma_f32_16x16x32_bf16 v[30:33], v[86:89], v[206:209], v[30:33]
	v_mfma_f32_16x16x32_bf16 v[14:17], v[82:85], v[210:213], v[14:17]
	v_mfma_f32_16x16x32_bf16 v[14:17], v[86:89], v[220:223], v[14:17]
	v_mfma_f32_16x16x32_bf16 v[58:61], v[90:93], v[178:181], v[58:61]
	v_mfma_f32_16x16x32_bf16 v[58:61], v[94:97], v[190:193], v[58:61]
	v_mfma_f32_16x16x32_bf16 v[42:45], v[90:93], v[194:197], v[42:45]
	v_mfma_f32_16x16x32_bf16 v[42:45], v[94:97], v[198:201], v[42:45]
	v_mfma_f32_16x16x32_bf16 v[26:29], v[90:93], v[202:205], v[26:29]
	v_mfma_f32_16x16x32_bf16 v[26:29], v[94:97], v[206:209], v[26:29]
	v_mfma_f32_16x16x32_bf16 v[10:13], v[90:93], v[210:213], v[10:13]
	v_mfma_f32_16x16x32_bf16 v[10:13], v[94:97], v[220:223], v[10:13]
	s_setprio 0
	s_setprio 1
	v_mfma_f32_16x16x32_bf16 v[54:57], v[146:149], v[178:181], v[54:57]
	v_mfma_f32_16x16x32_bf16 v[54:57], v[150:153], v[190:193], v[54:57]
	v_mfma_f32_16x16x32_bf16 v[38:41], v[146:149], v[194:197], v[38:41]
	v_mfma_f32_16x16x32_bf16 v[38:41], v[150:153], v[198:201], v[38:41]
	v_mfma_f32_16x16x32_bf16 v[22:25], v[146:149], v[202:205], v[22:25]
	v_mfma_f32_16x16x32_bf16 v[22:25], v[150:153], v[206:209], v[22:25]
	v_mfma_f32_16x16x32_bf16 v[6:9], v[146:149], v[210:213], v[6:9]
	v_mfma_f32_16x16x32_bf16 v[6:9], v[150:153], v[220:223], v[6:9]
	v_mfma_f32_16x16x32_bf16 v[50:53], v[154:157], v[178:181], v[50:53]
	v_mfma_f32_16x16x32_bf16 v[50:53], v[158:161], v[190:193], v[50:53]
	v_mfma_f32_16x16x32_bf16 v[34:37], v[154:157], v[194:197], v[34:37]
	v_mfma_f32_16x16x32_bf16 v[34:37], v[158:161], v[198:201], v[34:37]
	v_mfma_f32_16x16x32_bf16 v[18:21], v[154:157], v[202:205], v[18:21]
	v_mfma_f32_16x16x32_bf16 v[18:21], v[158:161], v[206:209], v[18:21]
	v_mfma_f32_16x16x32_bf16 v[2:5], v[154:157], v[210:213], v[2:5]
	v_mfma_f32_16x16x32_bf16 v[2:5], v[158:161], v[220:223], v[2:5]
	s_setprio 0
	s_cmp_eq_u32 s98, 0
	s_cbranch_scc1 .Lhb_19
	s_barrier
.Lhb_19:
	s_add_i32 s54, 0, 0x18000
	s_add_i32 s55, 0, 0x1c000
	ds_read_b128 v[82:85], v244 offset:32768
	ds_read_b128 v[86:89], v244 offset:33792
	ds_read_b128 v[90:93], v244 offset:34816
	ds_read_b128 v[94:97], v244 offset:35840
	ds_read_b128 v[146:149], v244 offset:49152
	ds_read_b128 v[150:153], v244 offset:50176
	ds_read_b128 v[154:157], v244 offset:51200
	ds_read_b128 v[158:161], v244 offset:52224
	s_add_u32 s14, s22, 0x80000
	s_addc_u32 s15, s23, 0
	s_mov_b32 m0, s29
	ds_read_b128 v[178:181], v188 offset:32768
	ds_read_b128 v[190:193], v188 offset:33792
	ds_read_b128 v[194:197], v188 offset:34816
	ds_read_b128 v[198:201], v188 offset:35840
	ds_read_b128 v[202:205], v188 offset:36864
	ds_read_b128 v[206:209], v188 offset:37888
	ds_read_b128 v[210:213], v188 offset:38912
	ds_read_b128 v[220:223], v188 offset:39936
	s_nop 0
	global_load_lds_dwordx4 v1, s[14:15]
	s_mov_b32 m0, s33
	s_nop 0
	global_load_lds_dwordx4 v164, s[14:15]
	s_waitcnt vmcnt(8)
	s_waitcnt lgkmcnt(0)
	s_cmp_lg_u32 s98, 0
	s_cbranch_scc1 .Lhb_20
	s_barrier

; #define PG8_STAGE(bufoff, gbase, voff) do { const char* gb_ = (const char*)(gbase); asm volatile("" : "+s"(gb_)); _Pragma("unroll") for (int _i = 0; _i < 2; ++_i) { unsigned vo_ = (voff)[_i]; asm volatile("" : "+v"(vo_));        \
;         __builtin_amdgcn_global_load_lds((const unsigned*)(gb_ + vo_), (PG8_LAS unsigned*)(lds + (bufoff) + ldsw + _i * 8192), 16, 0, 0); } } while (0)
; #define PG8_LDA(dst, b, h) do { _Pragma("unroll") for (int m = 0; m < 4; ++m) _Pragma("unroll") for (int k = 0; k < 2; ++k) dst[m][k] = *(const PG8_LAS bf16x8*)(lds + PG8_SA(b, h) + aoff + m * 2048 + k * 1024); } while (0)
; template <class Epi, class Sched, bool ALIGN_EPI = false, bool SP2 = false>
; __device__ __forceinline__ void gemm_phase(PG8_LAS unsigned char* lds, const Gemm g, const Sched& S, const Epi& E) {
;     ...
;             PG8_LDA(At, 1, 1); PG8_STAGE(PG8_SB(1, 0), b3, voffB); PG8_STAGE(PG8_SB(1, 1), b3 + hstep, voffB); PG8_STAGE(PG8_SA(1, 0), a3, voffA);
.Lhb_21:
	s_add_u32 s14, s20, 0x80
	s_addc_u32 s15, s21, 0
	s_add_i32 s22, s54, s26
	ds_read_b128 v[178:181], v188 offset:49152
	ds_read_b128 v[190:193], v188 offset:50176
	ds_read_b128 v[194:197], v188 offset:51200
	ds_read_b128 v[198:201], v188 offset:52224
	ds_read_b128 v[202:205], v188 offset:53248
	ds_read_b128 v[206:209], v188 offset:54272
	ds_read_b128 v[210:213], v188 offset:55296
	ds_read_b128 v[220:223], v188 offset:56320
	s_mov_b32 m0, s22
	s_nop 0
	global_load_lds_dwordx4 v162, s[14:15]
	s_add_i32 m0, s22, 0x2000
	s_nop 0
	global_load_lds_dwordx4 v184, s[14:15]
	s_add_u32 s14, s20, 0x80080
	s_addc_u32 s15, s21, 0
	s_add_i32 s20, s55, s26
	s_mov_b32 m0, s20
	s_nop 0
	global_load_lds_dwordx4 v162, s[14:15]
	s_add_i32 m0, s20, 0x2000
	s_nop 0
	global_load_lds_dwordx4 v184, s[14:15]
	s_mov_b32 m0, s38
	s_nop 0
	global_load_lds_dwordx4 v1, s[18:19]
	s_mov_b32 m0, s39
	s_nop 0
	global_load_lds_dwordx4 v164, s[18:19]
	s_waitcnt vmcnt(8)
	s_waitcnt lgkmcnt(0)
	s_cmp_lg_u32 s98, 0
	s_cbranch_scc1 .Lhb_22
	s_barrier

; __device__ __forceinline__ unsigned cvt_pk_bf16(float lo, float hi) { unsigned r; asm volatile("v_cvt_pk_bf16_f32 %0, %1, %2" : "=v"(r) : "v"(lo), "v"(hi)); return r; }
; #define PG8_BAR __builtin_amdgcn_s_barrier()
;     __device__ __forceinline__ void operator()(const f32x4 (&acc)[2][2][4][2], const Unit& u, int wr, int wc, int fr, int fq) const {
;         const int row0 = u.pm * BM + wr * 64 + fr, col0 = u.pn * HALF + wc * 32 + 8 * fq;
;         const float* cb = cvec + (size_t)((u.pm * BM) / rows_per_batch) * cstride + u.pn * BM + wc * 32 + 8 * fq;
;         long long sv[2][4];
; #pragma unroll
;         for (int ai = 0; ai < 2; ++ai)
; #pragma unroll
;             for (int m = 0; m < 4; ++m) sv[ai][m] = ss[row0 + ai * HALF + m * 16];
;         f32x4 cg0 = *(const f32x4*)(cb), cg1 = *(const f32x4*)(cb + 4), cu0 = *(const f32x4*)(cb + HALF), cu1 = *(const f32x4*)(cb + HALF + 4);
;         asm volatile("" : "+v"(sv[0][0]), "+v"(sv[0][1]), "+v"(sv[0][2]), "+v"(sv[0][3]), "+v"(sv[1][0]), "+v"(sv[1][1]), "+v"(sv[1][2]), "+v"(sv[1][3]), "+v"(cg0), "+v"(cg1), "+v"(cu0), "+v"(cu1));
; #pragma unroll
;         for (int ai = 0; ai < 2; ++ai)
; #pragma unroll
;             for (int m = 0; m < 4; ++m) { bf16_t* rowp = Hd + (size_t)(row0 + ai * HALF + m * 16) * ldh + col0;
;                 const float rstd = __builtin_amdgcn_rsqf((float)sv[ai][m] * (SS_INV * (1.0f / 2048.0f)) + RMS_EPS);
;                 const f32x4 ga = acc[ai][0][m][0] * rstd + cg0, gb = acc[ai][0][m][1] * rstd + cg1, ua = acc[ai][1][m][0] * rstd + cu0, ub = acc[ai][1][m][1] * rstd + cu1;
;                 const f32x4 v0 = fsilu4(ga) * ua, v1 = fsilu4(gb) * ub;
;                 u32x4 w; w.x = cvt_pk_bf16(v0[0], v0[1]); w.y = cvt_pk_bf16(v0[2], v0[3]); w.z = cvt_pk_bf16(v1[0], v1[1]); w.w = cvt_pk_bf16(v1[2], v1[3]);
;                 *(u32x4*)rowp = w; }
; template <class Epi, class Sched, bool ALIGN_EPI = false, bool SP2 = false>
; __device__ __forceinline__ void gemm_phase(PG8_LAS unsigned char* lds, const Gemm g, const Sched& S, const Epi& E) {
;     ...
;         if constexpr (ALIGN_EPI) { if (wr == 0) PG8_BAR; }
.Lhb_23:
	s_add_i32 s53, s53, 2
	s_add_u32 s51, s51, 0x100
	s_addc_u32 s52, s52, 0
	s_cmp_gt_u32 s53, 29
	s_mov_b64 s[14:15], s[16:17]
	s_cbranch_scc0 .LBB0_634
	s_and_b64 vcc, exec, s[2:3]
	s_cbranch_vccz .LBB0_637
.LBB0_637:
	s_ashr_i32 s5, s48, 31
	s_lshr_b32 s5, s5, 27
	s_add_i32 s5, s48, s5
	s_ashr_i32 s5, s5, 5
	s_lshl_b32 s14, s47, 8
	s_ashr_i32 s15, s14, 31
	s_mul_hi_i32 s7, s5, 0xb000
	s_mul_i32 s5, s5, 0xb000
	v_lshl_add_u32 v150, s48, 8, v185
	s_add_u32 s5, s34, s5
	v_or_b32_e32 v194, 16, v150
	s_addc_u32 s7, s35, s7
	s_lshl_b64 s[14:15], s[14:15], 2
	v_ashrrev_i32_e32 v151, 31, v150
	v_ashrrev_i32_e32 v195, 31, v194
	v_or_b32_e32 v180, 32, v150
	s_add_u32 s5, s5, s14
	v_lshl_add_u64 v[82:83], v[150:151], 3, s[42:43]
	v_lshl_add_u64 v[84:85], v[194:195], 3, s[42:43]
	v_ashrrev_i32_e32 v181, 31, v180
	v_or_b32_e32 v160, 48, v150
	s_addc_u32 s7, s7, s15
	global_load_dwordx2 v[182:183], v[84:85], off
	global_load_dwordx2 v[146:147], v[82:83], off offset:1408
	v_lshl_add_u64 v[84:85], v[180:181], 3, s[42:43]
	v_ashrrev_i32_e32 v161, 31, v160
	s_add_u32 s14, s5, s46
	global_load_dwordx2 v[178:179], v[84:85], off
	v_lshl_add_u64 v[84:85], v[160:161], 3, s[42:43]
	s_addc_u32 s15, s7, 0
	global_load_dwordx2 v[192:193], v[82:83], off
	global_load_dwordx2 v[156:157], v[82:83], off offset:1024
	global_load_dwordx2 v[154:155], v[82:83], off offset:1152
	global_load_dwordx2 v[152:153], v[82:83], off offset:1280
	global_load_dwordx2 v[158:159], v[84:85], off
	global_load_dwordx4 v[90:93], v189, s[14:15] offset:16
	global_load_dwordx4 v[94:97], v189, s[14:15]
	s_nop 0
	global_load_dwordx4 v[82:85], v189, s[14:15] offset:528
	global_load_dwordx4 v[86:89], v189, s[14:15] offset:512
	v_readlane_b32 s14, v242, 40
	v_lshl_or_b32 v196, s47, 7, v187
	v_readlane_b32 s15, v242, 41
	v_ashrrev_i32_e32 v197, 31, v196
	s_movk_i32 s5, 0x2c00
	v_mov_b64_e32 v[148:149], s[14:15]
	v_add_u32_e32 v191, 0x80, v150
	v_add_u32_e32 v190, 0x90, v150
	v_add_u32_e32 v181, 0xa0, v150
	v_add_u32_e32 v161, 0xb0, v150
	v_mad_i64_i32 v[198:199], s[14:15], v150, s5, v[148:149]
	v_lshlrev_b64 v[150:151], 1, v[196:197]
	v_lshl_add_u64 v[196:197], v[198:199], 0, v[150:151]
	s_mov_b32 s16, 0xbfb8aa3b
	s_andn2_b64 vcc, exec, s[12:13]
	s_movk_i32 s49, 0x3000
	v_readlane_b32 s50, v241, 17
	s_mov_b32 s51, 0xd800000
	s_waitcnt vmcnt(0)
	s_nop 0
	v_xor_b32_e32 v195, v192, v193
	v_ashrrev_i32_e32 v195, 31, v195
	v_ffbh_i32_e32 v198, v193
	v_add_u32_e32 v195, 32, v195
	v_add_u32_e32 v198, -1, v198
	v_min_u32_e32 v195, v198, v195
	v_lshlrev_b64 v[192:193], v195, v[192:193]
	v_min_u32_e32 v192, 1, v192
	v_or_b32_e32 v192, v193, v192
	v_cvt_f32_i32_e32 v192, v192
	v_sub_u32_e32 v193, 32, v195
	v_ldexp_f32 v192, v192, v193
	v_fmamk_f32 v192, v192, 0x32000000, v216
	v_rsq_f32_e32 v192, v192
	s_nop 0
	v_pk_fma_f32 v[142:143], v[142:143], v[192:193], v[94:95] op_sel_hi:[1,0,1]
	v_pk_fma_f32 v[144:145], v[144:145], v[192:193], v[96:97] op_sel_hi:[1,0,1]
	v_pk_fma_f32 v[138:139], v[138:139], v[192:193], v[90:91] op_sel_hi:[1,0,1]
	v_pk_fma_f32 v[140:141], v[140:141], v[192:193], v[92:93] op_sel_hi:[1,0,1]
	v_pk_fma_f32 v[134:135], v[134:135], v[192:193], v[86:87] op_sel_hi:[1,0,1]
	v_pk_fma_f32 v[136:137], v[136:137], v[192:193], v[88:89] op_sel_hi:[1,0,1]
	v_pk_fma_f32 v[130:131], v[130:131], v[192:193], v[82:83] op_sel_hi:[1,0,1]
	v_pk_fma_f32 v[132:133], v[132:133], v[192:193], v[84:85] op_sel_hi:[1,0,1]
	v_pk_mul_f32 v[192:193], v[144:145], s[16:17] op_sel_hi:[1,0]
	v_pk_mul_f32 v[198:199], v[142:143], s[16:17] op_sel_hi:[1,0]
	v_exp_f32_e32 v192, v192
	v_exp_f32_e32 v198, v198
	v_exp_f32_e32 v199, v199
	v_exp_f32_e32 v193, v193
	v_pk_add_f32 v[198:199], v[198:199], 1.0 op_sel_hi:[1,0]
	v_pk_add_f32 v[192:193], v[192:193], 1.0 op_sel_hi:[1,0]
	v_rcp_f32_e32 v198, v198
	v_rcp_f32_e32 v199, v199
	v_rcp_f32_e32 v192, v192
	v_rcp_f32_e32 v193, v193
	v_pk_mul_f32 v[142:143], v[142:143], v[198:199]
	s_nop 0
	v_pk_mul_f32 v[134:135], v[134:135], v[142:143]
	v_pk_mul_f32 v[144:145], v[144:145], v[192:193]
	v_pk_mul_f32 v[142:143], v[140:141], s[16:17] op_sel_hi:[1,0]
	v_pk_mul_f32 v[136:137], v[136:137], v[144:145]
	v_pk_mul_f32 v[144:145], v[138:139], s[16:17] op_sel_hi:[1,0]
	v_exp_f32_e32 v142, v142
	v_exp_f32_e32 v144, v144
	v_exp_f32_e32 v145, v145
	v_exp_f32_e32 v143, v143
	v_pk_add_f32 v[144:145], v[144:145], 1.0 op_sel_hi:[1,0]
	v_pk_add_f32 v[142:143], v[142:143], 1.0 op_sel_hi:[1,0]
	v_rcp_f32_e32 v144, v144
	v_rcp_f32_e32 v145, v145
	v_rcp_f32_e32 v142, v142
	v_rcp_f32_e32 v143, v143
	v_pk_mul_f32 v[138:139], v[138:139], v[144:145]
	v_pk_mul_f32 v[140:141], v[140:141], v[142:143]
	s_nop 0
	v_pk_mul_f32 v[140:141], v[132:133], v[140:141]
	v_pk_mul_f32 v[132:133], v[130:131], v[138:139]
	v_cvt_pk_bf16_f32 v130, v134, v135
	v_cvt_pk_bf16_f32 v131, v136, v137
	s_nop 0
	v_cvt_pk_bf16_f32 v132, v132, v133
	v_cvt_pk_bf16_f32 v133, v140, v141
	global_store_dwordx4 v[196:197], v[130:133], off
	s_nop 1
	v_xor_b32_e32 v132, v182, v183
	v_ashrrev_i32_e32 v132, 31, v132
	v_ffbh_i32_e32 v133, v183
	v_add_u32_e32 v132, 32, v132
	v_add_u32_e32 v133, -1, v133
	v_min_u32_e32 v134, v133, v132
	v_lshlrev_b64 v[132:133], v134, v[182:183]
	v_min_u32_e32 v132, 1, v132
	v_or_b32_e32 v132, v133, v132
	v_cvt_f32_i32_e32 v132, v132
	v_sub_u32_e32 v133, 32, v134
	v_mad_i64_i32 v[130:131], s[14:15], v194, s5, v[148:149]
	v_ldexp_f32 v132, v132, v133
	v_fmamk_f32 v132, v132, 0x32000000, v216
	v_rsq_f32_e32 v132, v132
	v_lshl_add_u64 v[130:131], v[130:131], 0, v[150:151]
	v_pk_fma_f32 v[126:127], v[126:127], v[132:133], v[94:95] op_sel_hi:[1,0,1]
	v_pk_fma_f32 v[128:129], v[128:129], v[132:133], v[96:97] op_sel_hi:[1,0,1]
; __device__ __forceinline__ unsigned cvt_pk_bf16(float lo, float hi) { unsigned r; asm volatile("v_cvt_pk_bf16_f32 %0, %1, %2" : "=v"(r) : "v"(lo), "v"(hi)); return r; }
;     __device__ __forceinline__ void operator()(const f32x4 (&acc)[2][2][4][2], const Unit& u, int wr, int wc, int fr, int fq) const {
;     ...
;             for (int m = 0; m < 4; ++m) { bf16_t* rowp = Hd + (size_t)(row0 + ai * HALF + m * 16) * ldh + col0;
;                 const float rstd = __builtin_amdgcn_rsqf((float)sv[ai][m] * (SS_INV * (1.0f / 2048.0f)) + RMS_EPS);
;                 const f32x4 ga = acc[ai][0][m][0] * rstd + cg0, gb = acc[ai][0][m][1] * rstd + cg1, ua = acc[ai][1][m][0] * rstd + cu0, ub = acc[ai][1][m][1] * rstd + cu1;
;                 const f32x4 v0 = fsilu4(ga) * ua, v1 = fsilu4(gb) * ub;
;                 u32x4 w; w.x = cvt_pk_bf16(v0[0], v0[1]); w.y = cvt_pk_bf16(v0[2], v0[3]); w.z = cvt_pk_bf16(v1[0], v1[1]); w.w = cvt_pk_bf16(v1[2], v1[3]);
;                 *(u32x4*)rowp = w; }
	v_pk_fma_f32 v[122:123], v[122:123], v[132:133], v[90:91] op_sel_hi:[1,0,1]
	v_pk_fma_f32 v[124:125], v[124:125], v[132:133], v[92:93] op_sel_hi:[1,0,1]
	v_pk_fma_f32 v[118:119], v[118:119], v[132:133], v[86:87] op_sel_hi:[1,0,1]
	v_pk_fma_f32 v[120:121], v[120:121], v[132:133], v[88:89] op_sel_hi:[1,0,1]
	v_pk_fma_f32 v[114:115], v[114:115], v[132:133], v[82:83] op_sel_hi:[1,0,1]
	v_pk_fma_f32 v[116:117], v[116:117], v[132:133], v[84:85] op_sel_hi:[1,0,1]
	v_pk_mul_f32 v[132:133], v[128:129], s[16:17] op_sel_hi:[1,0]
	v_pk_mul_f32 v[134:135], v[126:127], s[16:17] op_sel_hi:[1,0]
	v_exp_f32_e32 v132, v132
	v_exp_f32_e32 v134, v134
	v_exp_f32_e32 v135, v135
	v_exp_f32_e32 v133, v133
	v_pk_add_f32 v[134:135], v[134:135], 1.0 op_sel_hi:[1,0]
	v_pk_add_f32 v[132:133], v[132:133], 1.0 op_sel_hi:[1,0]
	v_rcp_f32_e32 v134, v134
	v_rcp_f32_e32 v135, v135
	v_rcp_f32_e32 v132, v132
	v_rcp_f32_e32 v133, v133
	v_pk_mul_f32 v[126:127], v[126:127], v[134:135]
	s_nop 0
	v_pk_mul_f32 v[118:119], v[118:119], v[126:127]
	v_pk_mul_f32 v[128:129], v[128:129], v[132:133]
	v_pk_mul_f32 v[126:127], v[124:125], s[16:17] op_sel_hi:[1,0]
	v_pk_mul_f32 v[120:121], v[120:121], v[128:129]
	v_pk_mul_f32 v[128:129], v[122:123], s[16:17] op_sel_hi:[1,0]
	v_exp_f32_e32 v126, v126
	v_exp_f32_e32 v128, v128
	v_exp_f32_e32 v129, v129
	v_exp_f32_e32 v127, v127
	v_pk_add_f32 v[128:129], v[128:129], 1.0 op_sel_hi:[1,0]
	v_pk_add_f32 v[126:127], v[126:127], 1.0 op_sel_hi:[1,0]
	v_rcp_f32_e32 v128, v128
	v_rcp_f32_e32 v129, v129
	v_rcp_f32_e32 v126, v126
	v_rcp_f32_e32 v127, v127
	v_pk_mul_f32 v[122:123], v[122:123], v[128:129]
	v_pk_mul_f32 v[124:125], v[124:125], v[126:127]
	s_nop 0
	v_pk_mul_f32 v[124:125], v[116:117], v[124:125]
	v_pk_mul_f32 v[116:117], v[114:115], v[122:123]
	v_cvt_pk_bf16_f32 v114, v118, v119
	v_cvt_pk_bf16_f32 v115, v120, v121
	s_nop 0
	v_cvt_pk_bf16_f32 v116, v116, v117
	v_cvt_pk_bf16_f32 v117, v124, v125
	global_store_dwordx4 v[130:131], v[114:117], off
	s_nop 1
	v_xor_b32_e32 v116, v178, v179
	v_ashrrev_i32_e32 v116, 31, v116
	v_ffbh_i32_e32 v117, v179
	v_add_u32_e32 v116, 32, v116
	v_add_u32_e32 v117, -1, v117
	v_min_u32_e32 v118, v117, v116
	v_lshlrev_b64 v[116:117], v118, v[178:179]
	v_min_u32_e32 v116, 1, v116
	v_or_b32_e32 v116, v117, v116
	v_cvt_f32_i32_e32 v116, v116
	v_sub_u32_e32 v117, 32, v118
	v_mad_i64_i32 v[114:115], s[14:15], v180, s5, v[148:149]
	v_ldexp_f32 v116, v116, v117
	v_fmamk_f32 v116, v116, 0x32000000, v216
	v_rsq_f32_e32 v116, v116
	v_lshl_add_u64 v[114:115], v[114:115], 0, v[150:151]
	v_pk_fma_f32 v[110:111], v[110:111], v[116:117], v[94:95] op_sel_hi:[1,0,1]
	v_pk_fma_f32 v[112:113], v[112:113], v[116:117], v[96:97] op_sel_hi:[1,0,1]
	v_pk_fma_f32 v[106:107], v[106:107], v[116:117], v[90:91] op_sel_hi:[1,0,1]
	v_pk_fma_f32 v[108:109], v[108:109], v[116:117], v[92:93] op_sel_hi:[1,0,1]
	v_pk_fma_f32 v[102:103], v[102:103], v[116:117], v[86:87] op_sel_hi:[1,0,1]
	v_pk_fma_f32 v[104:105], v[104:105], v[116:117], v[88:89] op_sel_hi:[1,0,1]
	v_pk_fma_f32 v[98:99], v[98:99], v[116:117], v[82:83] op_sel_hi:[1,0,1]
	v_pk_fma_f32 v[100:101], v[100:101], v[116:117], v[84:85] op_sel_hi:[1,0,1]
	v_pk_mul_f32 v[116:117], v[112:113], s[16:17] op_sel_hi:[1,0]
	v_pk_mul_f32 v[118:119], v[110:111], s[16:17] op_sel_hi:[1,0]
	v_exp_f32_e32 v116, v116
	v_exp_f32_e32 v118, v118
	v_exp_f32_e32 v119, v119
	v_exp_f32_e32 v117, v117
	v_pk_add_f32 v[118:119], v[118:119], 1.0 op_sel_hi:[1,0]
	v_pk_add_f32 v[116:117], v[116:117], 1.0 op_sel_hi:[1,0]
	v_rcp_f32_e32 v118, v118
	v_rcp_f32_e32 v119, v119
	v_rcp_f32_e32 v116, v116
	v_rcp_f32_e32 v117, v117
	v_pk_mul_f32 v[110:111], v[110:111], v[118:119]
	s_nop 0
	v_pk_mul_f32 v[102:103], v[102:103], v[110:111]
	v_pk_mul_f32 v[112:113], v[112:113], v[116:117]
	v_pk_mul_f32 v[110:111], v[108:109], s[16:17] op_sel_hi:[1,0]
	v_pk_mul_f32 v[104:105], v[104:105], v[112:113]
	v_pk_mul_f32 v[112:113], v[106:107], s[16:17] op_sel_hi:[1,0]
	v_exp_f32_e32 v110, v110
	v_exp_f32_e32 v112, v112
	v_exp_f32_e32 v113, v113
	v_exp_f32_e32 v111, v111
	v_pk_add_f32 v[112:113], v[112:113], 1.0 op_sel_hi:[1,0]
	v_pk_add_f32 v[110:111], v[110:111], 1.0 op_sel_hi:[1,0]
	v_rcp_f32_e32 v112, v112
	v_rcp_f32_e32 v113, v113
	v_rcp_f32_e32 v110, v110
	v_rcp_f32_e32 v111, v111
	v_pk_mul_f32 v[106:107], v[106:107], v[112:113]
	v_pk_mul_f32 v[108:109], v[108:109], v[110:111]
	s_nop 0
	v_pk_mul_f32 v[108:109], v[100:101], v[108:109]
	v_pk_mul_f32 v[100:101], v[98:99], v[106:107]
	v_cvt_pk_bf16_f32 v98, v102, v103
	v_cvt_pk_bf16_f32 v99, v104, v105
	s_nop 0
	v_cvt_pk_bf16_f32 v100, v100, v101
	v_cvt_pk_bf16_f32 v101, v108, v109
	global_store_dwordx4 v[114:115], v[98:101], off
	s_nop 1
	v_xor_b32_e32 v100, v158, v159
	v_ashrrev_i32_e32 v100, 31, v100
	v_ffbh_i32_e32 v101, v159
	v_add_u32_e32 v100, 32, v100
	v_add_u32_e32 v101, -1, v101
	v_min_u32_e32 v102, v101, v100
	v_lshlrev_b64 v[100:101], v102, v[158:159]
	v_min_u32_e32 v100, 1, v100
	v_or_b32_e32 v100, v101, v100
	v_cvt_f32_i32_e32 v100, v100
	v_sub_u32_e32 v101, 32, v102
	v_mad_i64_i32 v[98:99], s[14:15], v160, s5, v[148:149]
	v_ldexp_f32 v100, v100, v101
	v_fmamk_f32 v100, v100, 0x32000000, v216
	v_rsq_f32_e32 v100, v100
	v_lshl_add_u64 v[98:99], v[98:99], 0, v[150:151]
	v_pk_fma_f32 v[78:79], v[78:79], v[100:101], v[94:95] op_sel_hi:[1,0,1]
	v_pk_fma_f32 v[80:81], v[80:81], v[100:101], v[96:97] op_sel_hi:[1,0,1]
	v_pk_fma_f32 v[74:75], v[74:75], v[100:101], v[90:91] op_sel_hi:[1,0,1]
	v_pk_fma_f32 v[76:77], v[76:77], v[100:101], v[92:93] op_sel_hi:[1,0,1]
	v_pk_fma_f32 v[70:71], v[70:71], v[100:101], v[86:87] op_sel_hi:[1,0,1]
	v_pk_fma_f32 v[72:73], v[72:73], v[100:101], v[88:89] op_sel_hi:[1,0,1]
; __device__ __forceinline__ unsigned cvt_pk_bf16(float lo, float hi) { unsigned r; asm volatile("v_cvt_pk_bf16_f32 %0, %1, %2" : "=v"(r) : "v"(lo), "v"(hi)); return r; }
;     __device__ __forceinline__ void operator()(const f32x4 (&acc)[2][2][4][2], const Unit& u, int wr, int wc, int fr, int fq) const {
;     ...
;             for (int m = 0; m < 4; ++m) { bf16_t* rowp = Hd + (size_t)(row0 + ai * HALF + m * 16) * ldh + col0;
;                 const float rstd = __builtin_amdgcn_rsqf((float)sv[ai][m] * (SS_INV * (1.0f / 2048.0f)) + RMS_EPS);
;                 const f32x4 ga = acc[ai][0][m][0] * rstd + cg0, gb = acc[ai][0][m][1] * rstd + cg1, ua = acc[ai][1][m][0] * rstd + cu0, ub = acc[ai][1][m][1] * rstd + cu1;
;                 const f32x4 v0 = fsilu4(ga) * ua, v1 = fsilu4(gb) * ub;
;                 u32x4 w; w.x = cvt_pk_bf16(v0[0], v0[1]); w.y = cvt_pk_bf16(v0[2], v0[3]); w.z = cvt_pk_bf16(v1[0], v1[1]); w.w = cvt_pk_bf16(v1[2], v1[3]);
;                 *(u32x4*)rowp = w; }
	v_pk_fma_f32 v[66:67], v[66:67], v[100:101], v[82:83] op_sel_hi:[1,0,1]
	v_pk_fma_f32 v[68:69], v[68:69], v[100:101], v[84:85] op_sel_hi:[1,0,1]
	v_pk_mul_f32 v[100:101], v[80:81], s[16:17] op_sel_hi:[1,0]
	v_pk_mul_f32 v[102:103], v[78:79], s[16:17] op_sel_hi:[1,0]
	v_exp_f32_e32 v100, v100
	v_exp_f32_e32 v102, v102
	v_exp_f32_e32 v103, v103
	v_exp_f32_e32 v101, v101
	v_pk_add_f32 v[102:103], v[102:103], 1.0 op_sel_hi:[1,0]
	v_pk_add_f32 v[100:101], v[100:101], 1.0 op_sel_hi:[1,0]
	v_rcp_f32_e32 v102, v102
	v_rcp_f32_e32 v103, v103
	v_rcp_f32_e32 v100, v100
	v_rcp_f32_e32 v101, v101
	v_pk_mul_f32 v[78:79], v[78:79], v[102:103]
	s_nop 0
	v_pk_mul_f32 v[70:71], v[70:71], v[78:79]
	v_pk_mul_f32 v[80:81], v[80:81], v[100:101]
	v_pk_mul_f32 v[78:79], v[76:77], s[16:17] op_sel_hi:[1,0]
	v_pk_mul_f32 v[72:73], v[72:73], v[80:81]
	v_pk_mul_f32 v[80:81], v[74:75], s[16:17] op_sel_hi:[1,0]
	v_exp_f32_e32 v78, v78
	v_exp_f32_e32 v80, v80
	v_exp_f32_e32 v81, v81
	v_exp_f32_e32 v79, v79
	v_pk_add_f32 v[80:81], v[80:81], 1.0 op_sel_hi:[1,0]
	v_pk_add_f32 v[78:79], v[78:79], 1.0 op_sel_hi:[1,0]
	v_rcp_f32_e32 v80, v80
	v_rcp_f32_e32 v81, v81
	v_rcp_f32_e32 v78, v78
	v_rcp_f32_e32 v79, v79
	v_pk_mul_f32 v[74:75], v[74:75], v[80:81]
	v_pk_mul_f32 v[76:77], v[76:77], v[78:79]
	s_nop 0
	v_pk_mul_f32 v[76:77], v[68:69], v[76:77]
	v_pk_mul_f32 v[68:69], v[66:67], v[74:75]
	v_cvt_pk_bf16_f32 v66, v70, v71
	v_cvt_pk_bf16_f32 v67, v72, v73
	s_nop 0
	v_cvt_pk_bf16_f32 v68, v68, v69
	v_cvt_pk_bf16_f32 v69, v76, v77
	global_store_dwordx4 v[98:99], v[66:69], off
	s_nop 1
	v_xor_b32_e32 v68, v156, v157
	v_ashrrev_i32_e32 v68, 31, v68
	v_ffbh_i32_e32 v69, v157
	v_add_u32_e32 v68, 32, v68
	v_add_u32_e32 v69, -1, v69
	v_min_u32_e32 v70, v69, v68
	v_lshlrev_b64 v[68:69], v70, v[156:157]
	v_min_u32_e32 v68, 1, v68
	v_or_b32_e32 v68, v69, v68
	v_cvt_f32_i32_e32 v68, v68
	v_sub_u32_e32 v69, 32, v70
	v_mad_i64_i32 v[66:67], s[14:15], v191, s5, v[148:149]
	v_ldexp_f32 v68, v68, v69
	v_fmamk_f32 v68, v68, 0x32000000, v216
	v_rsq_f32_e32 v68, v68
	v_lshl_add_u64 v[66:67], v[66:67], 0, v[150:151]
	v_pk_fma_f32 v[62:63], v[62:63], v[68:69], v[94:95] op_sel_hi:[1,0,1]
	v_pk_fma_f32 v[64:65], v[64:65], v[68:69], v[96:97] op_sel_hi:[1,0,1]
	v_pk_fma_f32 v[58:59], v[58:59], v[68:69], v[90:91] op_sel_hi:[1,0,1]
	v_pk_fma_f32 v[60:61], v[60:61], v[68:69], v[92:93] op_sel_hi:[1,0,1]
	v_pk_fma_f32 v[54:55], v[54:55], v[68:69], v[86:87] op_sel_hi:[1,0,1]
	v_pk_fma_f32 v[56:57], v[56:57], v[68:69], v[88:89] op_sel_hi:[1,0,1]
	v_pk_fma_f32 v[50:51], v[50:51], v[68:69], v[82:83] op_sel_hi:[1,0,1]
	v_pk_fma_f32 v[52:53], v[52:53], v[68:69], v[84:85] op_sel_hi:[1,0,1]
	v_pk_mul_f32 v[68:69], v[64:65], s[16:17] op_sel_hi:[1,0]
	v_pk_mul_f32 v[70:71], v[62:63], s[16:17] op_sel_hi:[1,0]
	v_exp_f32_e32 v68, v68
	v_exp_f32_e32 v70, v70
	v_exp_f32_e32 v71, v71
	v_exp_f32_e32 v69, v69
	v_pk_add_f32 v[70:71], v[70:71], 1.0 op_sel_hi:[1,0]
	v_pk_add_f32 v[68:69], v[68:69], 1.0 op_sel_hi:[1,0]
	v_rcp_f32_e32 v70, v70
	v_rcp_f32_e32 v71, v71
	v_rcp_f32_e32 v68, v68
	v_rcp_f32_e32 v69, v69
	v_pk_mul_f32 v[62:63], v[62:63], v[70:71]
	s_nop 0
	v_pk_mul_f32 v[54:55], v[54:55], v[62:63]
	v_pk_mul_f32 v[64:65], v[64:65], v[68:69]
	v_pk_mul_f32 v[62:63], v[60:61], s[16:17] op_sel_hi:[1,0]
	v_pk_mul_f32 v[56:57], v[56:57], v[64:65]
	v_pk_mul_f32 v[64:65], v[58:59], s[16:17] op_sel_hi:[1,0]
	v_exp_f32_e32 v62, v62
	v_exp_f32_e32 v64, v64
	v_exp_f32_e32 v65, v65
	v_exp_f32_e32 v63, v63
	v_pk_add_f32 v[64:65], v[64:65], 1.0 op_sel_hi:[1,0]
	v_pk_add_f32 v[62:63], v[62:63], 1.0 op_sel_hi:[1,0]
	v_rcp_f32_e32 v64, v64
	v_rcp_f32_e32 v65, v65
	v_rcp_f32_e32 v62, v62
	v_rcp_f32_e32 v63, v63
	v_pk_mul_f32 v[58:59], v[58:59], v[64:65]
	v_pk_mul_f32 v[60:61], v[60:61], v[62:63]
	s_nop 0
	v_pk_mul_f32 v[60:61], v[52:53], v[60:61]
	v_pk_mul_f32 v[52:53], v[50:51], v[58:59]
	v_cvt_pk_bf16_f32 v50, v54, v55
	v_cvt_pk_bf16_f32 v51, v56, v57
	s_nop 0
	v_cvt_pk_bf16_f32 v52, v52, v53
	v_cvt_pk_bf16_f32 v53, v60, v61
	global_store_dwordx4 v[66:67], v[50:53], off
	s_nop 1
	v_xor_b32_e32 v52, v154, v155
	v_ashrrev_i32_e32 v52, 31, v52
	v_ffbh_i32_e32 v53, v155
	v_add_u32_e32 v52, 32, v52
	v_add_u32_e32 v53, -1, v53
	v_min_u32_e32 v54, v53, v52
	v_lshlrev_b64 v[52:53], v54, v[154:155]
	v_min_u32_e32 v52, 1, v52
	v_or_b32_e32 v52, v53, v52
	v_cvt_f32_i32_e32 v52, v52
	v_sub_u32_e32 v53, 32, v54
	v_mad_i64_i32 v[50:51], s[14:15], v190, s5, v[148:149]
	v_ldexp_f32 v52, v52, v53
	v_fmamk_f32 v52, v52, 0x32000000, v216
	v_rsq_f32_e32 v52, v52
	v_lshl_add_u64 v[50:51], v[50:51], 0, v[150:151]
	v_pk_fma_f32 v[46:47], v[46:47], v[52:53], v[94:95] op_sel_hi:[1,0,1]
	v_pk_fma_f32 v[48:49], v[48:49], v[52:53], v[96:97] op_sel_hi:[1,0,1]
	v_pk_fma_f32 v[42:43], v[42:43], v[52:53], v[90:91] op_sel_hi:[1,0,1]
	v_pk_fma_f32 v[44:45], v[44:45], v[52:53], v[92:93] op_sel_hi:[1,0,1]
	v_pk_fma_f32 v[38:39], v[38:39], v[52:53], v[86:87] op_sel_hi:[1,0,1]
	v_pk_fma_f32 v[40:41], v[40:41], v[52:53], v[88:89] op_sel_hi:[1,0,1]
	v_pk_fma_f32 v[34:35], v[34:35], v[52:53], v[82:83] op_sel_hi:[1,0,1]
	v_pk_fma_f32 v[36:37], v[36:37], v[52:53], v[84:85] op_sel_hi:[1,0,1]
	v_pk_mul_f32 v[52:53], v[48:49], s[16:17] op_sel_hi:[1,0]
	v_pk_mul_f32 v[54:55], v[46:47], s[16:17] op_sel_hi:[1,0]
	v_exp_f32_e32 v52, v52
	v_exp_f32_e32 v54, v54
	v_exp_f32_e32 v55, v55
	v_exp_f32_e32 v53, v53
	v_pk_add_f32 v[54:55], v[54:55], 1.0 op_sel_hi:[1,0]
	v_pk_add_f32 v[52:53], v[52:53], 1.0 op_sel_hi:[1,0]
	v_rcp_f32_e32 v54, v54
	v_rcp_f32_e32 v55, v55
	v_rcp_f32_e32 v52, v52
	v_rcp_f32_e32 v53, v53
	v_pk_mul_f32 v[46:47], v[46:47], v[54:55]
	s_nop 0
	v_pk_mul_f32 v[38:39], v[38:39], v[46:47]
; __device__ __forceinline__ unsigned cvt_pk_bf16(float lo, float hi) { unsigned r; asm volatile("v_cvt_pk_bf16_f32 %0, %1, %2" : "=v"(r) : "v"(lo), "v"(hi)); return r; }
; __device__ __forceinline__ f32x4 fsilu4(f32x4 x) {
;     f32x4 e = x * -1.4426950408889634f;
; #pragma unroll
;     for (int j = 0; j < 4; ++j) e[j] = __builtin_amdgcn_exp2f(e[j]);
;     f32x4 d = e + 1.0f;
; #pragma unroll
;     for (int j = 0; j < 4; ++j) d[j] = __builtin_amdgcn_rcpf(d[j]);
;     return x * d;
; }
;     __device__ __forceinline__ void operator()(const f32x4 (&acc)[2][2][4][2], const Unit& u, int wr, int wc, int fr, int fq) const {
;     ...
;             for (int m = 0; m < 4; ++m) { bf16_t* rowp = Hd + (size_t)(row0 + ai * HALF + m * 16) * ldh + col0;
;                 const float rstd = __builtin_amdgcn_rsqf((float)sv[ai][m] * (SS_INV * (1.0f / 2048.0f)) + RMS_EPS);
;                 const f32x4 ga = acc[ai][0][m][0] * rstd + cg0, gb = acc[ai][0][m][1] * rstd + cg1, ua = acc[ai][1][m][0] * rstd + cu0, ub = acc[ai][1][m][1] * rstd + cu1;
;                 const f32x4 v0 = fsilu4(ga) * ua, v1 = fsilu4(gb) * ub;
;                 u32x4 w; w.x = cvt_pk_bf16(v0[0], v0[1]); w.y = cvt_pk_bf16(v0[2], v0[3]); w.z = cvt_pk_bf16(v1[0], v1[1]); w.w = cvt_pk_bf16(v1[2], v1[3]);
;                 *(u32x4*)rowp = w; }
	v_pk_mul_f32 v[48:49], v[48:49], v[52:53]
	v_pk_mul_f32 v[46:47], v[44:45], s[16:17] op_sel_hi:[1,0]
	v_pk_mul_f32 v[40:41], v[40:41], v[48:49]
	v_pk_mul_f32 v[48:49], v[42:43], s[16:17] op_sel_hi:[1,0]
	v_exp_f32_e32 v46, v46
	v_exp_f32_e32 v48, v48
	v_exp_f32_e32 v49, v49
	v_exp_f32_e32 v47, v47
	v_pk_add_f32 v[48:49], v[48:49], 1.0 op_sel_hi:[1,0]
	v_pk_add_f32 v[46:47], v[46:47], 1.0 op_sel_hi:[1,0]
	v_rcp_f32_e32 v48, v48
	v_rcp_f32_e32 v49, v49
	v_rcp_f32_e32 v46, v46
	v_rcp_f32_e32 v47, v47
	v_pk_mul_f32 v[42:43], v[42:43], v[48:49]
	v_pk_mul_f32 v[44:45], v[44:45], v[46:47]
	s_nop 0
	v_pk_mul_f32 v[44:45], v[36:37], v[44:45]
	v_pk_mul_f32 v[36:37], v[34:35], v[42:43]
	v_cvt_pk_bf16_f32 v34, v38, v39
	v_cvt_pk_bf16_f32 v35, v40, v41
	s_nop 0
	v_cvt_pk_bf16_f32 v36, v36, v37
	v_cvt_pk_bf16_f32 v37, v44, v45
	global_store_dwordx4 v[50:51], v[34:37], off
	s_nop 1
	v_xor_b32_e32 v36, v152, v153
	v_ashrrev_i32_e32 v36, 31, v36
	v_ffbh_i32_e32 v37, v153
	v_add_u32_e32 v36, 32, v36
	v_add_u32_e32 v37, -1, v37
	v_min_u32_e32 v38, v37, v36
	v_lshlrev_b64 v[36:37], v38, v[152:153]
	v_min_u32_e32 v36, 1, v36
	v_or_b32_e32 v36, v37, v36
	v_cvt_f32_i32_e32 v36, v36
	v_sub_u32_e32 v37, 32, v38
	v_mad_i64_i32 v[34:35], s[14:15], v181, s5, v[148:149]
	v_ldexp_f32 v36, v36, v37
	v_fmamk_f32 v36, v36, 0x32000000, v216
	v_rsq_f32_e32 v36, v36
	v_lshl_add_u64 v[34:35], v[34:35], 0, v[150:151]
	v_pk_fma_f32 v[30:31], v[30:31], v[36:37], v[94:95] op_sel_hi:[1,0,1]
	v_pk_fma_f32 v[32:33], v[32:33], v[36:37], v[96:97] op_sel_hi:[1,0,1]
	v_pk_fma_f32 v[26:27], v[26:27], v[36:37], v[90:91] op_sel_hi:[1,0,1]
	v_pk_fma_f32 v[28:29], v[28:29], v[36:37], v[92:93] op_sel_hi:[1,0,1]
	v_pk_fma_f32 v[22:23], v[22:23], v[36:37], v[86:87] op_sel_hi:[1,0,1]
	v_pk_fma_f32 v[24:25], v[24:25], v[36:37], v[88:89] op_sel_hi:[1,0,1]
	v_pk_fma_f32 v[18:19], v[18:19], v[36:37], v[82:83] op_sel_hi:[1,0,1]
	v_pk_fma_f32 v[20:21], v[20:21], v[36:37], v[84:85] op_sel_hi:[1,0,1]
	v_pk_mul_f32 v[36:37], v[32:33], s[16:17] op_sel_hi:[1,0]
	v_pk_mul_f32 v[38:39], v[30:31], s[16:17] op_sel_hi:[1,0]
	v_exp_f32_e32 v36, v36
	v_exp_f32_e32 v38, v38
	v_exp_f32_e32 v39, v39
	v_exp_f32_e32 v37, v37
	v_pk_add_f32 v[38:39], v[38:39], 1.0 op_sel_hi:[1,0]
	v_pk_add_f32 v[36:37], v[36:37], 1.0 op_sel_hi:[1,0]
	v_rcp_f32_e32 v38, v38
	v_rcp_f32_e32 v39, v39
	v_rcp_f32_e32 v36, v36
	v_rcp_f32_e32 v37, v37
	v_pk_mul_f32 v[30:31], v[30:31], v[38:39]
	s_nop 0
	v_pk_mul_f32 v[22:23], v[22:23], v[30:31]
	v_pk_mul_f32 v[32:33], v[32:33], v[36:37]
	v_pk_mul_f32 v[30:31], v[28:29], s[16:17] op_sel_hi:[1,0]
	v_pk_mul_f32 v[24:25], v[24:25], v[32:33]
	v_pk_mul_f32 v[32:33], v[26:27], s[16:17] op_sel_hi:[1,0]
	v_exp_f32_e32 v30, v30
	v_exp_f32_e32 v32, v32
	v_exp_f32_e32 v33, v33
	v_exp_f32_e32 v31, v31
	v_pk_add_f32 v[32:33], v[32:33], 1.0 op_sel_hi:[1,0]
	v_pk_add_f32 v[30:31], v[30:31], 1.0 op_sel_hi:[1,0]
	v_rcp_f32_e32 v32, v32
	v_rcp_f32_e32 v33, v33
	v_rcp_f32_e32 v30, v30
	v_rcp_f32_e32 v31, v31
	v_pk_mul_f32 v[26:27], v[26:27], v[32:33]
	v_pk_mul_f32 v[28:29], v[28:29], v[30:31]
	s_nop 0
	v_pk_mul_f32 v[28:29], v[20:21], v[28:29]
	v_pk_mul_f32 v[20:21], v[18:19], v[26:27]
	v_cvt_pk_bf16_f32 v18, v22, v23
	v_cvt_pk_bf16_f32 v19, v24, v25
	s_nop 0
	v_cvt_pk_bf16_f32 v20, v20, v21
	v_cvt_pk_bf16_f32 v21, v28, v29
	global_store_dwordx4 v[34:35], v[18:21], off
	s_nop 1
	v_xor_b32_e32 v20, v146, v147
	v_ashrrev_i32_e32 v20, 31, v20
	v_ffbh_i32_e32 v21, v147
	v_add_u32_e32 v20, 32, v20
	v_add_u32_e32 v21, -1, v21
	v_min_u32_e32 v22, v21, v20
	v_lshlrev_b64 v[20:21], v22, v[146:147]
	v_min_u32_e32 v20, 1, v20
	v_or_b32_e32 v20, v21, v20
	v_cvt_f32_i32_e32 v20, v20
	v_sub_u32_e32 v21, 32, v22
	v_mad_i64_i32 v[18:19], s[14:15], v161, s5, v[148:149]
	v_ldexp_f32 v20, v20, v21
	v_fmamk_f32 v20, v20, 0x32000000, v216
	v_rsq_f32_e32 v20, v20
	v_lshl_add_u64 v[18:19], v[18:19], 0, v[150:151]
	s_mov_b64 s[14:15], -1
	v_pk_fma_f32 v[14:15], v[14:15], v[20:21], v[94:95] op_sel_hi:[1,0,1]
	v_pk_fma_f32 v[16:17], v[16:17], v[20:21], v[96:97] op_sel_hi:[1,0,1]
	v_pk_fma_f32 v[10:11], v[10:11], v[20:21], v[90:91] op_sel_hi:[1,0,1]
	v_pk_fma_f32 v[12:13], v[12:13], v[20:21], v[92:93] op_sel_hi:[1,0,1]
	v_pk_fma_f32 v[6:7], v[6:7], v[20:21], v[86:87] op_sel_hi:[1,0,1]
	v_pk_fma_f32 v[8:9], v[8:9], v[20:21], v[88:89] op_sel_hi:[1,0,1]
	v_pk_fma_f32 v[2:3], v[2:3], v[20:21], v[82:83] op_sel_hi:[1,0,1]
	v_pk_fma_f32 v[4:5], v[4:5], v[20:21], v[84:85] op_sel_hi:[1,0,1]
	v_pk_mul_f32 v[20:21], v[16:17], s[16:17] op_sel_hi:[1,0]
	v_pk_mul_f32 v[22:23], v[14:15], s[16:17] op_sel_hi:[1,0]
	v_exp_f32_e32 v20, v20
	v_exp_f32_e32 v22, v22
	v_exp_f32_e32 v23, v23
	v_exp_f32_e32 v21, v21
	v_pk_add_f32 v[22:23], v[22:23], 1.0 op_sel_hi:[1,0]
	v_pk_add_f32 v[20:21], v[20:21], 1.0 op_sel_hi:[1,0]
	v_rcp_f32_e32 v22, v22
	v_rcp_f32_e32 v23, v23
	v_rcp_f32_e32 v20, v20
	v_rcp_f32_e32 v21, v21
	v_pk_mul_f32 v[14:15], v[14:15], v[22:23]
	s_nop 0
	v_pk_mul_f32 v[6:7], v[6:7], v[14:15]
	v_pk_mul_f32 v[16:17], v[16:17], v[20:21]
	v_pk_mul_f32 v[14:15], v[12:13], s[16:17] op_sel_hi:[1,0]
	v_pk_mul_f32 v[8:9], v[8:9], v[16:17]
	v_pk_mul_f32 v[16:17], v[10:11], s[16:17] op_sel_hi:[1,0]
	v_exp_f32_e32 v14, v14
	v_exp_f32_e32 v16, v16
	v_exp_f32_e32 v17, v17
	v_exp_f32_e32 v15, v15
	v_pk_add_f32 v[16:17], v[16:17], 1.0 op_sel_hi:[1,0]
	v_pk_add_f32 v[14:15], v[14:15], 1.0 op_sel_hi:[1,0]
	v_rcp_f32_e32 v16, v16
	v_rcp_f32_e32 v17, v17
	v_rcp_f32_e32 v14, v14
	v_rcp_f32_e32 v15, v15
	v_pk_mul_f32 v[10:11], v[10:11], v[16:17]
	v_pk_mul_f32 v[12:13], v[12:13], v[14:15]
	s_nop 0
	v_pk_mul_f32 v[12:13], v[4:5], v[12:13]
	v_pk_mul_f32 v[4:5], v[2:3], v[10:11]
	v_cvt_pk_bf16_f32 v2, v6, v7
	v_cvt_pk_bf16_f32 v3, v8, v9
	s_nop 0
	v_cvt_pk_bf16_f32 v4, v4, v5
	v_cvt_pk_bf16_f32 v5, v12, v13
	global_store_dwordx4 v[18:19], v[2:5], off
	s_cbranch_vccnz .LBB0_630
	s_andn2_b64 vcc, exec, s[0:1]
	s_cbranch_vccnz .LBB0_629
	s_branch .LBB0_629

; #define PG8_STAGE(bufoff, gbase, voff) do { const char* gb_ = (const char*)(gbase); asm volatile("" : "+s"(gb_)); _Pragma("unroll") for (int _i = 0; _i < 2; ++_i) { unsigned vo_ = (voff)[_i]; asm volatile("" : "+v"(vo_));        \
;         __builtin_amdgcn_global_load_lds((const unsigned*)(gb_ + vo_), (PG8_LAS unsigned*)(lds + (bufoff) + ldsw + _i * 8192), 16, 0, 0); } } while (0)
; #define PG8_WAIT_V(n) asm volatile("s_waitcnt vmcnt(" #n ")" ::: "memory")
; #define PG8_BAR __builtin_amdgcn_s_barrier()
; template <class Epi, class Sched, bool ALIGN_EPI = false, bool SP2 = false>
; __device__ __forceinline__ void gemm_phase(PG8_LAS unsigned char* lds, const Gemm g, const Sched& S, const Epi& E) {
;     ...
;     for (int i = 0; i < 2; ++i) { int R, C; stage_rc(tid * 16 + i * 8192, R, C); const int Rb = Epi::PERM ? ((R & ~31) + perm32(R & 31)) : R;
;         voffA[i] = (unsigned)(R * K + C) * 2u; voffB[i] = (unsigned)(Rb * K + C) * 2u; }
;     const size_t kstep = (size_t)(BK * 2);
;     const size_t hstep = (size_t)HALF * K * 2;
;     const size_t tstep = 2 * hstep;
;     const unsigned ldsw = (unsigned)wid * 1024u;
;     const int aoff = lds_byte(wr * 64 + fr, fq * 8), boff = lds_byte(wc * 32 + fr, fq * 8);
;     ...
;     Unit cur, nxt; int ui = 0;
;     if (!S.next(0, cur)) return;
;     f32x4 acc[2][2][4][2];
; #pragma unroll
;     for (int a = 0; a < 2; ++a)
; #pragma unroll
;         for (int b = 0; b < 2; ++b)
; #pragma unroll
;             for (int m = 0; m < 4; ++m)
; #pragma unroll
;                 for (int n = 0; n < 2; ++n) acc[a][b][m][n] = (f32x4){0.f, 0.f, 0.f, 0.f};
;     bf16x8 At[4][2], B0[2][2], B1[2][2];
;     const char* cA = (const char*)g.A + (size_t)cur.pm * tstep; const char* cB = (const char*)g.Bt + (size_t)cur.pn * tstep;
;     S.a_ready(cur);
;     if constexpr (SP2) {
;         PG8_STAGE(PG8_SB(0, 0), cB, voffB); PG8_STAGE(PG8_SB(0, 1), cB + hstep, voffB); PG8_STAGE(PG8_SA(0, 0), cA, voffA); PG8_STAGE(PG8_SA(0, 1), cA + hstep, voffA);
;         if (wr == 1) PG8_BAR;
;         PG8_WAIT_V(2); PG8_BAR;
;         PG8_STAGE(PG8_SB(1, 0), cB + kstep, voffB); PG8_STAGE(PG8_SA(1, 0), cA + kstep, voffA); PG8_STAGE(PG8_SB(1, 1), cB + hstep + kstep, voffB);
;         PG8_WAIT_V(6); PG8_BAR;
.LBB0_689:
	s_andn2_b64 vcc, exec, s[0:1]
	s_cbranch_vccnz .LBB0_219
	s_waitcnt vmcnt(0)
	v_mov_b32_e32 v2, v0
	s_add_i32 s33, s8, 1
	s_and_b64 vcc, exec, s[36:37]
	v_readfirstlane_b32 s12, v2
	s_cbranch_vccnz .LBB0_763
	v_bfe_i32 v4, v2, 27, 1
	s_waitcnt lgkmcnt(0)
	v_lshlrev_b32_e32 v3, 4, v2
	v_lshrrev_b32_e32 v4, 22, v4
	v_add_u32_e32 v4, v3, v4
	v_and_b32_e32 v4, 0xfffffc00, v4
	v_sub_u32_e32 v4, v3, v4
	v_lshrrev_b32_e32 v5, 4, v4
	v_ashrrev_i32_e32 v1, 31, v2
	v_bitop3_b32 v4, v5, v4, 32 bitop3:0x6c
	v_lshrrev_b32_e32 v1, 26, v1
	v_ashrrev_i32_e32 v6, 31, v4
	v_add_u32_e32 v1, v2, v1
	v_lshrrev_b32_e32 v6, 26, v6
	v_ashrrev_i32_e32 v1, 6, v1
	v_add_u32_e32 v6, v4, v6
	v_lshlrev_b32_e32 v5, 3, v1
	v_ashrrev_i32_e32 v7, 6, v6
	v_and_b32_e32 v6, 0xc0, v6
	v_and_b32_e32 v5, -16, v5
	v_lshlrev_b32_e32 v1, 5, v1
	v_sub_u32_e32 v4, v4, v6
	v_add_u32_e32 v5, v7, v5
	v_and_b32_e32 v1, 32, v1
	v_ashrrev_i16_sdwa v4, v217, sext(v4) dst_sel:DWORD dst_unused:UNUSED_PAD src0_sel:DWORD src1_sel:BYTE_0
	v_add_u32_sdwa v4, v1, sext(v4) dst_sel:DWORD dst_unused:UNUSED_PAD src0_sel:DWORD src1_sel:WORD_0
	v_lshlrev_b32_e32 v1, 1, v5
	v_lshrrev_b32_e32 v6, 2, v5
	v_and_b32_e32 v7, 3, v7
	s_mov_b32 s1, 0x7fffe0
	v_and_b32_e32 v1, 24, v1
	v_and_b32_e32 v6, 4, v6
	v_and_or_b32 v7, v5, s1, v7
	v_or3_b32 v6, v7, v6, v1
	s_movk_i32 s2, 0x1600
	v_mul_lo_u32 v1, v5, s2
	v_mul_u32_u24_e32 v5, 0x1600, v6
	v_add_u32_e32 v3, 0x2000, v3
	v_add_lshl_u32 v1, v4, v1, 1
	v_add_lshl_u32 v162, v5, v4, 1
	v_ashrrev_i32_e32 v4, 31, v3
	v_lshrrev_b32_e32 v4, 22, v4
	v_add_u32_e32 v4, v3, v4
	v_ashrrev_i32_e32 v4, 10, v4
	v_mul_i32_i24_e32 v5, 0x400, v4
	v_sub_u32_e32 v3, v3, v5
	v_lshrrev_b32_e32 v5, 4, v3
	v_bitop3_b32 v3, v5, v3, 32 bitop3:0x6c
	v_ashrrev_i32_e32 v6, 31, v3
	v_lshrrev_b32_e32 v6, 26, v6
	v_add_u32_e32 v6, v3, v6
	v_lshlrev_b32_e32 v5, 3, v4
	v_ashrrev_i32_e32 v7, 6, v6
	v_and_b32_e32 v6, 0xc0, v6
	v_readlane_b32 s0, v241, 44
	v_and_b32_e32 v5, -16, v5
	v_lshlrev_b32_e32 v4, 5, v4
	v_sub_u32_e32 v3, v3, v6
	s_add_u32 s13, s0, 0x5000000
	v_readlane_b32 s0, v241, 45
	v_add_u32_e32 v5, v7, v5
	v_and_b32_e32 v4, 32, v4
	v_ashrrev_i16_sdwa v3, v217, sext(v3) dst_sel:DWORD dst_unused:UNUSED_PAD src0_sel:DWORD src1_sel:BYTE_0
	v_and_b32_e32 v7, 3, v7
	s_addc_u32 s14, s0, 0
	v_add_u32_sdwa v3, v4, sext(v3) dst_sel:DWORD dst_unused:UNUSED_PAD src0_sel:DWORD src1_sel:WORD_0
	v_lshlrev_b32_e32 v4, 1, v5
	v_lshrrev_b32_e32 v6, 2, v5
	v_and_or_b32 v7, v5, s1, v7
	s_ashr_i32 s1, s12, 6
	v_readlane_b32 s3, v242, 9
	s_ashr_i32 s0, s12, 8
	v_and_b32_e32 v4, 24, v4
	v_and_b32_e32 v6, 4, v6
	v_mul_lo_u32 v5, v5, s2
	s_lshl_b32 s15, s1, 10
	s_mul_i32 s2, s3, 0x2c0000
	v_or3_b32 v4, v7, v6, v4
	s_add_u32 s6, s13, s2
	s_mul_hi_i32 s2, s3, 0x2c0000
	v_mul_u32_u24_e32 v4, 0x1600, v4
	s_addc_u32 s7, s14, s2
	v_add_lshl_u32 v164, v3, v5, 1
	v_add_lshl_u32 v190, v4, v3, 1
	s_mov_b64 s[2:3], s[6:7]
	s_add_i32 s16, s15, 0
	v_mov_b32_e32 v3, v162
	s_add_i32 m0, s16, 0x10000
	s_nop 0
	global_load_lds_dwordx4 v3, s[2:3]
	v_mov_b32_e32 v3, v190
	s_add_i32 m0, s16, 0x12000
	s_nop 0
	global_load_lds_dwordx4 v3, s[2:3]
	s_add_u32 s2, s6, 0x160000
	s_addc_u32 s3, s7, 0
	v_mov_b32_e32 v3, v162
	s_add_i32 m0, s16, 0x14000
	s_add_i32 s17, s16, 0x2000
	global_load_lds_dwordx4 v3, s[2:3]
	v_mov_b32_e32 v3, v190
	s_add_i32 m0, s16, 0x16000
	s_add_i32 s18, s16, 0x4000
	global_load_lds_dwordx4 v3, s[2:3]
	v_readlane_b32 s2, v242, 44
	v_readlane_b32 s3, v242, 45
	v_mov_b32_e32 v3, v1
	s_mov_b32 m0, s16
	s_add_i32 s19, s16, 0x6000
	s_nop 1
	global_load_lds_dwordx4 v3, s[2:3]
	v_mov_b32_e32 v3, v164
	s_mov_b32 m0, s17
	s_cmp_lg_u32 s0, 1
	global_load_lds_dwordx4 v3, s[2:3]
	v_readlane_b32 s2, v242, 42
	v_readlane_b32 s3, v242, 43
	v_mov_b32_e32 v3, v1
	s_mov_b32 m0, s18
	s_nop 2
	global_load_lds_dwordx4 v3, s[2:3]
	v_mov_b32_e32 v3, v164
	s_mov_b32 m0, s19
	s_nop 0
	global_load_lds_dwordx4 v3, s[2:3]
	s_cbranch_scc1 .LBB0_693
.LBB0_693:
	s_add_u32 s20, s30, 0xa000
	s_addc_u32 s21, s31, 0
	s_cmp_lg_u32 s8, 3
	s_cselect_b64 s[46:47], -1, 0
	s_and_b64 s[2:3], s[46:47], exec
	s_cselect_b32 s4, s33, 3
	s_lshl_b32 s40, s4, 11
	v_readlane_b32 s48, v243, 2
	s_lshl_b64 s[2:3], s[40:41], 2
	v_readlane_b32 s52, v243, 6
	v_readlane_b32 s49, v243, 3
	v_readlane_b32 s53, v243, 7
	s_add_u32 s48, s52, s2
	s_mul_i32 s40, s4, 0x6000
	s_addc_u32 s49, s53, s3
	s_lshl_b64 s[2:3], s[40:41], 2
	s_add_u32 s2, s79, s2
	s_addc_u32 s3, s89, s3
	s_add_u32 s22, s2, 0x2000
	v_readlane_b32 s50, v243, 4
	s_addc_u32 s23, s3, 0
	v_readlane_b32 s2, v241, 46
	v_readlane_b32 s51, v243, 5
	v_readlane_b32 s3, v241, 47
	s_add_u32 s50, s2, 0x40000
	s_addc_u32 s51, s3, 0
	s_lshl_b32 s1, s1, 5
	s_and_b32 s1, s1, 0x60
	s_lshl_b32 s4, s0, 13
	s_lshl_b32 s5, s1, 7
	s_add_u32 s2, s6, 0x80
	s_addc_u32 s3, s7, 0
	v_mov_b32_e32 v3, v162
	s_waitcnt vmcnt(2)
	s_barrier
	s_add_i32 m0, s16, 0x18000
	s_add_i32 s24, s16, 0x8000
	global_load_lds_dwordx4 v3, s[2:3]
	v_mov_b32_e32 v3, v190
	s_add_i32 m0, s16, 0x1a000
	s_add_i32 s25, s16, 0xa000
	global_load_lds_dwordx4 v3, s[2:3]
	v_readlane_b32 s2, v242, 46
	v_readlane_b32 s3, v242, 47
	v_mov_b32_e32 v3, v1
	s_mov_b32 m0, s24
	v_bfe_u32 v4, v2, 4, 2
	s_nop 1
	global_load_lds_dwordx4 v3, s[2:3]
	v_mov_b32_e32 v3, v164
	s_mov_b32 m0, s25
	v_lshlrev_b32_e32 v5, 4, v4
	global_load_lds_dwordx4 v3, s[2:3]
	s_add_u32 s2, s6, 0x160080
	s_addc_u32 s3, s7, 0
	v_mov_b32_e32 v3, v162
	s_add_i32 m0, s16, 0x1c000
	v_readlane_b32 s56, v243, 10
	global_load_lds_dwordx4 v3, s[2:3]
	v_mov_b32_e32 v3, v190
	s_add_i32 m0, s16, 0x1e000
	v_readlane_b32 s57, v243, 11
	global_load_lds_dwordx4 v3, s[2:3]
	v_and_b32_e32 v3, 15, v2
	v_lshlrev_b32_e32 v2, 2, v2
	v_readlane_b32 s58, v243, 12
	v_readlane_b32 s59, v243, 13
	v_readlane_b32 s60, v243, 14
	v_readlane_b32 s61, v243, 15
	v_readlane_b32 s62, v243, 16
	v_readlane_b32 s63, v243, 17
	v_lshl_or_b32 v191, s0, 6, v3
	v_lshl_or_b32 v3, v3, 6, v5
	v_and_b32_e32 v2, 32, v2
	s_waitcnt vmcnt(6)
	v_bitop3_b32 v5, v3, s4, v2 bitop3:0xde
	v_bitop3_b32 v192, v3, s5, v2 bitop3:0xde
	v_lshl_or_b32 v193, v4, 3, s1
	v_readlane_b32 s0, v242, 38
	v_readlane_b32 s4, v242, 44
	v_readlane_b32 s56, v242, 62
	s_mov_b32 s26, 0
	v_cmp_eq_u32_e64 s[36:37], 0, v4
	v_add_u32_e32 v194, 0, v5
	v_readlane_b32 s30, v242, 9
	s_mov_b32 s29, s0
	v_readlane_b32 s5, v242, 45
	v_readlane_b32 s57, v242, 63
	v_readlane_b32 s60, v241, 2
	v_readlane_b32 s61, v241, 3
	v_readlane_b32 s70, v241, 12
	v_readlane_b32 s71, v241, 13
	s_mov_b32 s40, 0x2f800000
	v_readlane_b32 s54, v243, 8
	v_readlane_b32 s55, v243, 9
	s_barrier
	v_readlane_b32 s1, v242, 39
	v_readlane_b32 s58, v241, 0
	v_readlane_b32 s59, v241, 1
	v_readlane_b32 s62, v241, 4
	v_readlane_b32 s63, v241, 5
	v_readlane_b32 s64, v241, 6
	v_readlane_b32 s65, v241, 7
	v_readlane_b32 s66, v241, 8
	v_readlane_b32 s67, v241, 9
	v_readlane_b32 s68, v241, 10
	v_readlane_b32 s69, v241, 11
	s_branch .LBB0_696

; #define PG8_STAGE(bufoff, gbase, voff) do { const char* gb_ = (const char*)(gbase); asm volatile("" : "+s"(gb_)); _Pragma("unroll") for (int _i = 0; _i < 2; ++_i) { unsigned vo_ = (voff)[_i]; asm volatile("" : "+v"(vo_));        \
;         __builtin_amdgcn_global_load_lds((const unsigned*)(gb_ + vo_), (PG8_LAS unsigned*)(lds + (bufoff) + ldsw + _i * 8192), 16, 0, 0); } } while (0)
; #define PG8_LDA(dst, b, h) do { _Pragma("unroll") for (int m = 0; m < 4; ++m) _Pragma("unroll") for (int k = 0; k < 2; ++k) dst[m][k] = *(const PG8_LAS bf16x8*)(lds + PG8_SA(b, h) + aoff + m * 2048 + k * 1024); } while (0)
; #define PG8_LDB(dst, b, h) do { _Pragma("unroll") for (int n = 0; n < 2; ++n) _Pragma("unroll") for (int k = 0; k < 2; ++k) dst[n][k] = *(const PG8_LAS bf16x8*)(lds + PG8_SB(b, h) + boff + n * 2048 + k * 1024); } while (0)
; #define PG8_MMA(ai, bj, At, Bt) do { __builtin_amdgcn_s_setprio(1); _Pragma("unroll") for (int m = 0; m < 4; ++m) _Pragma("unroll") for (int n = 0; n < 2; ++n) _Pragma("unroll") for (int k = 0; k < 2; ++k) \
;         acc[ai][bj][m][n] = __builtin_amdgcn_mfma_f32_16x16x32_bf16(Bt[n][k], At[m][k], acc[ai][bj][m][n], 0, 0, 0); __builtin_amdgcn_s_setprio(0); } while (0)
; #define PG8_WAIT_V(n) asm volatile("s_waitcnt vmcnt(" #n ")" ::: "memory")
; template <class Epi, class Sched, bool ALIGN_EPI = false, bool SP2 = false>
; __device__ __forceinline__ void gemm_phase(PG8_LAS unsigned char* lds, const Gemm g, const Sched& S, const Epi& E) {
;     ...
;             const bool last = (t == nt - 2);
;             const char* a1 = cA + (size_t)(t + 1) * kstep;
;             const char* a2 = last ? nA : cA + (size_t)(t + 2) * kstep; const char* b2 = last ? nB : cB + (size_t)(t + 2) * kstep;
;             const char* a3 = a2 + kstep; const char* b3 = b2 + kstep;
;             if (last && has_next) S.a_ready(nxt);
;             if constexpr (SP2) {
;             PG8_LDB(B0, 0, 0); PG8_LDB(B1, 0, 1); PG8_SCHED; PG8_LDA(At, 0, 0); PG8_STAGE(PG8_SA(1, 1), a1 + hstep, voffA);
;             PG8_WAIT_V(8); PG8_WAIT_L(0); PG8_BAR; PG8_MMA(0, 0, At, B0); PG8_MMA(0, 1, At, B1); PG8_BAR; PG8_SCHED;
;             PG8_LDA(At, 0, 1); PG8_STAGE(PG8_SB(0, 0), b2, voffB); PG8_STAGE(PG8_SB(0, 1), b2 + hstep, voffB); PG8_STAGE(PG8_SA(0, 0), a2, voffA);
;             PG8_WAIT_V(8); PG8_WAIT_L(0); PG8_BAR; PG8_MMA(1, 0, At, B0); PG8_MMA(1, 1, At, B1); PG8_BAR; PG8_SCHED;
.LBB0_707:
	s_add_u32 s2, s4, 0x100
	s_addc_u32 s3, s5, 0
	s_cmpk_eq_i32 s35, 0x54
	s_cselect_b32 s10, s52, s2
	s_cselect_b32 s11, s53, s3
	s_cselect_b32 s8, s42, s31
	s_cselect_b32 s9, s43, s34
	s_add_u32 s6, s10, 0x80
	s_addc_u32 s7, s11, 0
	s_add_i32 s38, 0, 0x10000
	s_add_i32 s39, 0, 0x14000
	ds_read_b128 v[34:37], v244
	ds_read_b128 v[38:41], v244 offset:1024
	ds_read_b128 v[98:101], v244 offset:2048
	ds_read_b128 v[102:105], v244 offset:3072
	ds_read_b128 v[146:149], v244 offset:16384
	ds_read_b128 v[150:153], v244 offset:17408
	ds_read_b128 v[154:157], v244 offset:18432
	ds_read_b128 v[158:161], v244 offset:19456
	s_add_u32 s4, s4, 0x160080
	s_addc_u32 s5, s5, 0
	ds_read_b128 v[178:181], v194
	ds_read_b128 v[182:185], v194 offset:1024
	ds_read_b128 v[186:189], v194 offset:2048
	ds_read_b128 v[196:199], v194 offset:3072
	ds_read_b128 v[200:203], v194 offset:4096
	ds_read_b128 v[204:207], v194 offset:5120
	ds_read_b128 v[208:211], v194 offset:6144
	ds_read_b128 v[212:215], v194 offset:7168
	s_add_i32 m0, s16, 0xc000
	s_nop 0
	global_load_lds_dwordx4 v1, s[4:5]
	s_add_i32 m0, s16, 0xe000
	s_nop 0
	global_load_lds_dwordx4 v164, s[4:5]
	s_waitcnt vmcnt(8)
	s_waitcnt lgkmcnt(0)
	s_cmp_lg_u32 s98, 0
	s_cbranch_scc1 .Lhb_24
	s_barrier
.Lhb_24:
	s_setprio 1
	s_waitcnt lgkmcnt(0)
	v_mfma_f32_16x16x32_bf16 v[142:145], v[34:37], v[178:181], v[142:145]
	v_mfma_f32_16x16x32_bf16 v[142:145], v[38:41], v[182:185], v[142:145]
	v_mfma_f32_16x16x32_bf16 v[134:137], v[34:37], v[186:189], v[134:137]
	v_mfma_f32_16x16x32_bf16 v[134:137], v[38:41], v[196:199], v[134:137]
	v_mfma_f32_16x16x32_bf16 v[126:129], v[34:37], v[200:203], v[126:129]
	v_mfma_f32_16x16x32_bf16 v[126:129], v[38:41], v[204:207], v[126:129]
	v_mfma_f32_16x16x32_bf16 v[118:121], v[34:37], v[208:211], v[118:121]
	v_mfma_f32_16x16x32_bf16 v[118:121], v[38:41], v[212:215], v[118:121]
	v_mfma_f32_16x16x32_bf16 v[138:141], v[98:101], v[178:181], v[138:141]
	v_mfma_f32_16x16x32_bf16 v[138:141], v[102:105], v[182:185], v[138:141]
	v_mfma_f32_16x16x32_bf16 v[130:133], v[98:101], v[186:189], v[130:133]
	v_mfma_f32_16x16x32_bf16 v[130:133], v[102:105], v[196:199], v[130:133]
	v_mfma_f32_16x16x32_bf16 v[122:125], v[98:101], v[200:203], v[122:125]
	v_mfma_f32_16x16x32_bf16 v[122:125], v[102:105], v[204:207], v[122:125]
	v_mfma_f32_16x16x32_bf16 v[114:117], v[98:101], v[208:211], v[114:117]
	v_mfma_f32_16x16x32_bf16 v[114:117], v[102:105], v[212:215], v[114:117]
	s_setprio 0
	s_setprio 1
	v_mfma_f32_16x16x32_bf16 v[70:73], v[146:149], v[178:181], v[70:73]
	v_mfma_f32_16x16x32_bf16 v[70:73], v[150:153], v[182:185], v[70:73]
	v_mfma_f32_16x16x32_bf16 v[62:65], v[146:149], v[186:189], v[62:65]
	v_mfma_f32_16x16x32_bf16 v[62:65], v[150:153], v[196:199], v[62:65]
	v_mfma_f32_16x16x32_bf16 v[54:57], v[146:149], v[200:203], v[54:57]
	v_mfma_f32_16x16x32_bf16 v[54:57], v[150:153], v[204:207], v[54:57]
	v_mfma_f32_16x16x32_bf16 v[46:49], v[146:149], v[208:211], v[46:49]
	v_mfma_f32_16x16x32_bf16 v[46:49], v[150:153], v[212:215], v[46:49]
	v_mfma_f32_16x16x32_bf16 v[66:69], v[154:157], v[178:181], v[66:69]
	v_mfma_f32_16x16x32_bf16 v[66:69], v[158:161], v[182:185], v[66:69]
	v_mfma_f32_16x16x32_bf16 v[58:61], v[154:157], v[186:189], v[58:61]
	v_mfma_f32_16x16x32_bf16 v[58:61], v[158:161], v[196:199], v[58:61]
	v_mfma_f32_16x16x32_bf16 v[50:53], v[154:157], v[200:203], v[50:53]
	v_mfma_f32_16x16x32_bf16 v[50:53], v[158:161], v[204:207], v[50:53]
	v_mfma_f32_16x16x32_bf16 v[42:45], v[154:157], v[208:211], v[42:45]
	v_mfma_f32_16x16x32_bf16 v[42:45], v[158:161], v[212:215], v[42:45]
	s_setprio 0
	s_cmp_eq_u32 s98, 0
	s_cbranch_scc1 .Lhb_25
	s_barrier
.Lhb_25:
	s_mov_b64 s[4:5], s[8:9]
	s_add_i32 s38, s38, s15
	ds_read_b128 v[178:181], v194 offset:16384
	ds_read_b128 v[182:185], v194 offset:17408
	ds_read_b128 v[186:189], v194 offset:18432
	ds_read_b128 v[196:199], v194 offset:19456
	ds_read_b128 v[200:203], v194 offset:20480
	ds_read_b128 v[204:207], v194 offset:21504
	ds_read_b128 v[208:211], v194 offset:22528
	ds_read_b128 v[212:215], v194 offset:23552
	s_mov_b32 m0, s38
	s_nop 0
	global_load_lds_dwordx4 v162, s[4:5]
	s_add_i32 m0, s38, 0x2000
	s_nop 0
	global_load_lds_dwordx4 v190, s[4:5]
	s_add_u32 s4, s8, 0x160000
	s_addc_u32 s5, s9, 0
	s_add_i32 s38, s39, s15
	s_mov_b32 m0, s38
	s_nop 0
	global_load_lds_dwordx4 v162, s[4:5]
	s_add_i32 m0, s38, 0x2000
	s_nop 0
	global_load_lds_dwordx4 v190, s[4:5]
	s_mov_b64 s[4:5], s[10:11]
	s_mov_b32 m0, s16
	s_nop 0
	global_load_lds_dwordx4 v1, s[4:5]
	s_mov_b32 m0, s17
	s_nop 0
	global_load_lds_dwordx4 v164, s[4:5]
	s_waitcnt vmcnt(8)
	s_waitcnt lgkmcnt(0)
	s_cmp_lg_u32 s98, 0
	s_cbranch_scc1 .Lhb_26
	s_barrier
; #define PG8_STAGE(bufoff, gbase, voff) do { const char* gb_ = (const char*)(gbase); asm volatile("" : "+s"(gb_)); _Pragma("unroll") for (int _i = 0; _i < 2; ++_i) { unsigned vo_ = (voff)[_i]; asm volatile("" : "+v"(vo_));        \
;         __builtin_amdgcn_global_load_lds((const unsigned*)(gb_ + vo_), (PG8_LAS unsigned*)(lds + (bufoff) + ldsw + _i * 8192), 16, 0, 0); } } while (0)
; #define PG8_LDA(dst, b, h) do { _Pragma("unroll") for (int m = 0; m < 4; ++m) _Pragma("unroll") for (int k = 0; k < 2; ++k) dst[m][k] = *(const PG8_LAS bf16x8*)(lds + PG8_SA(b, h) + aoff + m * 2048 + k * 1024); } while (0)
; #define PG8_LDB(dst, b, h) do { _Pragma("unroll") for (int n = 0; n < 2; ++n) _Pragma("unroll") for (int k = 0; k < 2; ++k) dst[n][k] = *(const PG8_LAS bf16x8*)(lds + PG8_SB(b, h) + boff + n * 2048 + k * 1024); } while (0)
; #define PG8_MMA(ai, bj, At, Bt) do { __builtin_amdgcn_s_setprio(1); _Pragma("unroll") for (int m = 0; m < 4; ++m) _Pragma("unroll") for (int n = 0; n < 2; ++n) _Pragma("unroll") for (int k = 0; k < 2; ++k) \
;         acc[ai][bj][m][n] = __builtin_amdgcn_mfma_f32_16x16x32_bf16(Bt[n][k], At[m][k], acc[ai][bj][m][n], 0, 0, 0); __builtin_amdgcn_s_setprio(0); } while (0)
; #define PG8_WAIT_V(n) asm volatile("s_waitcnt vmcnt(" #n ")" ::: "memory")
; #define PG8_WAIT_L(n) asm volatile("s_waitcnt lgkmcnt(" #n ")" ::: "memory")
; #define PG8_BAR __builtin_amdgcn_s_barrier()
; #define PG8_SCHED __builtin_amdgcn_sched_barrier(0)
; template <class Epi, class Sched, bool ALIGN_EPI = false, bool SP2 = false>
; __device__ __forceinline__ void gemm_phase(PG8_LAS unsigned char* lds, const Gemm g, const Sched& S, const Epi& E) {
;     ...
;             PG8_WAIT_V(8); PG8_WAIT_L(0); PG8_BAR; PG8_MMA(1, 0, At, B0); PG8_MMA(1, 1, At, B1); PG8_BAR; PG8_SCHED;
;             PG8_LDB(B0, 1, 0); PG8_LDB(B1, 1, 1); PG8_SCHED; PG8_LDA(At, 1, 0); PG8_STAGE(PG8_SA(0, 1), a2 + hstep, voffA);
;             PG8_WAIT_V(8); PG8_WAIT_L(0); PG8_BAR; PG8_MMA(0, 0, At, B0); PG8_MMA(0, 1, At, B1); PG8_BAR; PG8_SCHED;
.Lhb_26:
	s_setprio 1
	s_waitcnt lgkmcnt(0)
	v_mfma_f32_16x16x32_bf16 v[110:113], v[34:37], v[178:181], v[110:113]
	v_mfma_f32_16x16x32_bf16 v[110:113], v[38:41], v[182:185], v[110:113]
	v_mfma_f32_16x16x32_bf16 v[94:97], v[34:37], v[186:189], v[94:97]
	v_mfma_f32_16x16x32_bf16 v[94:97], v[38:41], v[196:199], v[94:97]
	v_mfma_f32_16x16x32_bf16 v[86:89], v[34:37], v[200:203], v[86:89]
	v_mfma_f32_16x16x32_bf16 v[86:89], v[38:41], v[204:207], v[86:89]
	v_mfma_f32_16x16x32_bf16 v[34:37], v[34:37], v[208:211], v[78:81]
	v_mfma_f32_16x16x32_bf16 v[34:37], v[38:41], v[212:215], v[34:37]
	v_mfma_f32_16x16x32_bf16 v[106:109], v[98:101], v[178:181], v[106:109]
	v_mfma_f32_16x16x32_bf16 v[106:109], v[102:105], v[182:185], v[106:109]
	v_mfma_f32_16x16x32_bf16 v[90:93], v[98:101], v[186:189], v[90:93]
	v_mfma_f32_16x16x32_bf16 v[90:93], v[102:105], v[196:199], v[90:93]
	v_mfma_f32_16x16x32_bf16 v[82:85], v[98:101], v[200:203], v[82:85]
	v_mfma_f32_16x16x32_bf16 v[82:85], v[102:105], v[204:207], v[82:85]
	v_mfma_f32_16x16x32_bf16 v[38:41], v[98:101], v[208:211], v[74:77]
	v_mfma_f32_16x16x32_bf16 v[38:41], v[102:105], v[212:215], v[38:41]
	s_setprio 0
	s_setprio 1
	v_mfma_f32_16x16x32_bf16 v[30:33], v[146:149], v[178:181], v[30:33]
	v_mfma_f32_16x16x32_bf16 v[30:33], v[150:153], v[182:185], v[30:33]
	v_mfma_f32_16x16x32_bf16 v[22:25], v[146:149], v[186:189], v[22:25]
	v_mfma_f32_16x16x32_bf16 v[22:25], v[150:153], v[196:199], v[22:25]
	v_mfma_f32_16x16x32_bf16 v[14:17], v[146:149], v[200:203], v[14:17]
	v_mfma_f32_16x16x32_bf16 v[14:17], v[150:153], v[204:207], v[14:17]
	v_mfma_f32_16x16x32_bf16 v[6:9], v[146:149], v[208:211], v[6:9]
	v_mfma_f32_16x16x32_bf16 v[6:9], v[150:153], v[212:215], v[6:9]
	v_mfma_f32_16x16x32_bf16 v[26:29], v[154:157], v[178:181], v[26:29]
	v_mfma_f32_16x16x32_bf16 v[26:29], v[158:161], v[182:185], v[26:29]
	v_mfma_f32_16x16x32_bf16 v[18:21], v[154:157], v[186:189], v[18:21]
	v_mfma_f32_16x16x32_bf16 v[18:21], v[158:161], v[196:199], v[18:21]
	v_mfma_f32_16x16x32_bf16 v[10:13], v[154:157], v[200:203], v[10:13]
	v_mfma_f32_16x16x32_bf16 v[10:13], v[158:161], v[204:207], v[10:13]
	v_mfma_f32_16x16x32_bf16 v[2:5], v[154:157], v[208:211], v[2:5]
	v_mfma_f32_16x16x32_bf16 v[2:5], v[158:161], v[212:215], v[2:5]
	s_setprio 0
	s_cmp_eq_u32 s98, 0
	s_cbranch_scc1 .Lhb_27
	s_barrier
.Lhb_27:
	s_add_i32 s38, 0, 0x18000
	s_add_i32 s39, 0, 0x1c000
	ds_read_b128 v[74:77], v244 offset:32768
	ds_read_b128 v[78:81], v244 offset:33792
	ds_read_b128 v[98:101], v244 offset:34816
	ds_read_b128 v[102:105], v244 offset:35840
	ds_read_b128 v[146:149], v244 offset:49152
	ds_read_b128 v[150:153], v244 offset:50176
	ds_read_b128 v[154:157], v244 offset:51200
	ds_read_b128 v[158:161], v244 offset:52224
	s_add_u32 s4, s10, 0x160000
	s_addc_u32 s5, s11, 0
	s_mov_b32 m0, s18
	ds_read_b128 v[178:181], v194 offset:32768
	ds_read_b128 v[182:185], v194 offset:33792
	ds_read_b128 v[186:189], v194 offset:34816
	ds_read_b128 v[196:199], v194 offset:35840
	ds_read_b128 v[200:203], v194 offset:36864
	ds_read_b128 v[204:207], v194 offset:37888
	ds_read_b128 v[208:211], v194 offset:38912
	ds_read_b128 v[212:215], v194 offset:39936
	s_nop 0
	global_load_lds_dwordx4 v1, s[4:5]
	s_mov_b32 m0, s19
	s_nop 0
	global_load_lds_dwordx4 v164, s[4:5]
	s_waitcnt vmcnt(8)
	s_waitcnt lgkmcnt(0)
	s_cmp_lg_u32 s98, 0
	s_cbranch_scc1 .Lhb_28
	s_barrier
.Lhb_28:
	s_setprio 1
	s_waitcnt lgkmcnt(0)
	v_mfma_f32_16x16x32_bf16 v[142:145], v[74:77], v[178:181], v[142:145]
	v_mfma_f32_16x16x32_bf16 v[142:145], v[78:81], v[182:185], v[142:145]
	v_mfma_f32_16x16x32_bf16 v[134:137], v[74:77], v[186:189], v[134:137]
	v_mfma_f32_16x16x32_bf16 v[134:137], v[78:81], v[196:199], v[134:137]
	v_mfma_f32_16x16x32_bf16 v[126:129], v[74:77], v[200:203], v[126:129]
	v_mfma_f32_16x16x32_bf16 v[126:129], v[78:81], v[204:207], v[126:129]
	v_mfma_f32_16x16x32_bf16 v[118:121], v[74:77], v[208:211], v[118:121]
	v_mfma_f32_16x16x32_bf16 v[118:121], v[78:81], v[212:215], v[118:121]
	v_mfma_f32_16x16x32_bf16 v[138:141], v[98:101], v[178:181], v[138:141]
	v_mfma_f32_16x16x32_bf16 v[138:141], v[102:105], v[182:185], v[138:141]
	v_mfma_f32_16x16x32_bf16 v[130:133], v[98:101], v[186:189], v[130:133]
	v_mfma_f32_16x16x32_bf16 v[130:133], v[102:105], v[196:199], v[130:133]
	v_mfma_f32_16x16x32_bf16 v[122:125], v[98:101], v[200:203], v[122:125]
	v_mfma_f32_16x16x32_bf16 v[122:125], v[102:105], v[204:207], v[122:125]
	v_mfma_f32_16x16x32_bf16 v[114:117], v[98:101], v[208:211], v[114:117]
	v_mfma_f32_16x16x32_bf16 v[114:117], v[102:105], v[212:215], v[114:117]
	s_setprio 0
	s_setprio 1
	v_mfma_f32_16x16x32_bf16 v[70:73], v[146:149], v[178:181], v[70:73]
	v_mfma_f32_16x16x32_bf16 v[70:73], v[150:153], v[182:185], v[70:73]
	v_mfma_f32_16x16x32_bf16 v[62:65], v[146:149], v[186:189], v[62:65]
	v_mfma_f32_16x16x32_bf16 v[62:65], v[150:153], v[196:199], v[62:65]
	v_mfma_f32_16x16x32_bf16 v[54:57], v[146:149], v[200:203], v[54:57]
	v_mfma_f32_16x16x32_bf16 v[54:57], v[150:153], v[204:207], v[54:57]
	v_mfma_f32_16x16x32_bf16 v[46:49], v[146:149], v[208:211], v[46:49]
	v_mfma_f32_16x16x32_bf16 v[46:49], v[150:153], v[212:215], v[46:49]
	v_mfma_f32_16x16x32_bf16 v[66:69], v[154:157], v[178:181], v[66:69]
	v_mfma_f32_16x16x32_bf16 v[66:69], v[158:161], v[182:185], v[66:69]
	v_mfma_f32_16x16x32_bf16 v[58:61], v[154:157], v[186:189], v[58:61]
	v_mfma_f32_16x16x32_bf16 v[58:61], v[158:161], v[196:199], v[58:61]
	v_mfma_f32_16x16x32_bf16 v[50:53], v[154:157], v[200:203], v[50:53]
	v_mfma_f32_16x16x32_bf16 v[50:53], v[158:161], v[204:207], v[50:53]
	v_mfma_f32_16x16x32_bf16 v[42:45], v[154:157], v[208:211], v[42:45]
	v_mfma_f32_16x16x32_bf16 v[42:45], v[158:161], v[212:215], v[42:45]
	s_setprio 0
	s_cmp_eq_u32 s98, 0
	s_cbranch_scc1 .Lhb_29
	s_barrier
; #define PG8_STAGE(bufoff, gbase, voff) do { const char* gb_ = (const char*)(gbase); asm volatile("" : "+s"(gb_)); _Pragma("unroll") for (int _i = 0; _i < 2; ++_i) { unsigned vo_ = (voff)[_i]; asm volatile("" : "+v"(vo_));        \
;         __builtin_amdgcn_global_load_lds((const unsigned*)(gb_ + vo_), (PG8_LAS unsigned*)(lds + (bufoff) + ldsw + _i * 8192), 16, 0, 0); } } while (0)
; #define PG8_LDA(dst, b, h) do { _Pragma("unroll") for (int m = 0; m < 4; ++m) _Pragma("unroll") for (int k = 0; k < 2; ++k) dst[m][k] = *(const PG8_LAS bf16x8*)(lds + PG8_SA(b, h) + aoff + m * 2048 + k * 1024); } while (0)
; #define PG8_WAIT_V(n) asm volatile("s_waitcnt vmcnt(" #n ")" ::: "memory")
; #define PG8_WAIT_L(n) asm volatile("s_waitcnt lgkmcnt(" #n ")" ::: "memory")
; #define PG8_BAR __builtin_amdgcn_s_barrier()
; #define PG8_SCHED __builtin_amdgcn_sched_barrier(0)
;     __device__ __forceinline__ void operator()(const f32x4 (&acc)[2][2][4][2], const Unit& u, int wr, int wc, int fr, int fq) const {
;         const int row0 = u.pm * BM + wr * 64 + fr, col0 = u.pn * BM + wc * 32 + 8 * fq, b = (u.pm * BM) / rows_per_batch;
;         const float* g = gate + (size_t)b * gate_bstride + col0;
;         float ssq[2][4];
; #pragma unroll
;         for (int ai = 0; ai < 2; ++ai)
; #pragma unroll
;             for (int m = 0; m < 4; ++m) ssq[ai][m] = 0.f;
;         f32x4 gv[2][2], Gv[2][2];
; #pragma unroll
;         for (int bj = 0; bj < 2; ++bj) { gv[bj][0] = *(const f32x4*)(g + bj * HALF); gv[bj][1] = *(const f32x4*)(g + bj * HALF + 4); Gv[bj][0] = (f32x4){0.f, 0.f, 0.f, 0.f}; Gv[bj][1] = (f32x4){0.f, 0.f, 0.f, 0.f};
;             if (Hn) { const float* sc = scnext + (size_t)b * gate_bstride + col0 + bj * HALF;
;                 Gv[bj][0] = *(const f32x4*)(gnext + col0 + bj * HALF) * (1.0f + *(const f32x4*)(sc)); Gv[bj][1] = *(const f32x4*)(gnext + col0 + bj * HALF + 4) * (1.0f + *(const f32x4*)(sc + 4)); } }
; template <class Epi, class Sched, bool ALIGN_EPI = false, bool SP2 = false>
; __device__ __forceinline__ void gemm_phase(PG8_LAS unsigned char* lds, const Gemm g, const Sched& S, const Epi& E) {
;     ...
;             PG8_LDA(At, 1, 1); PG8_STAGE(PG8_SB(1, 0), b3, voffB); PG8_STAGE(PG8_SB(1, 1), b3 + hstep, voffB); PG8_STAGE(PG8_SA(1, 0), a3, voffA);
;             PG8_WAIT_V(8); PG8_WAIT_L(0); PG8_BAR; PG8_MMA(1, 0, At, B0); PG8_MMA(1, 1, At, B1); PG8_BAR; PG8_SCHED;
.Lhb_29:
	s_add_u32 s4, s8, 0x80
	s_addc_u32 s5, s9, 0
	s_add_i32 s10, s38, s15
	ds_read_b128 v[178:181], v194 offset:49152
	ds_read_b128 v[182:185], v194 offset:50176
	ds_read_b128 v[186:189], v194 offset:51200
	ds_read_b128 v[196:199], v194 offset:52224
	ds_read_b128 v[200:203], v194 offset:53248
	ds_read_b128 v[204:207], v194 offset:54272
	ds_read_b128 v[208:211], v194 offset:55296
	ds_read_b128 v[212:215], v194 offset:56320
	s_mov_b32 m0, s10
	s_nop 0
	global_load_lds_dwordx4 v162, s[4:5]
	s_add_i32 m0, s10, 0x2000
	s_nop 0
	global_load_lds_dwordx4 v190, s[4:5]
	s_add_u32 s4, s8, 0x160080
	s_addc_u32 s5, s9, 0
	s_add_i32 s8, s39, s15
	s_mov_b32 m0, s8
	s_nop 0
	global_load_lds_dwordx4 v162, s[4:5]
	s_add_i32 m0, s8, 0x2000
	s_nop 0
	global_load_lds_dwordx4 v190, s[4:5]
	s_mov_b32 m0, s24
	s_nop 0
	global_load_lds_dwordx4 v1, s[6:7]
	s_mov_b32 m0, s25
	s_nop 0
	global_load_lds_dwordx4 v164, s[6:7]
	s_waitcnt vmcnt(8)
	s_waitcnt lgkmcnt(0)
	s_cmp_lg_u32 s98, 0
	s_cbranch_scc1 .Lhb_30
	s_barrier
.Lhb_30:
	s_setprio 1
	s_waitcnt lgkmcnt(0)
	v_mfma_f32_16x16x32_bf16 v[110:113], v[74:77], v[178:181], v[110:113]
	v_mfma_f32_16x16x32_bf16 v[110:113], v[78:81], v[182:185], v[110:113]
	v_mfma_f32_16x16x32_bf16 v[94:97], v[74:77], v[186:189], v[94:97]
	v_mfma_f32_16x16x32_bf16 v[94:97], v[78:81], v[196:199], v[94:97]
	v_mfma_f32_16x16x32_bf16 v[86:89], v[74:77], v[200:203], v[86:89]
	v_mfma_f32_16x16x32_bf16 v[86:89], v[78:81], v[204:207], v[86:89]
	v_mfma_f32_16x16x32_bf16 v[34:37], v[74:77], v[208:211], v[34:37]
	v_mfma_f32_16x16x32_bf16 v[78:81], v[78:81], v[212:215], v[34:37]
	v_mfma_f32_16x16x32_bf16 v[106:109], v[98:101], v[178:181], v[106:109]
	v_mfma_f32_16x16x32_bf16 v[106:109], v[102:105], v[182:185], v[106:109]
	v_mfma_f32_16x16x32_bf16 v[90:93], v[98:101], v[186:189], v[90:93]
	v_mfma_f32_16x16x32_bf16 v[90:93], v[102:105], v[196:199], v[90:93]
	v_mfma_f32_16x16x32_bf16 v[82:85], v[98:101], v[200:203], v[82:85]
	v_mfma_f32_16x16x32_bf16 v[82:85], v[102:105], v[204:207], v[82:85]
	v_mfma_f32_16x16x32_bf16 v[34:37], v[98:101], v[208:211], v[38:41]
	v_mfma_f32_16x16x32_bf16 v[74:77], v[102:105], v[212:215], v[34:37]
	s_setprio 0
	s_setprio 1
	v_mfma_f32_16x16x32_bf16 v[30:33], v[146:149], v[178:181], v[30:33]
	v_mfma_f32_16x16x32_bf16 v[30:33], v[150:153], v[182:185], v[30:33]
	v_mfma_f32_16x16x32_bf16 v[22:25], v[146:149], v[186:189], v[22:25]
	v_mfma_f32_16x16x32_bf16 v[22:25], v[150:153], v[196:199], v[22:25]
	v_mfma_f32_16x16x32_bf16 v[14:17], v[146:149], v[200:203], v[14:17]
	v_mfma_f32_16x16x32_bf16 v[14:17], v[150:153], v[204:207], v[14:17]
	v_mfma_f32_16x16x32_bf16 v[6:9], v[146:149], v[208:211], v[6:9]
	v_mfma_f32_16x16x32_bf16 v[6:9], v[150:153], v[212:215], v[6:9]
	v_mfma_f32_16x16x32_bf16 v[26:29], v[154:157], v[178:181], v[26:29]
	v_mfma_f32_16x16x32_bf16 v[26:29], v[158:161], v[182:185], v[26:29]
	v_mfma_f32_16x16x32_bf16 v[18:21], v[154:157], v[186:189], v[18:21]
	v_mfma_f32_16x16x32_bf16 v[18:21], v[158:161], v[196:199], v[18:21]
	v_mfma_f32_16x16x32_bf16 v[10:13], v[154:157], v[200:203], v[10:13]
	v_mfma_f32_16x16x32_bf16 v[10:13], v[158:161], v[204:207], v[10:13]
	v_mfma_f32_16x16x32_bf16 v[2:5], v[154:157], v[208:211], v[2:5]
	v_mfma_f32_16x16x32_bf16 v[2:5], v[158:161], v[212:215], v[2:5]
	s_setprio 0
	s_cmp_eq_u32 s98, 0
	s_cbranch_scc1 .Lhb_31
	s_barrier
.Lhb_31:
	s_add_i32 s35, s35, 2
	s_add_u32 s31, s31, 0x100
	s_addc_u32 s34, s34, 0
	s_cmpk_gt_u32 s35, 0x55
	s_mov_b64 s[4:5], s[2:3]
	s_cbranch_scc0 .LBB0_707
	s_ashr_i32 s2, s29, 31
	s_lshr_b32 s2, s2, 27
	s_add_i32 s2, s29, s2
	s_ashr_i32 s2, s2, 5
	v_lshl_or_b32 v156, s30, 8, v193
	s_mul_i32 s5, s2, 0xc000
	v_ashrrev_i32_e32 v157, 31, v156
	s_mul_hi_i32 s4, s2, 0xc000
	s_add_u32 s2, s20, s5
	s_addc_u32 s3, s21, s4
	v_lshlrev_b64 v[34:35], 2, v[156:157]
	v_lshl_add_u64 v[38:39], s[2:3], 0, v[34:35]
	global_load_dwordx4 v[98:101], v[38:39], off offset:16
	global_load_dwordx4 v[102:105], v[38:39], off
	s_add_u32 s2, s22, s5
	s_addc_u32 s3, s23, s4
	v_lshl_add_u64 v[148:149], s[2:3], 0, v[34:35]
	v_lshl_add_u64 v[146:147], s[48:49], 0, v[34:35]
	v_mov_b32_e32 v158, 0
	v_cndmask_b32_e64 v34, 0, 1, s[46:47]
	v_cmp_ne_u32_e64 s[2:3], 1, v34
	s_andn2_b64 vcc, exec, s[46:47]
	v_mov_b32_e32 v159, v158
	v_mov_b32_e32 v160, v158
	v_mov_b32_e32 v161, v158
	v_mov_b32_e32 v178, v158
	v_mov_b32_e32 v179, v158
	v_mov_b32_e32 v180, v158
	v_mov_b32_e32 v181, v158
	s_cbranch_vccnz .LBB0_710
	global_load_dwordx4 v[34:37], v[148:149], off
	global_load_dwordx4 v[150:153], v[148:149], off offset:16
	global_load_dwordx4 v[158:161], v[146:147], off
	global_load_dwordx4 v[178:181], v[146:147], off offset:16
	s_waitcnt vmcnt(0)
	v_pk_add_f32 v[36:37], v[36:37], 1.0 op_sel_hi:[1,0]
	v_pk_add_f32 v[34:35], v[34:35], 1.0 op_sel_hi:[1,0]
	v_pk_add_f32 v[40:41], v[152:153], 1.0 op_sel_hi:[1,0]
	v_pk_add_f32 v[150:151], v[150:151], 1.0 op_sel_hi:[1,0]
	v_pk_mul_f32 v[160:161], v[160:161], v[36:37]
	v_pk_mul_f32 v[158:159], v[158:159], v[34:35]
	v_pk_mul_f32 v[180:181], v[180:181], v[40:41]
	v_pk_mul_f32 v[178:179], v[178:179], v[150:151]

; #define PG8_WAIT_V(n) asm volatile("s_waitcnt vmcnt(" #n ")" ::: "memory")
; #define PG8_BAR __builtin_amdgcn_s_barrier()
; template <class Epi, class Sched, bool ALIGN_EPI = false, bool SP2 = false>
; __device__ __forceinline__ void gemm_phase(PG8_LAS unsigned char* lds, const Gemm g, const Sched& S, const Epi& E) {
;     ...
;     PG8_WAIT_V(0);
;     if constexpr (!ALIGN_EPI) { if (wr == 0) PG8_BAR; }
;     PG8_BAR;
.LBB0_760:
	s_waitcnt vmcnt(0)
	s_cmpk_gt_u32 s12, 0xff
	s_movk_i32 s48, 0x2000
	s_movk_i32 s49, 0x3000
	s_movk_i32 s46, 0x1ff
	v_readlane_b32 s50, v241, 17
	s_mov_b32 s51, 0xd800000
	v_readlane_b32 s40, v241, 42
	s_cbranch_scc1 .LBB0_762
.LBB0_762:
	s_barrier

; __global__ void __launch_bounds__(NWAVES * 64, 2) skel_fwd(Args args) {
;     extern __shared__ __attribute__((aligned(16))) unsigned char lds[];
	.amdhsa_kernel _Z8skel_fwd4Args
		.amdhsa_group_segment_fixed_size 0
		.amdhsa_private_segment_fixed_size 0
		.amdhsa_kernarg_size 408
		.amdhsa_user_sgpr_count 2
		.amdhsa_user_sgpr_dispatch_ptr 0
		.amdhsa_user_sgpr_queue_ptr 0
		.amdhsa_user_sgpr_kernarg_segment_ptr 1
		.amdhsa_user_sgpr_dispatch_id 0
		.amdhsa_user_sgpr_kernarg_preload_length 0
		.amdhsa_user_sgpr_kernarg_preload_offset 0
		.amdhsa_user_sgpr_private_segment_size 0
		.amdhsa_uses_dynamic_stack 0
		.amdhsa_enable_private_segment 0
		.amdhsa_system_sgpr_workgroup_id_x 1
		.amdhsa_system_sgpr_workgroup_id_y 0
		.amdhsa_system_sgpr_workgroup_id_z 0
		.amdhsa_system_sgpr_workgroup_info 0
		.amdhsa_system_vgpr_workitem_id 0
		.amdhsa_next_free_vgpr 248
		.amdhsa_next_free_sgpr 102
		.amdhsa_accum_offset 248
		.amdhsa_reserve_vcc 1
		.amdhsa_float_round_mode_32 0
		.amdhsa_float_round_mode_16_64 0
		.amdhsa_float_denorm_mode_32 3
		.amdhsa_float_denorm_mode_16_64 3
		.amdhsa_dx10_clamp 1
		.amdhsa_ieee_mode 1
		.amdhsa_fp16_overflow 0
		.amdhsa_tg_split 0
		.amdhsa_exception_fp_ieee_invalid_op 0
		.amdhsa_exception_fp_denorm_src 0
		.amdhsa_exception_fp_ieee_div_zero 0
		.amdhsa_exception_fp_ieee_overflow 0
		.amdhsa_exception_fp_ieee_underflow 0
		.amdhsa_exception_fp_ieee_inexact 0
		.amdhsa_exception_int_div_zero 0
	.end_amdhsa_kernel

; __global__ void __launch_bounds__(NWAVES * 64, 2) skel_fwd(Args args) {
;     extern __shared__ __attribute__((aligned(16))) unsigned char lds[];
amdhsa.kernels:
  - .agpr_count:     0
    .args:
      - .offset:         0
        .size:           152
        .value_kind:     by_value
      - .offset:         152
        .size:           4
        .value_kind:     hidden_block_count_x
      - .offset:         156
        .size:           4
        .value_kind:     hidden_block_count_y
      - .offset:         160
        .size:           4
        .value_kind:     hidden_block_count_z
      - .offset:         164
        .size:           2
        .value_kind:     hidden_group_size_x
      - .offset:         166
        .size:           2
        .value_kind:     hidden_group_size_y
      - .offset:         168
        .size:           2
        .value_kind:     hidden_group_size_z
      - .offset:         170
        .size:           2
        .value_kind:     hidden_remainder_x
      - .offset:         172
        .size:           2
        .value_kind:     hidden_remainder_y
      - .offset:         174
        .size:           2
        .value_kind:     hidden_remainder_z
      - .offset:         192
        .size:           8
        .value_kind:     hidden_global_offset_x
      - .offset:         200
        .size:           8
        .value_kind:     hidden_global_offset_y
      - .offset:         208
        .size:           8
        .value_kind:     hidden_global_offset_z
      - .offset:         216
        .size:           2
        .value_kind:     hidden_grid_dims
      - .offset:         272
        .size:           4
        .value_kind:     hidden_dynamic_lds_size
    .group_segment_fixed_size: 0
    .kernarg_segment_align: 8
    .kernarg_segment_size: 408
    .language:       OpenCL C
    .language_version:
      - 2
      - 0
    .max_flat_workgroup_size: 512
    .name:           _Z8skel_fwd4Args
    .private_segment_fixed_size: 0
    .sgpr_count:     108
    .sgpr_spill_count: 247
    .symbol:         _Z8skel_fwd4Args.kd
    .uniform_work_group_size: 1
    .uses_dynamic_stack: false
    .vgpr_count:     248
    .vgpr_spill_count: 0
    .wavefront_size: 64
